# small-M K-split loops software-pipelined: 2-3 k-steps of loads in flight, immediate k offsets, on top of v23
# baseline (speedup 1.0000x reference)
; #define LAS __attribute__((address_space(3)))
; template <int KSTEPS  >
; __device__ __forceinline__ void small_mma_ksplit(f32x4 (&acc)[2], const bf16_t* A, int lda, const bf16_t* Bt, int ldb, int n0, LAS unsigned char* lds, const SmallId& id) {
;     ...
;     for (int ks = 0; ks < KSTEPS; ++ks) {
;         bf16x8 a[8], b[2];
; #pragma unroll
;         for (int rb = 0; rb < 8; ++rb) a[rb] = *(const bf16x8*)(ap + (size_t)(16 * rb) * lda + 32 * ks);
;         b[0] = *(const bf16x8*)(bp + 32 * ks); b[1] = *(const bf16x8*)(bp + (size_t)16 * ldb + 32 * ks);
; #pragma unroll
;         for (int rb = 0; rb < 8; ++rb) { part[rb][0] = __builtin_amdgcn_mfma_f32_16x16x32_bf16(b[0], a[rb], part[rb][0], 0, 0, 0); part[rb][1] = __builtin_amdgcn_mfma_f32_16x16x32_bf16(b[1], a[rb], part[rb][1], 0, 0, 0); }
;     }
;     LAS f32x4* red = (LAS f32x4*)lds;
; #pragma unroll
;     for (int rb = 0; rb < 8; ++rb) { red[((id.w * 8 + rb) * 2 + 0) * 64 + lane] = part[rb][0]; red[((id.w * 8 + rb) * 2 + 1) * 64 + lane] = part[rb][1]; }
.LBB0_710:
	s_waitcnt lgkmcnt(0)
	s_mov_b32 s3, 0
	global_load_dwordx4 v[76:79], v[64:65], off
	global_load_dwordx4 v[80:83], v[130:131], off
	global_load_dwordx4 v[84:87], v[66:67], off
	s_mov_b32 s2, s9
	v_lshl_add_u64 v[68:69], v[130:131], 0, s[2:3]
	global_load_dwordx4 v[88:91], v[68:69], off
	s_mov_b32 s2, s10
	v_lshl_add_u64 v[70:71], v[130:131], 0, s[2:3]
	global_load_dwordx4 v[92:95], v[70:71], off
	s_mov_b32 s2, s11
	v_lshl_add_u64 v[72:73], v[130:131], 0, s[2:3]
	global_load_dwordx4 v[98:101], v[72:73], off
	s_mov_b32 s2, s12
	v_lshl_add_u64 v[74:75], v[130:131], 0, s[2:3]
	global_load_dwordx4 v[102:105], v[74:75], off
	s_mov_b32 s2, s13
	v_lshl_add_u64 v[68:69], v[130:131], 0, s[2:3]
	global_load_dwordx4 v[106:109], v[68:69], off
	s_mov_b32 s2, s14
	v_lshl_add_u64 v[70:71], v[130:131], 0, s[2:3]
	global_load_dwordx4 v[110:113], v[70:71], off
	s_mov_b32 s2, s15
	v_lshl_add_u64 v[72:73], v[130:131], 0, s[2:3]
	global_load_dwordx4 v[114:117], v[72:73], off
	global_load_dwordx4 v[118:121], v[64:65], off offset:64
	global_load_dwordx4 v[122:125], v[130:131], off offset:64
	global_load_dwordx4 v[126:129], v[66:67], off offset:64
	s_mov_b32 s2, s9
	v_lshl_add_u64 v[74:75], v[130:131], 0, s[2:3]
	global_load_dwordx4 v[160:163], v[74:75], off offset:64
	s_mov_b32 s2, s10
	v_lshl_add_u64 v[68:69], v[130:131], 0, s[2:3]
	global_load_dwordx4 v[164:167], v[68:69], off offset:64
	s_mov_b32 s2, s11
	v_lshl_add_u64 v[70:71], v[130:131], 0, s[2:3]
	global_load_dwordx4 v[168:171], v[70:71], off offset:64
	s_mov_b32 s2, s12
	v_lshl_add_u64 v[72:73], v[130:131], 0, s[2:3]
	global_load_dwordx4 v[172:175], v[72:73], off offset:64
	s_mov_b32 s2, s13
	v_lshl_add_u64 v[74:75], v[130:131], 0, s[2:3]
	global_load_dwordx4 v[176:179], v[74:75], off offset:64
	s_mov_b32 s2, s14
	v_lshl_add_u64 v[68:69], v[130:131], 0, s[2:3]
	global_load_dwordx4 v[180:183], v[68:69], off offset:64
	s_mov_b32 s2, s15
	v_lshl_add_u64 v[70:71], v[130:131], 0, s[2:3]
	global_load_dwordx4 v[184:187], v[70:71], off offset:64
	s_waitcnt vmcnt(10)
	v_mfma_f32_16x16x32_bf16 v[36:39], v[76:79], v[80:83], v[36:39]
	v_mfma_f32_16x16x32_bf16 v[24:27], v[84:87], v[80:83], v[24:27]
	v_mfma_f32_16x16x32_bf16 v[20:23], v[76:79], v[88:91], v[20:23]
	v_mfma_f32_16x16x32_bf16 v[16:19], v[84:87], v[88:91], v[16:19]
	v_mfma_f32_16x16x32_bf16 v[12:15], v[76:79], v[92:95], v[12:15]
	v_mfma_f32_16x16x32_bf16 v[8:11], v[84:87], v[92:95], v[8:11]
	v_mfma_f32_16x16x32_bf16 v[4:7], v[76:79], v[98:101], v[4:7]
	v_mfma_f32_16x16x32_bf16 v[0:3], v[84:87], v[98:101], v[0:3]
	v_mfma_f32_16x16x32_bf16 v[28:31], v[76:79], v[102:105], v[28:31]
	v_mfma_f32_16x16x32_bf16 v[32:35], v[84:87], v[102:105], v[32:35]
	v_mfma_f32_16x16x32_bf16 v[40:43], v[76:79], v[106:109], v[40:43]
	v_mfma_f32_16x16x32_bf16 v[44:47], v[84:87], v[106:109], v[44:47]
	v_mfma_f32_16x16x32_bf16 v[48:51], v[76:79], v[110:113], v[48:51]
	v_mfma_f32_16x16x32_bf16 v[52:55], v[84:87], v[110:113], v[52:55]
	v_mfma_f32_16x16x32_bf16 v[56:59], v[76:79], v[114:117], v[56:59]
	v_mfma_f32_16x16x32_bf16 v[60:63], v[84:87], v[114:117], v[60:63]
	s_waitcnt vmcnt(0)
	v_mfma_f32_16x16x32_bf16 v[36:39], v[118:121], v[122:125], v[36:39]
	v_mfma_f32_16x16x32_bf16 v[24:27], v[126:129], v[122:125], v[24:27]
	v_mfma_f32_16x16x32_bf16 v[20:23], v[118:121], v[160:163], v[20:23]
	v_mfma_f32_16x16x32_bf16 v[16:19], v[126:129], v[160:163], v[16:19]
	v_mfma_f32_16x16x32_bf16 v[12:15], v[118:121], v[164:167], v[12:15]
	v_mfma_f32_16x16x32_bf16 v[8:11], v[126:129], v[164:167], v[8:11]
	v_mfma_f32_16x16x32_bf16 v[4:7], v[118:121], v[168:171], v[4:7]
	v_mfma_f32_16x16x32_bf16 v[0:3], v[126:129], v[168:171], v[0:3]
	v_mfma_f32_16x16x32_bf16 v[28:31], v[118:121], v[172:175], v[28:31]
	v_mfma_f32_16x16x32_bf16 v[32:35], v[126:129], v[172:175], v[32:35]
	v_mfma_f32_16x16x32_bf16 v[40:43], v[118:121], v[176:179], v[40:43]
	v_mfma_f32_16x16x32_bf16 v[44:47], v[126:129], v[176:179], v[44:47]
	v_mfma_f32_16x16x32_bf16 v[48:51], v[118:121], v[180:183], v[48:51]
	v_mfma_f32_16x16x32_bf16 v[52:55], v[126:129], v[180:183], v[52:55]
	v_mfma_f32_16x16x32_bf16 v[56:59], v[118:121], v[184:187], v[56:59]
	v_mfma_f32_16x16x32_bf16 v[60:63], v[126:129], v[184:187], v[60:63]
	ds_write_b128 v149, v[36:39]
	ds_write_b128 v149, v[24:27] offset:1024
	ds_write_b128 v149, v[20:23] offset:2048
	ds_write_b128 v149, v[16:19] offset:3072
	ds_write_b128 v149, v[12:15] offset:4096
	ds_write_b128 v149, v[8:11] offset:5120
	ds_write_b128 v149, v[4:7] offset:6144
	ds_write_b128 v149, v[0:3] offset:7168
	ds_write_b128 v149, v[28:31] offset:8192
	ds_write_b128 v149, v[32:35] offset:9216
	ds_write_b128 v149, v[40:43] offset:10240
	ds_write_b128 v149, v[44:47] offset:11264
	ds_write_b128 v149, v[48:51] offset:12288
	ds_write_b128 v149, v[52:55] offset:13312
	ds_write_b128 v149, v[56:59] offset:14336
	ds_write_b128 v149, v[60:63] offset:15360
	s_waitcnt lgkmcnt(0)
	s_waitcnt lgkmcnt(0)
	s_barrier
; template <int KSTEPS  >
; __device__ __forceinline__ void small_mma_ksplit(f32x4 (&acc)[2], const bf16_t* A, int lda, const bf16_t* Bt, int ldb, int n0, LAS unsigned char* lds, const SmallId& id) {
;     ...
;     for (int ks = 0; ks < KSTEPS; ++ks) {
;         bf16x8 a[8], b[2];
; #pragma unroll
;         for (int rb = 0; rb < 8; ++rb) a[rb] = *(const bf16x8*)(ap + (size_t)(16 * rb) * lda + 32 * ks);
;         b[0] = *(const bf16x8*)(bp + 32 * ks); b[1] = *(const bf16x8*)(bp + (size_t)16 * ldb + 32 * ks);
; #pragma unroll
;         for (int rb = 0; rb < 8; ++rb) { part[rb][0] = __builtin_amdgcn_mfma_f32_16x16x32_bf16(b[0], a[rb], part[rb][0], 0, 0, 0); part[rb][1] = __builtin_amdgcn_mfma_f32_16x16x32_bf16(b[1], a[rb], part[rb][1], 0, 0, 0); }
;     }
;     ...
;     for (int rb = 0; rb < 8; ++rb) { red[((id.w * 8 + rb) * 2 + 0) * 64 + lane] = part[rb][0]; red[((id.w * 8 + rb) * 2 + 1) * 64 + lane] = part[rb][1]; }
;     asm volatile("s_waitcnt lgkmcnt(0)" ::: "memory"); __syncthreads();
;     acc[0] = (f32x4){0.f, 0.f, 0.f, 0.f}; acc[1] = acc[0];
; #pragma unroll
;     for (int w2 = 0; w2 < 8; ++w2) { acc[0] += red[((w2 * 8 + id.w) * 2 + 0) * 64 + lane]; acc[1] += red[((w2 * 8 + id.w) * 2 + 1) * 64 + lane]; }
	ds_read_b128 v[126:129], v150
	ds_read_b128 v[122:125], v150 offset:1024
	ds_read_b128 v[118:121], v150 offset:16384
	ds_read_b128 v[114:117], v150 offset:17408
	ds_read_b128 v[110:113], v150 offset:32768
	ds_read_b128 v[106:109], v150 offset:33792
	ds_read_b128 v[102:105], v150 offset:49152
	ds_read_b128 v[98:101], v150 offset:50176
	ds_read_b128 v[92:95], v151
	ds_read_b128 v[88:91], v152
	ds_read_b128 v[84:87], v153
	ds_read_b128 v[80:83], v154
	ds_read_b128 v[76:79], v155
	ds_read_b128 v[72:75], v156
	ds_read_b128 v[68:71], v157
	ds_read_b128 v[64:67], v158
	s_waitcnt lgkmcnt(0)
	v_lshl_add_u64 v[144:145], v[136:137], 0, v[144:145]
	s_mov_b64 s[0:1], 0x4000
	v_mov_b32_e32 v0, 0
	v_lshl_add_u64 v[146:147], v[144:145], 0, s[0:1]
	s_mov_b64 s[2:3], 0
	s_mov_b64 s[0:1], -1
	v_mov_b32_e32 v1, v0
	v_mov_b32_e32 v2, v0
	v_mov_b32_e32 v3, v0
	v_mov_b32_e32 v4, v0
	v_mov_b32_e32 v5, v0
	v_mov_b32_e32 v6, v0
	v_mov_b32_e32 v7, v0
	v_mov_b32_e32 v8, v0
	v_mov_b32_e32 v9, v0
	v_mov_b32_e32 v10, v0
	v_mov_b32_e32 v11, v0
	v_mov_b32_e32 v12, v0
	v_mov_b32_e32 v13, v0
	v_mov_b32_e32 v14, v0
	v_mov_b32_e32 v15, v0
	v_mov_b32_e32 v16, v0
	v_mov_b32_e32 v17, v0
	v_mov_b32_e32 v18, v0
	v_mov_b32_e32 v19, v0
	v_mov_b32_e32 v20, v0
	v_mov_b32_e32 v21, v0
	v_mov_b32_e32 v22, v0
	v_mov_b32_e32 v23, v0
	v_mov_b32_e32 v24, v0
	v_mov_b32_e32 v25, v0
	v_mov_b32_e32 v26, v0
	v_mov_b32_e32 v27, v0
	v_mov_b32_e32 v36, v0
	v_mov_b32_e32 v37, v0
	v_mov_b32_e32 v38, v0
	v_mov_b32_e32 v39, v0
	v_mov_b32_e32 v28, v0
	v_mov_b32_e32 v29, v0
	v_mov_b32_e32 v30, v0
	v_mov_b32_e32 v31, v0
	v_mov_b32_e32 v32, v0
	v_mov_b32_e32 v33, v0
	v_mov_b32_e32 v34, v0
	v_mov_b32_e32 v35, v0
	v_mov_b32_e32 v40, v0
	v_mov_b32_e32 v41, v0
	v_mov_b32_e32 v42, v0
	v_mov_b32_e32 v43, v0
	v_mov_b32_e32 v44, v0
	v_mov_b32_e32 v45, v0
	v_mov_b32_e32 v46, v0
	v_mov_b32_e32 v47, v0
	v_mov_b32_e32 v48, v0
	v_mov_b32_e32 v49, v0
	v_mov_b32_e32 v50, v0
	v_mov_b32_e32 v51, v0
	v_mov_b32_e32 v52, v0
	v_mov_b32_e32 v53, v0
	v_mov_b32_e32 v54, v0
	v_mov_b32_e32 v55, v0
	v_mov_b32_e32 v56, v0
	v_mov_b32_e32 v57, v0
	v_mov_b32_e32 v58, v0
	v_mov_b32_e32 v59, v0
	v_mov_b32_e32 v60, v0
	v_mov_b32_e32 v61, v0
	v_mov_b32_e32 v62, v0
	v_mov_b32_e32 v63, v0
	s_waitcnt lgkmcnt(0)
	s_barrier
.LBB0_712:
	s_waitcnt lgkmcnt(0)
	s_mov_b32 s3, 0
	global_load_dwordx4 v[162:165], v[144:145], off
	global_load_dwordx4 v[166:169], v[134:135], off
	global_load_dwordx4 v[170:173], v[146:147], off
	s_mov_b32 s2, s9
	v_lshl_add_u64 v[130:131], v[134:135], 0, s[2:3]
	global_load_dwordx4 v[174:177], v[130:131], off
	s_mov_b32 s2, s10
	v_lshl_add_u64 v[132:133], v[134:135], 0, s[2:3]
	global_load_dwordx4 v[178:181], v[132:133], off
	s_mov_b32 s2, s11
	v_lshl_add_u64 v[136:137], v[134:135], 0, s[2:3]
	global_load_dwordx4 v[182:185], v[136:137], off
	s_mov_b32 s2, s12
	v_lshl_add_u64 v[160:161], v[134:135], 0, s[2:3]
	global_load_dwordx4 v[186:189], v[160:161], off
	s_mov_b32 s2, s13
	v_lshl_add_u64 v[130:131], v[134:135], 0, s[2:3]
	global_load_dwordx4 v[190:193], v[130:131], off
	s_mov_b32 s2, s14
	v_lshl_add_u64 v[132:133], v[134:135], 0, s[2:3]
	global_load_dwordx4 v[206:209], v[132:133], off
	s_mov_b32 s2, s15
	v_lshl_add_u64 v[136:137], v[134:135], 0, s[2:3]
	global_load_dwordx4 v[210:213], v[136:137], off
	s_waitcnt vmcnt(0)
	v_mfma_f32_16x16x32_bf16 v[36:39], v[162:165], v[166:169], v[36:39]
	v_mfma_f32_16x16x32_bf16 v[24:27], v[170:173], v[166:169], v[24:27]
	v_mfma_f32_16x16x32_bf16 v[20:23], v[162:165], v[174:177], v[20:23]
	v_mfma_f32_16x16x32_bf16 v[16:19], v[170:173], v[174:177], v[16:19]
	v_mfma_f32_16x16x32_bf16 v[12:15], v[162:165], v[178:181], v[12:15]
	v_mfma_f32_16x16x32_bf16 v[8:11], v[170:173], v[178:181], v[8:11]
	v_mfma_f32_16x16x32_bf16 v[4:7], v[162:165], v[182:185], v[4:7]
	v_mfma_f32_16x16x32_bf16 v[0:3], v[170:173], v[182:185], v[0:3]
	v_mfma_f32_16x16x32_bf16 v[28:31], v[162:165], v[186:189], v[28:31]
	v_mfma_f32_16x16x32_bf16 v[32:35], v[170:173], v[186:189], v[32:35]
	v_mfma_f32_16x16x32_bf16 v[40:43], v[162:165], v[190:193], v[40:43]
	v_mfma_f32_16x16x32_bf16 v[44:47], v[170:173], v[190:193], v[44:47]
	v_mfma_f32_16x16x32_bf16 v[48:51], v[162:165], v[206:209], v[48:51]
	v_mfma_f32_16x16x32_bf16 v[52:55], v[170:173], v[206:209], v[52:55]
	v_mfma_f32_16x16x32_bf16 v[56:59], v[162:165], v[210:213], v[56:59]
	v_mfma_f32_16x16x32_bf16 v[60:63], v[170:173], v[210:213], v[60:63]
	global_load_dwordx4 v[162:165], v[144:145], off offset:64
	global_load_dwordx4 v[166:169], v[134:135], off offset:64
	global_load_dwordx4 v[170:173], v[146:147], off offset:64
	s_mov_b32 s2, s9
	v_lshl_add_u64 v[160:161], v[134:135], 0, s[2:3]
	global_load_dwordx4 v[174:177], v[160:161], off offset:64
	s_mov_b32 s2, s10
	v_lshl_add_u64 v[130:131], v[134:135], 0, s[2:3]
	global_load_dwordx4 v[178:181], v[130:131], off offset:64
	s_mov_b32 s2, s11
	v_lshl_add_u64 v[132:133], v[134:135], 0, s[2:3]
	global_load_dwordx4 v[182:185], v[132:133], off offset:64
	s_mov_b32 s2, s12
	v_lshl_add_u64 v[136:137], v[134:135], 0, s[2:3]
	global_load_dwordx4 v[186:189], v[136:137], off offset:64
	s_mov_b32 s2, s13
	v_lshl_add_u64 v[160:161], v[134:135], 0, s[2:3]
	global_load_dwordx4 v[190:193], v[160:161], off offset:64
	s_mov_b32 s2, s14
	v_lshl_add_u64 v[130:131], v[134:135], 0, s[2:3]
	global_load_dwordx4 v[206:209], v[130:131], off offset:64
	s_mov_b32 s2, s15
	v_lshl_add_u64 v[132:133], v[134:135], 0, s[2:3]
	global_load_dwordx4 v[210:213], v[132:133], off offset:64
	s_waitcnt vmcnt(0)
; #define LAS __attribute__((address_space(3)))
; template <int KSTEPS  >
; __device__ __forceinline__ void small_mma_ksplit(f32x4 (&acc)[2], const bf16_t* A, int lda, const bf16_t* Bt, int ldb, int n0, LAS unsigned char* lds, const SmallId& id) {
;     ...
;         for (int rb = 0; rb < 8; ++rb) { part[rb][0] = __builtin_amdgcn_mfma_f32_16x16x32_bf16(b[0], a[rb], part[rb][0], 0, 0, 0); part[rb][1] = __builtin_amdgcn_mfma_f32_16x16x32_bf16(b[1], a[rb], part[rb][1], 0, 0, 0); }
;     }
;     LAS f32x4* red = (LAS f32x4*)lds;
; #pragma unroll
;     for (int rb = 0; rb < 8; ++rb) { red[((id.w * 8 + rb) * 2 + 0) * 64 + lane] = part[rb][0]; red[((id.w * 8 + rb) * 2 + 1) * 64 + lane] = part[rb][1]; }
;     asm volatile("s_waitcnt lgkmcnt(0)" ::: "memory"); __syncthreads();
;     acc[0] = (f32x4){0.f, 0.f, 0.f, 0.f}; acc[1] = acc[0];
; #pragma unroll
;     for (int w2 = 0; w2 < 8; ++w2) { acc[0] += red[((w2 * 8 + id.w) * 2 + 0) * 64 + lane]; acc[1] += red[((w2 * 8 + id.w) * 2 + 1) * 64 + lane]; }
;     asm volatile("s_waitcnt lgkmcnt(0)" ::: "memory"); __syncthreads();
	v_mfma_f32_16x16x32_bf16 v[36:39], v[162:165], v[166:169], v[36:39]
	v_mfma_f32_16x16x32_bf16 v[24:27], v[170:173], v[166:169], v[24:27]
	v_mfma_f32_16x16x32_bf16 v[20:23], v[162:165], v[174:177], v[20:23]
	v_mfma_f32_16x16x32_bf16 v[16:19], v[170:173], v[174:177], v[16:19]
	v_mfma_f32_16x16x32_bf16 v[12:15], v[162:165], v[178:181], v[12:15]
	v_mfma_f32_16x16x32_bf16 v[8:11], v[170:173], v[178:181], v[8:11]
	v_mfma_f32_16x16x32_bf16 v[4:7], v[162:165], v[182:185], v[4:7]
	v_mfma_f32_16x16x32_bf16 v[0:3], v[170:173], v[182:185], v[0:3]
	v_mfma_f32_16x16x32_bf16 v[28:31], v[162:165], v[186:189], v[28:31]
	v_mfma_f32_16x16x32_bf16 v[32:35], v[170:173], v[186:189], v[32:35]
	v_mfma_f32_16x16x32_bf16 v[40:43], v[162:165], v[190:193], v[40:43]
	v_mfma_f32_16x16x32_bf16 v[44:47], v[170:173], v[190:193], v[44:47]
	v_mfma_f32_16x16x32_bf16 v[48:51], v[162:165], v[206:209], v[48:51]
	v_mfma_f32_16x16x32_bf16 v[52:55], v[170:173], v[206:209], v[52:55]
	v_mfma_f32_16x16x32_bf16 v[56:59], v[162:165], v[210:213], v[56:59]
	v_mfma_f32_16x16x32_bf16 v[60:63], v[170:173], v[210:213], v[60:63]
	ds_write_b128 v149, v[36:39]
	ds_write_b128 v149, v[24:27] offset:1024
	ds_write_b128 v149, v[20:23] offset:2048
	ds_write_b128 v149, v[16:19] offset:3072
	ds_write_b128 v149, v[12:15] offset:4096
	ds_write_b128 v149, v[8:11] offset:5120
	ds_write_b128 v149, v[4:7] offset:6144
	ds_write_b128 v149, v[0:3] offset:7168
	ds_write_b128 v149, v[28:31] offset:8192
	ds_write_b128 v149, v[32:35] offset:9216
	ds_write_b128 v149, v[40:43] offset:10240
	ds_write_b128 v149, v[44:47] offset:11264
	ds_write_b128 v149, v[48:51] offset:12288
	ds_write_b128 v149, v[52:55] offset:13312
	ds_write_b128 v149, v[56:59] offset:14336
	ds_write_b128 v149, v[60:63] offset:15360
	s_waitcnt lgkmcnt(0)
	s_waitcnt lgkmcnt(0)
	s_barrier
	ds_read_b128 v[0:3], v150
	v_pk_add_f32 v[126:127], v[126:127], 0 op_sel_hi:[1,0]
	v_pk_add_f32 v[128:129], v[128:129], 0 op_sel_hi:[1,0]
	v_pk_add_f32 v[118:119], v[126:127], v[118:119]
	v_pk_add_f32 v[120:121], v[128:129], v[120:121]
	s_waitcnt lgkmcnt(0)
	v_pk_add_f32 v[4:5], v[2:3], 0 op_sel_hi:[1,0]
	v_pk_add_f32 v[6:7], v[0:1], 0 op_sel_hi:[1,0]
	ds_read_b128 v[0:3], v150 offset:1024
	v_pk_add_f32 v[110:111], v[118:119], v[110:111]
	v_pk_add_f32 v[112:113], v[120:121], v[112:113]
	v_pk_add_f32 v[102:103], v[110:111], v[102:103]
	v_pk_add_f32 v[104:105], v[112:113], v[104:105]
	s_waitcnt lgkmcnt(0)
	v_pk_add_f32 v[8:9], v[2:3], 0 op_sel_hi:[1,0]
	v_pk_add_f32 v[10:11], v[0:1], 0 op_sel_hi:[1,0]
	ds_read_b128 v[0:3], v150 offset:16384
	v_pk_add_f32 v[92:93], v[102:103], v[92:93]
	v_pk_add_f32 v[94:95], v[104:105], v[94:95]
	v_pk_add_f32 v[84:85], v[92:93], v[84:85]
	v_pk_add_f32 v[86:87], v[94:95], v[86:87]
	s_waitcnt lgkmcnt(0)
	v_pk_add_f32 v[4:5], v[4:5], v[2:3]
	v_pk_add_f32 v[6:7], v[6:7], v[0:1]
	ds_read_b128 v[0:3], v150 offset:17408
	v_pk_add_f32 v[76:77], v[84:85], v[76:77]
	v_pk_add_f32 v[78:79], v[86:87], v[78:79]
	v_pk_add_f32 v[68:69], v[76:77], v[68:69]
	v_pk_add_f32 v[70:71], v[78:79], v[70:71]
	s_waitcnt lgkmcnt(0)
	v_pk_add_f32 v[8:9], v[8:9], v[2:3]
	v_pk_add_f32 v[10:11], v[10:11], v[0:1]
	ds_read_b128 v[0:3], v150 offset:32768
	v_mov_b32_e32 v20, v68
	v_pk_add_f32 v[122:123], v[122:123], 0 op_sel_hi:[1,0]
	v_pk_add_f32 v[124:125], v[124:125], 0 op_sel_hi:[1,0]
	v_pk_add_f32 v[114:115], v[122:123], v[114:115]
	s_waitcnt lgkmcnt(0)
	v_pk_add_f32 v[4:5], v[4:5], v[2:3]
	v_pk_add_f32 v[6:7], v[6:7], v[0:1]
	ds_read_b128 v[0:3], v150 offset:33792
	v_pk_add_f32 v[106:107], v[114:115], v[106:107]
	v_pk_add_f32 v[116:117], v[124:125], v[116:117]
	v_pk_add_f32 v[98:99], v[106:107], v[98:99]
	v_pk_add_f32 v[108:109], v[116:117], v[108:109]
	s_waitcnt lgkmcnt(0)
	v_pk_add_f32 v[8:9], v[8:9], v[2:3]
	v_pk_add_f32 v[10:11], v[10:11], v[0:1]
	ds_read_b128 v[0:3], v150 offset:49152
	v_pk_add_f32 v[88:89], v[98:99], v[88:89]
	v_pk_add_f32 v[100:101], v[108:109], v[100:101]
	v_pk_add_f32 v[80:81], v[88:89], v[80:81]
	v_pk_add_f32 v[90:91], v[100:101], v[90:91]
	s_waitcnt lgkmcnt(0)
	v_pk_add_f32 v[4:5], v[4:5], v[2:3]
	v_pk_add_f32 v[6:7], v[6:7], v[0:1]
	ds_read_b128 v[0:3], v150 offset:50176
	v_pk_add_f32 v[72:73], v[80:81], v[72:73]
	v_pk_add_f32 v[82:83], v[90:91], v[82:83]
	v_pk_add_f32 v[64:65], v[72:73], v[64:65]
	v_pk_add_f32 v[74:75], v[82:83], v[74:75]
	s_waitcnt lgkmcnt(0)
	v_pk_add_f32 v[8:9], v[8:9], v[2:3]
	v_pk_add_f32 v[10:11], v[10:11], v[0:1]
	ds_read_b128 v[0:3], v151
	v_pk_add_f32 v[66:67], v[74:75], v[66:67]
	s_add_i32 s7, s7, s92
	s_cmp_lt_i32 s7, 32
	s_waitcnt lgkmcnt(0)
	v_pk_add_f32 v[4:5], v[4:5], v[2:3]
	v_pk_add_f32 v[6:7], v[6:7], v[0:1]
	ds_read_b128 v[0:3], v152
	s_waitcnt lgkmcnt(0)
	v_pk_add_f32 v[8:9], v[8:9], v[2:3]
	v_pk_add_f32 v[10:11], v[10:11], v[0:1]
	ds_read_b128 v[0:3], v153
	s_waitcnt lgkmcnt(0)
	v_pk_add_f32 v[4:5], v[4:5], v[2:3]
	v_pk_add_f32 v[6:7], v[6:7], v[0:1]
	ds_read_b128 v[0:3], v154
	s_waitcnt lgkmcnt(0)
	v_pk_add_f32 v[8:9], v[8:9], v[2:3]
	v_pk_add_f32 v[10:11], v[10:11], v[0:1]
	ds_read_b128 v[0:3], v155
	s_waitcnt lgkmcnt(0)
	v_pk_add_f32 v[4:5], v[4:5], v[2:3]
	v_pk_add_f32 v[6:7], v[6:7], v[0:1]
	ds_read_b128 v[0:3], v156
	s_waitcnt lgkmcnt(0)
	v_pk_add_f32 v[8:9], v[8:9], v[2:3]
	v_pk_add_f32 v[10:11], v[10:11], v[0:1]
	ds_read_b128 v[0:3], v157
	s_waitcnt lgkmcnt(0)
	v_pk_add_f32 v[12:13], v[4:5], v[2:3]
	ds_read_b128 v[2:5], v158
	v_pk_add_f32 v[6:7], v[6:7], v[0:1]
	s_waitcnt lgkmcnt(0)
	s_waitcnt lgkmcnt(0)
	s_barrier
; __device__ __forceinline__ unsigned cvt_pk_bf16(float lo, float hi) { unsigned r; asm volatile("v_cvt_pk_bf16_f32 %0, %1, %2" : "=v"(r) : "v"(lo), "v"(hi)); return r; }
; __device__ __forceinline__ void small_mix(const Params& p, int l, LAS unsigned char* lds, int G, int bx) {
;     ...
;         for (int nb = 0; nb < 2; ++nb) { const int col = n0 + 16 * nb + 4 * id.fq;
;             const u32x2 g0 = *(const u32x2*)(PROJ + (size_t)id.row * INW + 1280 + col), g1 = *(const u32x2*)(PROJ + (size_t)id.row * INW + 2304 + col);
;             const float v0 = bf_lo(g0.x) * ya[nb][0] + bf_lo(g1.x) * yb[nb][0], v1 = bf_hi(g0.x) * ya[nb][1] + bf_hi(g1.x) * yb[nb][1];
;             const float v2 = bf_lo(g0.y) * ya[nb][2] + bf_lo(g1.y) * yb[nb][2], v3 = bf_hi(g0.y) * ya[nb][3] + bf_hi(g1.y) * yb[nb][3];
;             u32x2 w; w.x = cvt_pk_bf16(v0, v1); w.y = cvt_pk_bf16(v2, v3); *(u32x2*)(MIX + (size_t)id.row * DM + col) = w; }
	v_pk_add_f32 v[0:1], v[8:9], v[4:5]
	v_or_b32_e32 v4, s8, v96
	v_ashrrev_i32_e32 v5, 31, v4
	v_lshlrev_b64 v[8:9], 1, v[4:5]
	v_pk_add_f32 v[2:3], v[10:11], v[2:3]
	v_lshl_add_u64 v[10:11], v[138:139], 0, v[8:9]
	v_lshl_add_u64 v[16:17], v[140:141], 0, v[8:9]
	global_load_dwordx2 v[14:15], v[10:11], off offset:2560
	v_mov_b32_e32 v21, v6
	global_load_dwordx2 v[16:17], v[16:17], off
	v_mov_b32_e32 v6, v69
	v_or_b32_e32 v4, 16, v4
	v_lshl_add_u64 v[8:9], v[142:143], 0, v[8:9]
	s_waitcnt vmcnt(0) lgkmcnt(0)
	v_lshlrev_b32_e32 v18, 16, v14
	v_lshlrev_b32_e32 v19, 16, v16
	v_pk_mul_f32 v[18:19], v[20:21], v[18:19]
	s_nop 0
	v_add_f32_e32 v5, v18, v19
	v_and_b32_e32 v19, 0xffff0000, v16
	v_and_b32_e32 v18, 0xffff0000, v14
	v_pk_mul_f32 v[6:7], v[6:7], v[18:19]
	v_mov_b32_e32 v18, v70
	v_add_f32_e32 v14, v6, v7
	v_lshlrev_b32_e32 v7, 16, v17
	v_lshlrev_b32_e32 v6, 16, v15
	v_mov_b32_e32 v19, v12
	v_pk_mul_f32 v[6:7], v[18:19], v[6:7]
	v_mov_b32_e32 v12, v71
	v_add_f32_e32 v16, v6, v7
	v_and_b32_e32 v7, 0xffff0000, v17
	v_and_b32_e32 v6, 0xffff0000, v15
	v_pk_mul_f32 v[6:7], v[12:13], v[6:7]
	v_mov_b32_e32 v12, v64
	v_add_f32_e32 v7, v6, v7
	v_cvt_pk_bf16_f32 v6, v5, v14
	v_ashrrev_i32_e32 v5, 31, v4
	v_cvt_pk_bf16_f32 v7, v16, v7
	v_lshl_add_u64 v[4:5], v[4:5], 1, v[140:141]
	global_store_dwordx2 v[8:9], v[6:7], off
	global_load_dwordx2 v[6:7], v[10:11], off offset:2592
	v_mov_b32_e32 v13, v2
	global_load_dwordx2 v[4:5], v[4:5], off
	v_mov_b32_e32 v2, v65
	s_waitcnt vmcnt(0) lgkmcnt(0)
	v_lshlrev_b32_e32 v10, 16, v6
	v_lshlrev_b32_e32 v11, 16, v4
	v_pk_mul_f32 v[10:11], v[12:13], v[10:11]
	s_nop 0
	v_add_f32_e32 v12, v10, v11
	v_and_b32_e32 v11, 0xffff0000, v4
	v_and_b32_e32 v10, 0xffff0000, v6
	v_pk_mul_f32 v[2:3], v[2:3], v[10:11]
	v_mov_b32_e32 v10, v66
	v_add_f32_e32 v4, v2, v3
	v_lshlrev_b32_e32 v3, 16, v5
	v_lshlrev_b32_e32 v2, 16, v7
	v_mov_b32_e32 v11, v0
	v_pk_mul_f32 v[2:3], v[10:11], v[2:3]
	v_mov_b32_e32 v0, v67
	v_add_f32_e32 v6, v2, v3
	v_and_b32_e32 v3, 0xffff0000, v5
	v_and_b32_e32 v2, 0xffff0000, v7
	v_pk_mul_f32 v[0:1], v[0:1], v[2:3]
	s_nop 0
	v_add_f32_e32 v1, v0, v1
	v_cvt_pk_bf16_f32 v0, v12, v4
	v_cvt_pk_bf16_f32 v1, v6, v1
	global_store_dwordx2 v[8:9], v[0:1], off offset:32
	s_cbranch_scc1 .LBB0_709

; template <int KSTEPS  >
; __device__ __forceinline__ void small_mma_ksplit(f32x4 (&acc)[2], const bf16_t* A, int lda, const bf16_t* Bt, int ldb, int n0, LAS unsigned char* lds, const SmallId& id) {
;     ...
;     for (int ks = 0; ks < KSTEPS; ++ks) {
;         bf16x8 a[8], b[2];
; #pragma unroll
;         for (int rb = 0; rb < 8; ++rb) a[rb] = *(const bf16x8*)(ap + (size_t)(16 * rb) * lda + 32 * ks);
;         b[0] = *(const bf16x8*)(bp + 32 * ks); b[1] = *(const bf16x8*)(bp + (size_t)16 * ldb + 32 * ks);
; #pragma unroll
;         for (int rb = 0; rb < 8; ++rb) { part[rb][0] = __builtin_amdgcn_mfma_f32_16x16x32_bf16(b[0], a[rb], part[rb][0], 0, 0, 0); part[rb][1] = __builtin_amdgcn_mfma_f32_16x16x32_bf16(b[1], a[rb], part[rb][1], 0, 0, 0); }
;     }
.LBB0_863:
	s_waitcnt lgkmcnt(0)
	s_mov_b32 s9, 0
	s_mov_b32 s8, s18
	v_lshl_add_u64 v[68:69], v[74:75], 0, s[8:9]
	global_load_dwordx4 v[92:95], v[68:69], off
	s_mov_b32 s8, s10
	v_lshl_add_u64 v[70:71], v[72:73], 0, s[8:9]
	global_load_dwordx4 v[98:101], v[70:71], off
	s_mov_b32 s8, s19
	v_lshl_add_u64 v[88:89], v[74:75], 0, s[8:9]
	global_load_dwordx4 v[102:105], v[88:89], off
	s_mov_b32 s8, s11
	v_lshl_add_u64 v[90:91], v[72:73], 0, s[8:9]
	global_load_dwordx4 v[106:109], v[90:91], off
	s_mov_b32 s8, s12
	v_lshl_add_u64 v[68:69], v[72:73], 0, s[8:9]
	global_load_dwordx4 v[110:113], v[68:69], off
	s_mov_b32 s8, s13
	v_lshl_add_u64 v[70:71], v[72:73], 0, s[8:9]
	global_load_dwordx4 v[114:117], v[70:71], off
	s_mov_b32 s8, s14
	v_lshl_add_u64 v[88:89], v[72:73], 0, s[8:9]
	global_load_dwordx4 v[118:121], v[88:89], off
	s_mov_b32 s8, s15
	v_lshl_add_u64 v[90:91], v[72:73], 0, s[8:9]
	global_load_dwordx4 v[122:125], v[90:91], off
	s_mov_b32 s8, s16
	v_lshl_add_u64 v[68:69], v[72:73], 0, s[8:9]
	global_load_dwordx4 v[126:129], v[68:69], off
	s_mov_b32 s8, s17
	v_lshl_add_u64 v[70:71], v[72:73], 0, s[8:9]
	global_load_dwordx4 v[130:133], v[70:71], off
	s_mov_b32 s8, s18
	v_lshl_add_u64 v[88:89], v[74:75], 0, s[8:9]
	global_load_dwordx4 v[134:137], v[88:89], off offset:64
	s_mov_b32 s8, s10
	v_lshl_add_u64 v[90:91], v[72:73], 0, s[8:9]
	global_load_dwordx4 v[138:141], v[90:91], off offset:64
	s_mov_b32 s8, s19
	v_lshl_add_u64 v[68:69], v[74:75], 0, s[8:9]
	global_load_dwordx4 v[142:145], v[68:69], off offset:64
	s_mov_b32 s8, s11
	v_lshl_add_u64 v[70:71], v[72:73], 0, s[8:9]
	global_load_dwordx4 v[146:149], v[70:71], off offset:64
	s_mov_b32 s8, s12
	v_lshl_add_u64 v[88:89], v[72:73], 0, s[8:9]
	global_load_dwordx4 v[150:153], v[88:89], off offset:64
	s_mov_b32 s8, s13
	v_lshl_add_u64 v[90:91], v[72:73], 0, s[8:9]
	global_load_dwordx4 v[154:157], v[90:91], off offset:64
	s_mov_b32 s8, s14
	v_lshl_add_u64 v[68:69], v[72:73], 0, s[8:9]
	global_load_dwordx4 v[158:161], v[68:69], off offset:64
	s_mov_b32 s8, s15
	v_lshl_add_u64 v[70:71], v[72:73], 0, s[8:9]
	global_load_dwordx4 v[162:165], v[70:71], off offset:64
	s_mov_b32 s8, s16
	v_lshl_add_u64 v[88:89], v[72:73], 0, s[8:9]
	global_load_dwordx4 v[166:169], v[88:89], off offset:64
	s_mov_b32 s8, s17
	v_lshl_add_u64 v[90:91], v[72:73], 0, s[8:9]
	global_load_dwordx4 v[170:173], v[90:91], off offset:64
	s_mov_b32 s8, s18
	v_lshl_add_u64 v[68:69], v[74:75], 0, s[8:9]
	global_load_dwordx4 v[174:177], v[68:69], off offset:128
	s_mov_b32 s8, s10
	v_lshl_add_u64 v[70:71], v[72:73], 0, s[8:9]
	global_load_dwordx4 v[178:181], v[70:71], off offset:128
	s_mov_b32 s8, s19
	v_lshl_add_u64 v[88:89], v[74:75], 0, s[8:9]
	global_load_dwordx4 v[182:185], v[88:89], off offset:128
	s_mov_b32 s8, s11
	v_lshl_add_u64 v[90:91], v[72:73], 0, s[8:9]
	global_load_dwordx4 v[186:189], v[90:91], off offset:128
	s_mov_b32 s8, s12
	v_lshl_add_u64 v[68:69], v[72:73], 0, s[8:9]
	global_load_dwordx4 v[190:193], v[68:69], off offset:128
	s_mov_b32 s8, s13
	v_lshl_add_u64 v[70:71], v[72:73], 0, s[8:9]
	global_load_dwordx4 v[206:209], v[70:71], off offset:128
	s_mov_b32 s8, s14
	v_lshl_add_u64 v[88:89], v[72:73], 0, s[8:9]
	global_load_dwordx4 v[210:213], v[88:89], off offset:128
	s_mov_b32 s8, s15
	v_lshl_add_u64 v[90:91], v[72:73], 0, s[8:9]
	global_load_dwordx4 v[214:217], v[90:91], off offset:128
	s_mov_b32 s8, s16
	v_lshl_add_u64 v[68:69], v[72:73], 0, s[8:9]
	global_load_dwordx4 v[218:221], v[68:69], off offset:128
	s_mov_b32 s8, s17
	v_lshl_add_u64 v[70:71], v[72:73], 0, s[8:9]
	global_load_dwordx4 v[234:237], v[70:71], off offset:128
	s_waitcnt vmcnt(20)
	v_mfma_f32_16x16x32_bf16 v[36:39], v[92:95], v[98:101], v[36:39]
	v_mfma_f32_16x16x32_bf16 v[24:27], v[102:105], v[98:101], v[24:27]
	v_mfma_f32_16x16x32_bf16 v[20:23], v[92:95], v[106:109], v[20:23]
	v_mfma_f32_16x16x32_bf16 v[16:19], v[102:105], v[106:109], v[16:19]
	v_mfma_f32_16x16x32_bf16 v[12:15], v[92:95], v[110:113], v[12:15]
	v_mfma_f32_16x16x32_bf16 v[8:11], v[102:105], v[110:113], v[8:11]
	v_mfma_f32_16x16x32_bf16 v[4:7], v[92:95], v[114:117], v[4:7]
	v_mfma_f32_16x16x32_bf16 v[0:3], v[102:105], v[114:117], v[0:3]
	v_mfma_f32_16x16x32_bf16 v[28:31], v[92:95], v[118:121], v[28:31]
	v_mfma_f32_16x16x32_bf16 v[32:35], v[102:105], v[118:121], v[32:35]
	v_mfma_f32_16x16x32_bf16 v[40:43], v[92:95], v[122:125], v[40:43]
	v_mfma_f32_16x16x32_bf16 v[44:47], v[102:105], v[122:125], v[44:47]
	v_mfma_f32_16x16x32_bf16 v[48:51], v[92:95], v[126:129], v[48:51]
	v_mfma_f32_16x16x32_bf16 v[52:55], v[102:105], v[126:129], v[52:55]
	v_mfma_f32_16x16x32_bf16 v[56:59], v[92:95], v[130:133], v[56:59]
	v_mfma_f32_16x16x32_bf16 v[60:63], v[102:105], v[130:133], v[60:63]
	s_mov_b32 s8, s18
	v_lshl_add_u64 v[88:89], v[74:75], 0, s[8:9]
	global_load_dwordx4 v[92:95], v[88:89], off offset:192
	s_mov_b32 s8, s10
	v_lshl_add_u64 v[90:91], v[72:73], 0, s[8:9]
	global_load_dwordx4 v[98:101], v[90:91], off offset:192
	s_mov_b32 s8, s19
	v_lshl_add_u64 v[68:69], v[74:75], 0, s[8:9]
	global_load_dwordx4 v[102:105], v[68:69], off offset:192
	s_mov_b32 s8, s11
	v_lshl_add_u64 v[70:71], v[72:73], 0, s[8:9]
	global_load_dwordx4 v[106:109], v[70:71], off offset:192
	s_mov_b32 s8, s12
	v_lshl_add_u64 v[88:89], v[72:73], 0, s[8:9]
	global_load_dwordx4 v[110:113], v[88:89], off offset:192
	s_mov_b32 s8, s13
	v_lshl_add_u64 v[90:91], v[72:73], 0, s[8:9]
	global_load_dwordx4 v[114:117], v[90:91], off offset:192
	s_mov_b32 s8, s14
	v_lshl_add_u64 v[68:69], v[72:73], 0, s[8:9]
	global_load_dwordx4 v[118:121], v[68:69], off offset:192
	s_mov_b32 s8, s15
	v_lshl_add_u64 v[70:71], v[72:73], 0, s[8:9]
	global_load_dwordx4 v[122:125], v[70:71], off offset:192
	s_mov_b32 s8, s16
	v_lshl_add_u64 v[88:89], v[72:73], 0, s[8:9]
	global_load_dwordx4 v[126:129], v[88:89], off offset:192
	s_mov_b32 s8, s17
	v_lshl_add_u64 v[90:91], v[72:73], 0, s[8:9]
	global_load_dwordx4 v[130:133], v[90:91], off offset:192
	s_waitcnt vmcnt(20)
; #define LAS __attribute__((address_space(3)))
; template <int KSTEPS  >
; __device__ __forceinline__ void small_mma_ksplit(f32x4 (&acc)[2], const bf16_t* A, int lda, const bf16_t* Bt, int ldb, int n0, LAS unsigned char* lds, const SmallId& id) {
;     ...
; #pragma unroll
;         for (int rb = 0; rb < 8; ++rb) { part[rb][0] = __builtin_amdgcn_mfma_f32_16x16x32_bf16(b[0], a[rb], part[rb][0], 0, 0, 0); part[rb][1] = __builtin_amdgcn_mfma_f32_16x16x32_bf16(b[1], a[rb], part[rb][1], 0, 0, 0); }
;     }
;     LAS f32x4* red = (LAS f32x4*)lds;
; #pragma unroll
;     for (int rb = 0; rb < 8; ++rb) { red[((id.w * 8 + rb) * 2 + 0) * 64 + lane] = part[rb][0]; red[((id.w * 8 + rb) * 2 + 1) * 64 + lane] = part[rb][1]; }
	v_mfma_f32_16x16x32_bf16 v[36:39], v[134:137], v[138:141], v[36:39]
	v_mfma_f32_16x16x32_bf16 v[24:27], v[142:145], v[138:141], v[24:27]
	v_mfma_f32_16x16x32_bf16 v[20:23], v[134:137], v[146:149], v[20:23]
	v_mfma_f32_16x16x32_bf16 v[16:19], v[142:145], v[146:149], v[16:19]
	v_mfma_f32_16x16x32_bf16 v[12:15], v[134:137], v[150:153], v[12:15]
	v_mfma_f32_16x16x32_bf16 v[8:11], v[142:145], v[150:153], v[8:11]
	v_mfma_f32_16x16x32_bf16 v[4:7], v[134:137], v[154:157], v[4:7]
	v_mfma_f32_16x16x32_bf16 v[0:3], v[142:145], v[154:157], v[0:3]
	v_mfma_f32_16x16x32_bf16 v[28:31], v[134:137], v[158:161], v[28:31]
	v_mfma_f32_16x16x32_bf16 v[32:35], v[142:145], v[158:161], v[32:35]
	v_mfma_f32_16x16x32_bf16 v[40:43], v[134:137], v[162:165], v[40:43]
	v_mfma_f32_16x16x32_bf16 v[44:47], v[142:145], v[162:165], v[44:47]
	v_mfma_f32_16x16x32_bf16 v[48:51], v[134:137], v[166:169], v[48:51]
	v_mfma_f32_16x16x32_bf16 v[52:55], v[142:145], v[166:169], v[52:55]
	v_mfma_f32_16x16x32_bf16 v[56:59], v[134:137], v[170:173], v[56:59]
	v_mfma_f32_16x16x32_bf16 v[60:63], v[142:145], v[170:173], v[60:63]
	s_waitcnt vmcnt(10)
	v_mfma_f32_16x16x32_bf16 v[36:39], v[174:177], v[178:181], v[36:39]
	v_mfma_f32_16x16x32_bf16 v[24:27], v[182:185], v[178:181], v[24:27]
	v_mfma_f32_16x16x32_bf16 v[20:23], v[174:177], v[186:189], v[20:23]
	v_mfma_f32_16x16x32_bf16 v[16:19], v[182:185], v[186:189], v[16:19]
	v_mfma_f32_16x16x32_bf16 v[12:15], v[174:177], v[190:193], v[12:15]
	v_mfma_f32_16x16x32_bf16 v[8:11], v[182:185], v[190:193], v[8:11]
	v_mfma_f32_16x16x32_bf16 v[4:7], v[174:177], v[206:209], v[4:7]
	v_mfma_f32_16x16x32_bf16 v[0:3], v[182:185], v[206:209], v[0:3]
	v_mfma_f32_16x16x32_bf16 v[28:31], v[174:177], v[210:213], v[28:31]
	v_mfma_f32_16x16x32_bf16 v[32:35], v[182:185], v[210:213], v[32:35]
	v_mfma_f32_16x16x32_bf16 v[40:43], v[174:177], v[214:217], v[40:43]
	v_mfma_f32_16x16x32_bf16 v[44:47], v[182:185], v[214:217], v[44:47]
	v_mfma_f32_16x16x32_bf16 v[48:51], v[174:177], v[218:221], v[48:51]
	v_mfma_f32_16x16x32_bf16 v[52:55], v[182:185], v[218:221], v[52:55]
	v_mfma_f32_16x16x32_bf16 v[56:59], v[174:177], v[234:237], v[56:59]
	v_mfma_f32_16x16x32_bf16 v[60:63], v[182:185], v[234:237], v[60:63]
	s_waitcnt vmcnt(0)
	v_mfma_f32_16x16x32_bf16 v[36:39], v[92:95], v[98:101], v[36:39]
	v_mfma_f32_16x16x32_bf16 v[24:27], v[102:105], v[98:101], v[24:27]
	v_mfma_f32_16x16x32_bf16 v[20:23], v[92:95], v[106:109], v[20:23]
	v_mfma_f32_16x16x32_bf16 v[16:19], v[102:105], v[106:109], v[16:19]
	v_mfma_f32_16x16x32_bf16 v[12:15], v[92:95], v[110:113], v[12:15]
	v_mfma_f32_16x16x32_bf16 v[8:11], v[102:105], v[110:113], v[8:11]
	v_mfma_f32_16x16x32_bf16 v[4:7], v[92:95], v[114:117], v[4:7]
	v_mfma_f32_16x16x32_bf16 v[0:3], v[102:105], v[114:117], v[0:3]
	v_mfma_f32_16x16x32_bf16 v[28:31], v[92:95], v[118:121], v[28:31]
	v_mfma_f32_16x16x32_bf16 v[32:35], v[102:105], v[118:121], v[32:35]
	v_mfma_f32_16x16x32_bf16 v[40:43], v[92:95], v[122:125], v[40:43]
	v_mfma_f32_16x16x32_bf16 v[44:47], v[102:105], v[122:125], v[44:47]
	v_mfma_f32_16x16x32_bf16 v[48:51], v[92:95], v[126:129], v[48:51]
	v_mfma_f32_16x16x32_bf16 v[52:55], v[102:105], v[126:129], v[52:55]
	v_mfma_f32_16x16x32_bf16 v[56:59], v[92:95], v[130:133], v[56:59]
	v_mfma_f32_16x16x32_bf16 v[60:63], v[102:105], v[130:133], v[60:63]
	ds_write_b128 v76, v[36:39]
	ds_write_b128 v76, v[24:27] offset:1024
	ds_write_b128 v76, v[20:23] offset:2048
	ds_write_b128 v76, v[16:19] offset:3072
	ds_write_b128 v76, v[12:15] offset:4096
	ds_write_b128 v76, v[8:11] offset:5120
	ds_write_b128 v76, v[4:7] offset:6144
	ds_write_b128 v76, v[0:3] offset:7168
	ds_write_b128 v76, v[28:31] offset:8192
	ds_write_b128 v76, v[32:35] offset:9216
	ds_write_b128 v76, v[40:43] offset:10240
	ds_write_b128 v76, v[44:47] offset:11264
	ds_write_b128 v76, v[48:51] offset:12288
	ds_write_b128 v76, v[52:55] offset:13312
	ds_write_b128 v76, v[56:59] offset:14336
	ds_write_b128 v76, v[60:63] offset:15360
	s_waitcnt lgkmcnt(0)
	s_waitcnt lgkmcnt(0)
	s_barrier
; __device__ __forceinline__ unsigned cvt_pk_bf16(float lo, float hi) { unsigned r; asm volatile("v_cvt_pk_bf16_f32 %0, %1, %2" : "=v"(r) : "v"(lo), "v"(hi)); return r; }
; template <int KSTEPS  >
; __device__ __forceinline__ void small_mma_ksplit(f32x4 (&acc)[2], const bf16_t* A, int lda, const bf16_t* Bt, int ldb, int n0, LAS unsigned char* lds, const SmallId& id) {
;     ...
;     acc[0] = (f32x4){0.f, 0.f, 0.f, 0.f}; acc[1] = acc[0];
; #pragma unroll
;     for (int w2 = 0; w2 < 8; ++w2) { acc[0] += red[((w2 * 8 + id.w) * 2 + 0) * 64 + lane]; acc[1] += red[((w2 * 8 + id.w) * 2 + 1) * 64 + lane]; }
;     asm volatile("s_waitcnt lgkmcnt(0)" ::: "memory"); __syncthreads();
; template <bool RES_F32, bool OUT_F32, int KSTEPS>
; __device__ __forceinline__ void small_res(const Params& p, LAS unsigned char* lds, const bf16_t* A, int lda, const bf16_t* Bt, int K, float* ssq_next, int G, int bx) {
;     ...
; #pragma unroll
;         for (int nb = 0; nb < 2; ++nb) { const int col = n0 + 16 * nb + 4 * id.fq;
;             f32x4 r;
;             if (RES_F32) r = *(const f32x4*)(p.xs + (size_t)(id.row - MP) * DM + col);
;             else { const u32x2 w = *(const u32x2*)(XB + (size_t)id.row * DM + col); r = (f32x4){bf_lo(w.x), bf_hi(w.x), bf_lo(w.y), bf_hi(w.y)}; }
;             const f32x4 x = r + acc[nb];
;             if (OUT_F32) *(f32x4*)(p.out + (size_t)id.row * DM + col) = x;
;             else { u32x2 w; w.x = cvt_pk_bf16(x[0], x[1]); w.y = cvt_pk_bf16(x[2], x[3]); *(u32x2*)(XB + (size_t)id.row * DM + col) = w; }
;             s += (x[0] * x[0] + x[1] * x[1]) + (x[2] * x[2] + x[3] * x[3]); }
;         if (!OUT_F32) { s += __shfl_xor(s, 16); s += __shfl_xor(s, 32); if (id.fq == 0) atomicAdd(ssq_next + id.row, s); }
	ds_read_b128 v[0:3], v77
	s_waitcnt lgkmcnt(0)
	v_pk_add_f32 v[4:5], v[2:3], 0 op_sel_hi:[1,0]
	v_pk_add_f32 v[6:7], v[0:1], 0 op_sel_hi:[1,0]
	ds_read_b128 v[0:3], v77 offset:1024
	s_waitcnt lgkmcnt(0)
	v_pk_add_f32 v[8:9], v[2:3], 0 op_sel_hi:[1,0]
	v_pk_add_f32 v[10:11], v[0:1], 0 op_sel_hi:[1,0]
	ds_read_b128 v[0:3], v77 offset:16384
	s_waitcnt lgkmcnt(0)
	v_pk_add_f32 v[4:5], v[4:5], v[2:3]
	v_pk_add_f32 v[6:7], v[6:7], v[0:1]
	ds_read_b128 v[0:3], v77 offset:17408
	s_waitcnt lgkmcnt(0)
	v_pk_add_f32 v[8:9], v[8:9], v[2:3]
	v_pk_add_f32 v[10:11], v[10:11], v[0:1]
	ds_read_b128 v[0:3], v77 offset:32768
	s_waitcnt lgkmcnt(0)
	v_pk_add_f32 v[4:5], v[4:5], v[2:3]
	v_pk_add_f32 v[6:7], v[6:7], v[0:1]
	ds_read_b128 v[0:3], v77 offset:33792
	s_waitcnt lgkmcnt(0)
	v_pk_add_f32 v[8:9], v[8:9], v[2:3]
	v_pk_add_f32 v[10:11], v[10:11], v[0:1]
	ds_read_b128 v[0:3], v77 offset:49152
	s_waitcnt lgkmcnt(0)
	v_pk_add_f32 v[4:5], v[4:5], v[2:3]
	v_pk_add_f32 v[6:7], v[6:7], v[0:1]
	ds_read_b128 v[0:3], v77 offset:50176
	s_waitcnt lgkmcnt(0)
	v_pk_add_f32 v[8:9], v[8:9], v[2:3]
	v_pk_add_f32 v[10:11], v[10:11], v[0:1]
	ds_read_b128 v[0:3], v78
	s_waitcnt lgkmcnt(0)
	v_pk_add_f32 v[4:5], v[4:5], v[2:3]
	v_pk_add_f32 v[6:7], v[6:7], v[0:1]
	ds_read_b128 v[0:3], v79
	s_waitcnt lgkmcnt(0)
	v_pk_add_f32 v[8:9], v[8:9], v[2:3]
	v_pk_add_f32 v[10:11], v[10:11], v[0:1]
	ds_read_b128 v[0:3], v80
	s_waitcnt lgkmcnt(0)
	v_pk_add_f32 v[4:5], v[4:5], v[2:3]
	v_pk_add_f32 v[6:7], v[6:7], v[0:1]
	ds_read_b128 v[0:3], v81
	s_waitcnt lgkmcnt(0)
	v_pk_add_f32 v[8:9], v[8:9], v[2:3]
	v_pk_add_f32 v[10:11], v[10:11], v[0:1]
	ds_read_b128 v[0:3], v82
	s_waitcnt lgkmcnt(0)
	v_pk_add_f32 v[4:5], v[4:5], v[2:3]
	v_pk_add_f32 v[6:7], v[6:7], v[0:1]
	ds_read_b128 v[0:3], v83
	s_waitcnt lgkmcnt(0)
	v_pk_add_f32 v[8:9], v[8:9], v[2:3]
	v_pk_add_f32 v[10:11], v[10:11], v[0:1]
	ds_read_b128 v[0:3], v84
	s_waitcnt lgkmcnt(0)
	v_pk_add_f32 v[4:5], v[4:5], v[2:3]
	v_pk_add_f32 v[6:7], v[6:7], v[0:1]
	ds_read_b128 v[0:3], v85
	s_waitcnt lgkmcnt(0)
	s_waitcnt lgkmcnt(0)
	s_barrier
	v_pk_add_f32 v[2:3], v[8:9], v[2:3]
	v_lshl_or_b32 v8, s7, 5, v86
	v_ashrrev_i32_e32 v9, 31, v8
	v_lshl_add_u64 v[8:9], v[8:9], 1, v[64:65]
	v_pk_add_f32 v[0:1], v[10:11], v[0:1]
	global_load_dwordx2 v[10:11], v[8:9], off
	s_waitcnt vmcnt(0) lgkmcnt(0)
	v_lshlrev_b32_e32 v12, 16, v10
	v_and_b32_e32 v13, 0xffff0000, v10
	v_lshlrev_b32_e32 v10, 16, v11
	v_and_b32_e32 v11, 0xffff0000, v11
	v_pk_add_f32 v[4:5], v[4:5], v[10:11]
	v_pk_add_f32 v[6:7], v[6:7], v[12:13]
	s_nop 0
	v_cvt_pk_bf16_f32 v10, v6, v7
	v_cvt_pk_bf16_f32 v11, v4, v5
	v_mul_f32_e32 v7, v7, v7
	v_mul_f32_e32 v5, v5, v5
	v_fmac_f32_e32 v7, v6, v6
	v_fmac_f32_e32 v5, v4, v4
	global_store_dwordx2 v[8:9], v[10:11], off
	v_add_f32_e32 v10, v7, v5
	global_load_dwordx2 v[4:5], v[8:9], off offset:32
	s_waitcnt vmcnt(0) lgkmcnt(0)
	v_lshlrev_b32_e32 v6, 16, v4
	v_and_b32_e32 v7, 0xffff0000, v4
	v_lshlrev_b32_e32 v4, 16, v5
	v_and_b32_e32 v5, 0xffff0000, v5
	v_pk_add_f32 v[0:1], v[0:1], v[6:7]
	v_pk_add_f32 v[2:3], v[2:3], v[4:5]
	v_cvt_pk_bf16_f32 v4, v0, v1
	v_mul_f32_e32 v1, v1, v1
	v_fmac_f32_e32 v1, v0, v0
	v_mul_f32_e32 v0, v3, v3
	v_cvt_pk_bf16_f32 v5, v2, v3
	v_fmac_f32_e32 v0, v2, v2
	v_and_b32_e32 v2, 64, v225
	v_add_f32_e32 v0, v1, v0
	v_xor_b32_e32 v1, 16, v225
	v_add_u32_e32 v2, 64, v2
	v_cmp_lt_i32_e64 s[0:1], v1, v2
	v_add_f32_e32 v0, v10, v0
	global_store_dwordx2 v[8:9], v[4:5], off offset:32
	v_cndmask_b32_e64 v1, v225, v1, s[0:1]
	v_lshlrev_b32_e32 v1, 2, v1
	ds_bpermute_b32 v1, v1, v0
	s_waitcnt lgkmcnt(0)
	v_add_f32_e32 v0, v0, v1
	v_xor_b32_e32 v1, 32, v225
	v_cmp_lt_i32_e64 s[0:1], v1, v2
	s_nop 1
	v_cndmask_b32_e64 v1, v225, v1, s[0:1]
	v_lshlrev_b32_e32 v1, 2, v1
	ds_bpermute_b32 v1, v1, v0
	s_and_saveexec_b64 s[0:1], vcc
	s_cbranch_execz .LBB0_861
	s_waitcnt lgkmcnt(0)
	v_add_f32_e32 v0, v0, v1
	global_atomic_add_f32 v[66:67], v0, off
	s_branch .LBB0_861

; template <int KSTEPS  >
; __device__ __forceinline__ void small_mma_ksplit(f32x4 (&acc)[2], const bf16_t* A, int lda, const bf16_t* Bt, int ldb, int n0, LAS unsigned char* lds, const SmallId& id) {
;     ...
;     for (int ks = 0; ks < KSTEPS; ++ks) {
;         bf16x8 a[8], b[2];
; #pragma unroll
;         for (int rb = 0; rb < 8; ++rb) a[rb] = *(const bf16x8*)(ap + (size_t)(16 * rb) * lda + 32 * ks);
;         b[0] = *(const bf16x8*)(bp + 32 * ks); b[1] = *(const bf16x8*)(bp + (size_t)16 * ldb + 32 * ks);
; #pragma unroll
;         for (int rb = 0; rb < 8; ++rb) { part[rb][0] = __builtin_amdgcn_mfma_f32_16x16x32_bf16(b[0], a[rb], part[rb][0], 0, 0, 0); part[rb][1] = __builtin_amdgcn_mfma_f32_16x16x32_bf16(b[1], a[rb], part[rb][1], 0, 0, 0); }
;     }
.LBB0_908:
	s_waitcnt lgkmcnt(0)
	s_mov_b32 s9, 0
	s_mov_b32 s8, s18
	v_lshl_add_u64 v[70:71], v[76:77], 0, s[8:9]
	global_load_dwordx4 v[98:101], v[70:71], off
	s_mov_b32 s8, s10
	v_lshl_add_u64 v[72:73], v[74:75], 0, s[8:9]
	global_load_dwordx4 v[102:105], v[72:73], off
	s_mov_b32 s8, s19
	v_lshl_add_u64 v[90:91], v[76:77], 0, s[8:9]
	global_load_dwordx4 v[106:109], v[90:91], off
	s_mov_b32 s8, s11
	v_lshl_add_u64 v[92:93], v[74:75], 0, s[8:9]
	global_load_dwordx4 v[110:113], v[92:93], off
	s_mov_b32 s8, s12
	v_lshl_add_u64 v[70:71], v[74:75], 0, s[8:9]
	global_load_dwordx4 v[114:117], v[70:71], off
	s_mov_b32 s8, s13
	v_lshl_add_u64 v[72:73], v[74:75], 0, s[8:9]
	global_load_dwordx4 v[118:121], v[72:73], off
	s_mov_b32 s8, s14
	v_lshl_add_u64 v[90:91], v[74:75], 0, s[8:9]
	global_load_dwordx4 v[122:125], v[90:91], off
	s_mov_b32 s8, s15
	v_lshl_add_u64 v[92:93], v[74:75], 0, s[8:9]
	global_load_dwordx4 v[126:129], v[92:93], off
	s_mov_b32 s8, s16
	v_lshl_add_u64 v[70:71], v[74:75], 0, s[8:9]
	global_load_dwordx4 v[130:133], v[70:71], off
	s_mov_b32 s8, s17
	v_lshl_add_u64 v[72:73], v[74:75], 0, s[8:9]
	global_load_dwordx4 v[134:137], v[72:73], off
	s_mov_b32 s8, s18
	v_lshl_add_u64 v[90:91], v[76:77], 0, s[8:9]
	global_load_dwordx4 v[138:141], v[90:91], off offset:64
	s_mov_b32 s8, s10
	v_lshl_add_u64 v[92:93], v[74:75], 0, s[8:9]
	global_load_dwordx4 v[142:145], v[92:93], off offset:64
	s_mov_b32 s8, s19
	v_lshl_add_u64 v[70:71], v[76:77], 0, s[8:9]
	global_load_dwordx4 v[146:149], v[70:71], off offset:64
	s_mov_b32 s8, s11
	v_lshl_add_u64 v[72:73], v[74:75], 0, s[8:9]
	global_load_dwordx4 v[150:153], v[72:73], off offset:64
	s_mov_b32 s8, s12
	v_lshl_add_u64 v[90:91], v[74:75], 0, s[8:9]
	global_load_dwordx4 v[154:157], v[90:91], off offset:64
	s_mov_b32 s8, s13
	v_lshl_add_u64 v[92:93], v[74:75], 0, s[8:9]
	global_load_dwordx4 v[158:161], v[92:93], off offset:64
	s_mov_b32 s8, s14
	v_lshl_add_u64 v[70:71], v[74:75], 0, s[8:9]
	global_load_dwordx4 v[162:165], v[70:71], off offset:64
	s_mov_b32 s8, s15
	v_lshl_add_u64 v[72:73], v[74:75], 0, s[8:9]
	global_load_dwordx4 v[166:169], v[72:73], off offset:64
	s_mov_b32 s8, s16
	v_lshl_add_u64 v[90:91], v[74:75], 0, s[8:9]
	global_load_dwordx4 v[170:173], v[90:91], off offset:64
	s_mov_b32 s8, s17
	v_lshl_add_u64 v[92:93], v[74:75], 0, s[8:9]
	global_load_dwordx4 v[174:177], v[92:93], off offset:64
	s_mov_b32 s8, s18
	v_lshl_add_u64 v[70:71], v[76:77], 0, s[8:9]
	global_load_dwordx4 v[178:181], v[70:71], off offset:128
	s_mov_b32 s8, s10
	v_lshl_add_u64 v[72:73], v[74:75], 0, s[8:9]
	global_load_dwordx4 v[182:185], v[72:73], off offset:128
	s_mov_b32 s8, s19
	v_lshl_add_u64 v[90:91], v[76:77], 0, s[8:9]
	global_load_dwordx4 v[186:189], v[90:91], off offset:128
	s_mov_b32 s8, s11
	v_lshl_add_u64 v[92:93], v[74:75], 0, s[8:9]
	global_load_dwordx4 v[190:193], v[92:93], off offset:128
	s_mov_b32 s8, s12
	v_lshl_add_u64 v[70:71], v[74:75], 0, s[8:9]
	global_load_dwordx4 v[206:209], v[70:71], off offset:128
	s_mov_b32 s8, s13
	v_lshl_add_u64 v[72:73], v[74:75], 0, s[8:9]
	global_load_dwordx4 v[210:213], v[72:73], off offset:128
	s_mov_b32 s8, s14
	v_lshl_add_u64 v[90:91], v[74:75], 0, s[8:9]
	global_load_dwordx4 v[214:217], v[90:91], off offset:128
	s_mov_b32 s8, s15
	v_lshl_add_u64 v[92:93], v[74:75], 0, s[8:9]
	global_load_dwordx4 v[218:221], v[92:93], off offset:128
	s_mov_b32 s8, s16
	v_lshl_add_u64 v[70:71], v[74:75], 0, s[8:9]
	global_load_dwordx4 v[234:237], v[70:71], off offset:128
	s_mov_b32 s8, s17
	v_lshl_add_u64 v[72:73], v[74:75], 0, s[8:9]
	global_load_dwordx4 v[250:253], v[72:73], off offset:128
	s_waitcnt vmcnt(20)
	v_mfma_f32_16x16x32_bf16 v[36:39], v[98:101], v[102:105], v[36:39]
	v_mfma_f32_16x16x32_bf16 v[24:27], v[106:109], v[102:105], v[24:27]
	v_mfma_f32_16x16x32_bf16 v[20:23], v[98:101], v[110:113], v[20:23]
	v_mfma_f32_16x16x32_bf16 v[16:19], v[106:109], v[110:113], v[16:19]
	v_mfma_f32_16x16x32_bf16 v[12:15], v[98:101], v[114:117], v[12:15]
	v_mfma_f32_16x16x32_bf16 v[8:11], v[106:109], v[114:117], v[8:11]
	v_mfma_f32_16x16x32_bf16 v[4:7], v[98:101], v[118:121], v[4:7]
	v_mfma_f32_16x16x32_bf16 v[0:3], v[106:109], v[118:121], v[0:3]
	v_mfma_f32_16x16x32_bf16 v[28:31], v[98:101], v[122:125], v[28:31]
	v_mfma_f32_16x16x32_bf16 v[32:35], v[106:109], v[122:125], v[32:35]
	v_mfma_f32_16x16x32_bf16 v[40:43], v[98:101], v[126:129], v[40:43]
	v_mfma_f32_16x16x32_bf16 v[44:47], v[106:109], v[126:129], v[44:47]
	v_mfma_f32_16x16x32_bf16 v[48:51], v[98:101], v[130:133], v[48:51]
	v_mfma_f32_16x16x32_bf16 v[52:55], v[106:109], v[130:133], v[52:55]
	v_mfma_f32_16x16x32_bf16 v[56:59], v[98:101], v[134:137], v[56:59]
	v_mfma_f32_16x16x32_bf16 v[60:63], v[106:109], v[134:137], v[60:63]
	s_mov_b32 s8, s18
	v_lshl_add_u64 v[90:91], v[76:77], 0, s[8:9]
	global_load_dwordx4 v[98:101], v[90:91], off offset:192
	s_mov_b32 s8, s10
	v_lshl_add_u64 v[92:93], v[74:75], 0, s[8:9]
	global_load_dwordx4 v[102:105], v[92:93], off offset:192
	s_mov_b32 s8, s19
	v_lshl_add_u64 v[70:71], v[76:77], 0, s[8:9]
	global_load_dwordx4 v[106:109], v[70:71], off offset:192
	s_mov_b32 s8, s11
	v_lshl_add_u64 v[72:73], v[74:75], 0, s[8:9]
	global_load_dwordx4 v[110:113], v[72:73], off offset:192
	s_mov_b32 s8, s12
	v_lshl_add_u64 v[90:91], v[74:75], 0, s[8:9]
	global_load_dwordx4 v[114:117], v[90:91], off offset:192
	s_mov_b32 s8, s13
	v_lshl_add_u64 v[92:93], v[74:75], 0, s[8:9]
	global_load_dwordx4 v[118:121], v[92:93], off offset:192
	s_mov_b32 s8, s14
	v_lshl_add_u64 v[70:71], v[74:75], 0, s[8:9]
	global_load_dwordx4 v[122:125], v[70:71], off offset:192
	s_mov_b32 s8, s15
	v_lshl_add_u64 v[72:73], v[74:75], 0, s[8:9]
	global_load_dwordx4 v[126:129], v[72:73], off offset:192
	s_mov_b32 s8, s16
	v_lshl_add_u64 v[90:91], v[74:75], 0, s[8:9]
	global_load_dwordx4 v[130:133], v[90:91], off offset:192
	s_mov_b32 s8, s17
	v_lshl_add_u64 v[92:93], v[74:75], 0, s[8:9]
	global_load_dwordx4 v[134:137], v[92:93], off offset:192
	s_waitcnt vmcnt(20)
; #define LAS __attribute__((address_space(3)))
; template <int KSTEPS  >
; __device__ __forceinline__ void small_mma_ksplit(f32x4 (&acc)[2], const bf16_t* A, int lda, const bf16_t* Bt, int ldb, int n0, LAS unsigned char* lds, const SmallId& id) {
;     ...
; #pragma unroll
;         for (int rb = 0; rb < 8; ++rb) { part[rb][0] = __builtin_amdgcn_mfma_f32_16x16x32_bf16(b[0], a[rb], part[rb][0], 0, 0, 0); part[rb][1] = __builtin_amdgcn_mfma_f32_16x16x32_bf16(b[1], a[rb], part[rb][1], 0, 0, 0); }
;     }
;     LAS f32x4* red = (LAS f32x4*)lds;
; #pragma unroll
;     for (int rb = 0; rb < 8; ++rb) { red[((id.w * 8 + rb) * 2 + 0) * 64 + lane] = part[rb][0]; red[((id.w * 8 + rb) * 2 + 1) * 64 + lane] = part[rb][1]; }
	v_mfma_f32_16x16x32_bf16 v[36:39], v[138:141], v[142:145], v[36:39]
	v_mfma_f32_16x16x32_bf16 v[24:27], v[146:149], v[142:145], v[24:27]
	v_mfma_f32_16x16x32_bf16 v[20:23], v[138:141], v[150:153], v[20:23]
	v_mfma_f32_16x16x32_bf16 v[16:19], v[146:149], v[150:153], v[16:19]
	v_mfma_f32_16x16x32_bf16 v[12:15], v[138:141], v[154:157], v[12:15]
	v_mfma_f32_16x16x32_bf16 v[8:11], v[146:149], v[154:157], v[8:11]
	v_mfma_f32_16x16x32_bf16 v[4:7], v[138:141], v[158:161], v[4:7]
	v_mfma_f32_16x16x32_bf16 v[0:3], v[146:149], v[158:161], v[0:3]
	v_mfma_f32_16x16x32_bf16 v[28:31], v[138:141], v[162:165], v[28:31]
	v_mfma_f32_16x16x32_bf16 v[32:35], v[146:149], v[162:165], v[32:35]
	v_mfma_f32_16x16x32_bf16 v[40:43], v[138:141], v[166:169], v[40:43]
	v_mfma_f32_16x16x32_bf16 v[44:47], v[146:149], v[166:169], v[44:47]
	v_mfma_f32_16x16x32_bf16 v[48:51], v[138:141], v[170:173], v[48:51]
	v_mfma_f32_16x16x32_bf16 v[52:55], v[146:149], v[170:173], v[52:55]
	v_mfma_f32_16x16x32_bf16 v[56:59], v[138:141], v[174:177], v[56:59]
	v_mfma_f32_16x16x32_bf16 v[60:63], v[146:149], v[174:177], v[60:63]
	s_waitcnt vmcnt(10)
	v_mfma_f32_16x16x32_bf16 v[36:39], v[178:181], v[182:185], v[36:39]
	v_mfma_f32_16x16x32_bf16 v[24:27], v[186:189], v[182:185], v[24:27]
	v_mfma_f32_16x16x32_bf16 v[20:23], v[178:181], v[190:193], v[20:23]
	v_mfma_f32_16x16x32_bf16 v[16:19], v[186:189], v[190:193], v[16:19]
	v_mfma_f32_16x16x32_bf16 v[12:15], v[178:181], v[206:209], v[12:15]
	v_mfma_f32_16x16x32_bf16 v[8:11], v[186:189], v[206:209], v[8:11]
	v_mfma_f32_16x16x32_bf16 v[4:7], v[178:181], v[210:213], v[4:7]
	v_mfma_f32_16x16x32_bf16 v[0:3], v[186:189], v[210:213], v[0:3]
	v_mfma_f32_16x16x32_bf16 v[28:31], v[178:181], v[214:217], v[28:31]
	v_mfma_f32_16x16x32_bf16 v[32:35], v[186:189], v[214:217], v[32:35]
	v_mfma_f32_16x16x32_bf16 v[40:43], v[178:181], v[218:221], v[40:43]
	v_mfma_f32_16x16x32_bf16 v[44:47], v[186:189], v[218:221], v[44:47]
	v_mfma_f32_16x16x32_bf16 v[48:51], v[178:181], v[234:237], v[48:51]
	v_mfma_f32_16x16x32_bf16 v[52:55], v[186:189], v[234:237], v[52:55]
	v_mfma_f32_16x16x32_bf16 v[56:59], v[178:181], v[250:253], v[56:59]
	v_mfma_f32_16x16x32_bf16 v[60:63], v[186:189], v[250:253], v[60:63]
	s_waitcnt vmcnt(0)
	v_mfma_f32_16x16x32_bf16 v[36:39], v[98:101], v[102:105], v[36:39]
	v_mfma_f32_16x16x32_bf16 v[24:27], v[106:109], v[102:105], v[24:27]
	v_mfma_f32_16x16x32_bf16 v[20:23], v[98:101], v[110:113], v[20:23]
	v_mfma_f32_16x16x32_bf16 v[16:19], v[106:109], v[110:113], v[16:19]
	v_mfma_f32_16x16x32_bf16 v[12:15], v[98:101], v[114:117], v[12:15]
	v_mfma_f32_16x16x32_bf16 v[8:11], v[106:109], v[114:117], v[8:11]
	v_mfma_f32_16x16x32_bf16 v[4:7], v[98:101], v[118:121], v[4:7]
	v_mfma_f32_16x16x32_bf16 v[0:3], v[106:109], v[118:121], v[0:3]
	v_mfma_f32_16x16x32_bf16 v[28:31], v[98:101], v[122:125], v[28:31]
	v_mfma_f32_16x16x32_bf16 v[32:35], v[106:109], v[122:125], v[32:35]
	v_mfma_f32_16x16x32_bf16 v[40:43], v[98:101], v[126:129], v[40:43]
	v_mfma_f32_16x16x32_bf16 v[44:47], v[106:109], v[126:129], v[44:47]
	v_mfma_f32_16x16x32_bf16 v[48:51], v[98:101], v[130:133], v[48:51]
	v_mfma_f32_16x16x32_bf16 v[52:55], v[106:109], v[130:133], v[52:55]
	v_mfma_f32_16x16x32_bf16 v[56:59], v[98:101], v[134:137], v[56:59]
	v_mfma_f32_16x16x32_bf16 v[60:63], v[106:109], v[134:137], v[60:63]
	ds_write_b128 v78, v[36:39]
	ds_write_b128 v78, v[24:27] offset:1024
	ds_write_b128 v78, v[20:23] offset:2048
	ds_write_b128 v78, v[16:19] offset:3072
	ds_write_b128 v78, v[12:15] offset:4096
	ds_write_b128 v78, v[8:11] offset:5120
	ds_write_b128 v78, v[4:7] offset:6144
	ds_write_b128 v78, v[0:3] offset:7168
	ds_write_b128 v78, v[28:31] offset:8192
	ds_write_b128 v78, v[32:35] offset:9216
	ds_write_b128 v78, v[40:43] offset:10240
	ds_write_b128 v78, v[44:47] offset:11264
	ds_write_b128 v78, v[48:51] offset:12288
	ds_write_b128 v78, v[52:55] offset:13312
	ds_write_b128 v78, v[56:59] offset:14336
	ds_write_b128 v78, v[60:63] offset:15360
	s_waitcnt lgkmcnt(0)
	s_waitcnt lgkmcnt(0)
	s_barrier
; __device__ __forceinline__ unsigned cvt_pk_bf16(float lo, float hi) { unsigned r; asm volatile("v_cvt_pk_bf16_f32 %0, %1, %2" : "=v"(r) : "v"(lo), "v"(hi)); return r; }
; template <int KSTEPS  >
; __device__ __forceinline__ void small_mma_ksplit(f32x4 (&acc)[2], const bf16_t* A, int lda, const bf16_t* Bt, int ldb, int n0, LAS unsigned char* lds, const SmallId& id) {
;     ...
;     acc[0] = (f32x4){0.f, 0.f, 0.f, 0.f}; acc[1] = acc[0];
; #pragma unroll
;     for (int w2 = 0; w2 < 8; ++w2) { acc[0] += red[((w2 * 8 + id.w) * 2 + 0) * 64 + lane]; acc[1] += red[((w2 * 8 + id.w) * 2 + 1) * 64 + lane]; }
;     asm volatile("s_waitcnt lgkmcnt(0)" ::: "memory"); __syncthreads();
; template <bool RES_F32, bool OUT_F32, int KSTEPS>
; __device__ __forceinline__ void small_res(const Params& p, LAS unsigned char* lds, const bf16_t* A, int lda, const bf16_t* Bt, int K, float* ssq_next, int G, int bx) {
;     ...
;         for (int nb = 0; nb < 2; ++nb) { const int col = n0 + 16 * nb + 4 * id.fq;
;             f32x4 r;
;             if (RES_F32) r = *(const f32x4*)(p.xs + (size_t)(id.row - MP) * DM + col);
;             else { const u32x2 w = *(const u32x2*)(XB + (size_t)id.row * DM + col); r = (f32x4){bf_lo(w.x), bf_hi(w.x), bf_lo(w.y), bf_hi(w.y)}; }
;             const f32x4 x = r + acc[nb];
;             if (OUT_F32) *(f32x4*)(p.out + (size_t)id.row * DM + col) = x;
;             else { u32x2 w; w.x = cvt_pk_bf16(x[0], x[1]); w.y = cvt_pk_bf16(x[2], x[3]); *(u32x2*)(XB + (size_t)id.row * DM + col) = w; }
;             s += (x[0] * x[0] + x[1] * x[1]) + (x[2] * x[2] + x[3] * x[3]); }
;         if (!OUT_F32) { s += __shfl_xor(s, 16); s += __shfl_xor(s, 32); if (id.fq == 0) atomicAdd(ssq_next + id.row, s); }
	ds_read_b128 v[0:3], v79
	v_lshl_or_b32 v12, s7, 5, v88
	v_ashrrev_i32_e32 v13, 31, v12
	v_lshl_add_u64 v[14:15], v[12:13], 2, v[68:69]
	s_waitcnt lgkmcnt(0)
	v_pk_add_f32 v[4:5], v[2:3], 0 op_sel_hi:[1,0]
	v_pk_add_f32 v[6:7], v[0:1], 0 op_sel_hi:[1,0]
	ds_read_b128 v[0:3], v79 offset:1024
	s_waitcnt lgkmcnt(0)
	v_pk_add_f32 v[8:9], v[2:3], 0 op_sel_hi:[1,0]
	v_pk_add_f32 v[10:11], v[0:1], 0 op_sel_hi:[1,0]
	ds_read_b128 v[0:3], v79 offset:16384
	s_waitcnt lgkmcnt(0)
	v_pk_add_f32 v[4:5], v[4:5], v[2:3]
	v_pk_add_f32 v[6:7], v[6:7], v[0:1]
	ds_read_b128 v[0:3], v79 offset:17408
	s_waitcnt lgkmcnt(0)
	v_pk_add_f32 v[8:9], v[8:9], v[2:3]
	v_pk_add_f32 v[10:11], v[10:11], v[0:1]
	ds_read_b128 v[0:3], v79 offset:32768
	s_waitcnt lgkmcnt(0)
	v_pk_add_f32 v[4:5], v[4:5], v[2:3]
	v_pk_add_f32 v[6:7], v[6:7], v[0:1]
	ds_read_b128 v[0:3], v79 offset:33792
	s_waitcnt lgkmcnt(0)
	v_pk_add_f32 v[8:9], v[8:9], v[2:3]
	v_pk_add_f32 v[10:11], v[10:11], v[0:1]
	ds_read_b128 v[0:3], v79 offset:49152
	s_waitcnt lgkmcnt(0)
	v_pk_add_f32 v[4:5], v[4:5], v[2:3]
	v_pk_add_f32 v[6:7], v[6:7], v[0:1]
	ds_read_b128 v[0:3], v79 offset:50176
	s_waitcnt lgkmcnt(0)
	v_pk_add_f32 v[8:9], v[8:9], v[2:3]
	v_pk_add_f32 v[10:11], v[10:11], v[0:1]
	ds_read_b128 v[0:3], v80
	s_waitcnt lgkmcnt(0)
	v_pk_add_f32 v[4:5], v[4:5], v[2:3]
	v_pk_add_f32 v[6:7], v[6:7], v[0:1]
	ds_read_b128 v[0:3], v81
	s_waitcnt lgkmcnt(0)
	v_pk_add_f32 v[8:9], v[8:9], v[2:3]
	v_pk_add_f32 v[10:11], v[10:11], v[0:1]
	ds_read_b128 v[0:3], v82
	s_waitcnt lgkmcnt(0)
	v_pk_add_f32 v[4:5], v[4:5], v[2:3]
	v_pk_add_f32 v[6:7], v[6:7], v[0:1]
	ds_read_b128 v[0:3], v83
	s_waitcnt lgkmcnt(0)
	v_pk_add_f32 v[8:9], v[8:9], v[2:3]
	v_pk_add_f32 v[10:11], v[10:11], v[0:1]
	ds_read_b128 v[0:3], v84
	s_waitcnt lgkmcnt(0)
	v_pk_add_f32 v[4:5], v[4:5], v[2:3]
	v_pk_add_f32 v[6:7], v[6:7], v[0:1]
	ds_read_b128 v[0:3], v85
	s_waitcnt lgkmcnt(0)
	v_pk_add_f32 v[8:9], v[8:9], v[2:3]
	v_pk_add_f32 v[10:11], v[10:11], v[0:1]
	ds_read_b128 v[0:3], v86
	s_waitcnt lgkmcnt(0)
	v_pk_add_f32 v[4:5], v[4:5], v[2:3]
	v_pk_add_f32 v[6:7], v[6:7], v[0:1]
	ds_read_b128 v[0:3], v87
	s_waitcnt lgkmcnt(0)
	s_waitcnt lgkmcnt(0)
	s_barrier
	v_pk_add_f32 v[8:9], v[8:9], v[2:3]
	v_pk_add_f32 v[10:11], v[10:11], v[0:1]
	global_load_dwordx4 v[0:3], v[14:15], off
	s_waitcnt vmcnt(0)
	v_pk_add_f32 v[0:1], v[6:7], v[0:1]
	v_pk_add_f32 v[2:3], v[4:5], v[2:3]
	v_cvt_pk_bf16_f32 v4, v0, v1
	v_mul_f32_e32 v1, v1, v1
	v_lshl_add_u64 v[6:7], v[12:13], 1, v[64:65]
	v_fmac_f32_e32 v1, v0, v0
	v_mul_f32_e32 v0, v3, v3
	v_cvt_pk_bf16_f32 v5, v2, v3
	global_store_dwordx2 v[6:7], v[4:5], off
	v_fmac_f32_e32 v0, v2, v2
	v_add_f32_e32 v12, v1, v0
	global_load_dwordx4 v[0:3], v[14:15], off offset:64
	s_waitcnt vmcnt(0)
	v_pk_add_f32 v[0:1], v[10:11], v[0:1]
	v_pk_add_f32 v[2:3], v[8:9], v[2:3]
	v_cvt_pk_bf16_f32 v4, v0, v1
	v_mul_f32_e32 v1, v1, v1
	v_fmac_f32_e32 v1, v0, v0
	v_mul_f32_e32 v0, v3, v3
	v_cvt_pk_bf16_f32 v5, v2, v3
	v_fmac_f32_e32 v0, v2, v2
	v_and_b32_e32 v2, 64, v225
	v_add_f32_e32 v0, v1, v0
	v_xor_b32_e32 v1, 16, v225
	v_add_u32_e32 v2, 64, v2
	v_cmp_lt_i32_e64 s[0:1], v1, v2
	v_add_f32_e32 v0, v12, v0
	global_store_dwordx2 v[6:7], v[4:5], off offset:32
	v_cndmask_b32_e64 v1, v225, v1, s[0:1]
	v_lshlrev_b32_e32 v1, 2, v1
	ds_bpermute_b32 v1, v1, v0
	s_waitcnt lgkmcnt(0)
	v_add_f32_e32 v0, v0, v1
	v_xor_b32_e32 v1, 32, v225
	v_cmp_lt_i32_e64 s[0:1], v1, v2
	s_nop 1
	v_cndmask_b32_e64 v1, v225, v1, s[0:1]
	v_lshlrev_b32_e32 v1, 2, v1
	ds_bpermute_b32 v1, v1, v0
	s_and_saveexec_b64 s[0:1], vcc
	s_cbranch_execz .LBB0_906
	s_waitcnt lgkmcnt(0)
	v_add_f32_e32 v0, v0, v1
	global_atomic_add_f32 v[66:67], v0, off
	s_branch .LBB0_906

; template <int KSTEPS  >
; __device__ __forceinline__ void small_mma_ksplit(f32x4 (&acc)[2], const bf16_t* A, int lda, const bf16_t* Bt, int ldb, int n0, LAS unsigned char* lds, const SmallId& id) {
;     ...
;     for (int ks = 0; ks < KSTEPS; ++ks) {
;         bf16x8 a[8], b[2];
; #pragma unroll
;         for (int rb = 0; rb < 8; ++rb) a[rb] = *(const bf16x8*)(ap + (size_t)(16 * rb) * lda + 32 * ks);
;         b[0] = *(const bf16x8*)(bp + 32 * ks); b[1] = *(const bf16x8*)(bp + (size_t)16 * ldb + 32 * ks);
; #pragma unroll
;         for (int rb = 0; rb < 8; ++rb) { part[rb][0] = __builtin_amdgcn_mfma_f32_16x16x32_bf16(b[0], a[rb], part[rb][0], 0, 0, 0); part[rb][1] = __builtin_amdgcn_mfma_f32_16x16x32_bf16(b[1], a[rb], part[rb][1], 0, 0, 0); }
;     }
.LBB0_1003:
	s_waitcnt lgkmcnt(0)
	s_mov_b32 s1, 0
	s_mov_b32 s0, s26
	v_lshl_add_u64 v[66:67], v[64:65], 0, s[0:1]
	global_load_dwordx4 v[74:77], v[66:67], off
	s_mov_b32 s0, s11
	v_lshl_add_u64 v[68:69], v[148:149], 0, s[0:1]
	global_load_dwordx4 v[78:81], v[68:69], off
	s_mov_b32 s0, s88
	v_lshl_add_u64 v[70:71], v[64:65], 0, s[0:1]
	global_load_dwordx4 v[82:85], v[70:71], off
	s_mov_b32 s0, s12
	v_lshl_add_u64 v[72:73], v[148:149], 0, s[0:1]
	global_load_dwordx4 v[86:89], v[72:73], off
	s_mov_b32 s0, s13
	v_lshl_add_u64 v[66:67], v[148:149], 0, s[0:1]
	global_load_dwordx4 v[90:93], v[66:67], off
	s_mov_b32 s0, s14
	v_lshl_add_u64 v[68:69], v[148:149], 0, s[0:1]
	global_load_dwordx4 v[98:101], v[68:69], off
	s_mov_b32 s0, s15
	v_lshl_add_u64 v[70:71], v[148:149], 0, s[0:1]
	global_load_dwordx4 v[102:105], v[70:71], off
	s_mov_b32 s0, s16
	v_lshl_add_u64 v[72:73], v[148:149], 0, s[0:1]
	global_load_dwordx4 v[106:109], v[72:73], off
	s_mov_b32 s0, s17
	v_lshl_add_u64 v[66:67], v[148:149], 0, s[0:1]
	global_load_dwordx4 v[110:113], v[66:67], off
	s_mov_b32 s0, s35
	v_lshl_add_u64 v[68:69], v[148:149], 0, s[0:1]
	global_load_dwordx4 v[114:117], v[68:69], off
	s_mov_b32 s0, s26
	v_lshl_add_u64 v[70:71], v[64:65], 0, s[0:1]
	global_load_dwordx4 v[118:121], v[70:71], off offset:64
	s_mov_b32 s0, s11
	v_lshl_add_u64 v[72:73], v[148:149], 0, s[0:1]
	global_load_dwordx4 v[122:125], v[72:73], off offset:64
	s_mov_b32 s0, s88
	v_lshl_add_u64 v[66:67], v[64:65], 0, s[0:1]
	global_load_dwordx4 v[126:129], v[66:67], off offset:64
	s_mov_b32 s0, s12
	v_lshl_add_u64 v[68:69], v[148:149], 0, s[0:1]
	global_load_dwordx4 v[130:133], v[68:69], off offset:64
	s_mov_b32 s0, s13
	v_lshl_add_u64 v[70:71], v[148:149], 0, s[0:1]
	global_load_dwordx4 v[134:137], v[70:71], off offset:64
	s_mov_b32 s0, s14
	v_lshl_add_u64 v[72:73], v[148:149], 0, s[0:1]
	global_load_dwordx4 v[150:153], v[72:73], off offset:64
	s_mov_b32 s0, s15
	v_lshl_add_u64 v[66:67], v[148:149], 0, s[0:1]
	global_load_dwordx4 v[168:171], v[66:67], off offset:64
	s_mov_b32 s0, s16
	v_lshl_add_u64 v[68:69], v[148:149], 0, s[0:1]
	global_load_dwordx4 v[172:175], v[68:69], off offset:64
	s_mov_b32 s0, s17
	v_lshl_add_u64 v[70:71], v[148:149], 0, s[0:1]
	global_load_dwordx4 v[176:179], v[70:71], off offset:64
	s_mov_b32 s0, s35
	v_lshl_add_u64 v[72:73], v[148:149], 0, s[0:1]
	global_load_dwordx4 v[180:183], v[72:73], off offset:64
	s_waitcnt vmcnt(10)
	v_mfma_f32_16x16x32_bf16 v[36:39], v[74:77], v[78:81], v[36:39]
	v_mfma_f32_16x16x32_bf16 v[24:27], v[82:85], v[78:81], v[24:27]
	v_mfma_f32_16x16x32_bf16 v[20:23], v[74:77], v[86:89], v[20:23]
	v_mfma_f32_16x16x32_bf16 v[16:19], v[82:85], v[86:89], v[16:19]
	v_mfma_f32_16x16x32_bf16 v[12:15], v[74:77], v[90:93], v[12:15]
	v_mfma_f32_16x16x32_bf16 v[8:11], v[82:85], v[90:93], v[8:11]
	v_mfma_f32_16x16x32_bf16 v[4:7], v[74:77], v[98:101], v[4:7]
	v_mfma_f32_16x16x32_bf16 v[0:3], v[82:85], v[98:101], v[0:3]
	v_mfma_f32_16x16x32_bf16 v[28:31], v[74:77], v[102:105], v[28:31]
	v_mfma_f32_16x16x32_bf16 v[32:35], v[82:85], v[102:105], v[32:35]
	v_mfma_f32_16x16x32_bf16 v[40:43], v[74:77], v[106:109], v[40:43]
	v_mfma_f32_16x16x32_bf16 v[44:47], v[82:85], v[106:109], v[44:47]
	v_mfma_f32_16x16x32_bf16 v[48:51], v[74:77], v[110:113], v[48:51]
	v_mfma_f32_16x16x32_bf16 v[52:55], v[82:85], v[110:113], v[52:55]
	v_mfma_f32_16x16x32_bf16 v[56:59], v[74:77], v[114:117], v[56:59]
	v_mfma_f32_16x16x32_bf16 v[60:63], v[82:85], v[114:117], v[60:63]
	s_mov_b32 s0, s26
	v_lshl_add_u64 v[66:67], v[64:65], 0, s[0:1]
	global_load_dwordx4 v[74:77], v[66:67], off offset:128
	s_mov_b32 s0, s11
	v_lshl_add_u64 v[68:69], v[148:149], 0, s[0:1]
	global_load_dwordx4 v[78:81], v[68:69], off offset:128
	s_mov_b32 s0, s88
	v_lshl_add_u64 v[70:71], v[64:65], 0, s[0:1]
	global_load_dwordx4 v[82:85], v[70:71], off offset:128
	s_mov_b32 s0, s12
	v_lshl_add_u64 v[72:73], v[148:149], 0, s[0:1]
	global_load_dwordx4 v[86:89], v[72:73], off offset:128
	s_mov_b32 s0, s13
	v_lshl_add_u64 v[66:67], v[148:149], 0, s[0:1]
	global_load_dwordx4 v[90:93], v[66:67], off offset:128
	s_mov_b32 s0, s14
	v_lshl_add_u64 v[68:69], v[148:149], 0, s[0:1]
	global_load_dwordx4 v[98:101], v[68:69], off offset:128
	s_mov_b32 s0, s15
	v_lshl_add_u64 v[70:71], v[148:149], 0, s[0:1]
	global_load_dwordx4 v[102:105], v[70:71], off offset:128
	s_mov_b32 s0, s16
	v_lshl_add_u64 v[72:73], v[148:149], 0, s[0:1]
	global_load_dwordx4 v[106:109], v[72:73], off offset:128
	s_mov_b32 s0, s17
	v_lshl_add_u64 v[66:67], v[148:149], 0, s[0:1]
	global_load_dwordx4 v[110:113], v[66:67], off offset:128
	s_mov_b32 s0, s35
	v_lshl_add_u64 v[68:69], v[148:149], 0, s[0:1]
	global_load_dwordx4 v[114:117], v[68:69], off offset:128
	s_waitcnt vmcnt(10)
; #define LAS __attribute__((address_space(3)))
; template <int KSTEPS  >
; __device__ __forceinline__ void small_mma_ksplit(f32x4 (&acc)[2], const bf16_t* A, int lda, const bf16_t* Bt, int ldb, int n0, LAS unsigned char* lds, const SmallId& id) {
;     ...
; #pragma unroll 1
;     for (int ks = 0; ks < KSTEPS; ++ks) {
;         bf16x8 a[8], b[2];
; #pragma unroll
;         for (int rb = 0; rb < 8; ++rb) a[rb] = *(const bf16x8*)(ap + (size_t)(16 * rb) * lda + 32 * ks);
;         b[0] = *(const bf16x8*)(bp + 32 * ks); b[1] = *(const bf16x8*)(bp + (size_t)16 * ldb + 32 * ks);
; #pragma unroll
;         for (int rb = 0; rb < 8; ++rb) { part[rb][0] = __builtin_amdgcn_mfma_f32_16x16x32_bf16(b[0], a[rb], part[rb][0], 0, 0, 0); part[rb][1] = __builtin_amdgcn_mfma_f32_16x16x32_bf16(b[1], a[rb], part[rb][1], 0, 0, 0); }
;     }
;     LAS f32x4* red = (LAS f32x4*)lds;
; #pragma unroll
;     for (int rb = 0; rb < 8; ++rb) { red[((id.w * 8 + rb) * 2 + 0) * 64 + lane] = part[rb][0]; red[((id.w * 8 + rb) * 2 + 1) * 64 + lane] = part[rb][1]; }
;     asm volatile("s_waitcnt lgkmcnt(0)" ::: "memory"); __syncthreads();
; __device__ __forceinline__ void small_up(const Params& p, int l, LAS unsigned char* lds, int G, int bx) {
;     ...
;         const int rb0 = (c0 >> 7) * 256 + (c0 & 127);
;         { f32x4 ag[2], av[2];
;           small_mma_ksplit<4>(ag, XB, DM, Bu, DM, rb0, lds, id);
;           small_mma_ksplit<4>(av, XB, DM, Bu, DM, rb0 + 128, lds, id);
;           acc[0] = ag[0]; acc[1] = ag[1]; acc[2] = av[0]; acc[3] = av[1]; }
	v_mfma_f32_16x16x32_bf16 v[36:39], v[118:121], v[122:125], v[36:39]
	v_mfma_f32_16x16x32_bf16 v[24:27], v[126:129], v[122:125], v[24:27]
	v_mfma_f32_16x16x32_bf16 v[20:23], v[118:121], v[130:133], v[20:23]
	v_mfma_f32_16x16x32_bf16 v[16:19], v[126:129], v[130:133], v[16:19]
	v_mfma_f32_16x16x32_bf16 v[12:15], v[118:121], v[134:137], v[12:15]
	v_mfma_f32_16x16x32_bf16 v[8:11], v[126:129], v[134:137], v[8:11]
	v_mfma_f32_16x16x32_bf16 v[4:7], v[118:121], v[150:153], v[4:7]
	v_mfma_f32_16x16x32_bf16 v[0:3], v[126:129], v[150:153], v[0:3]
	v_mfma_f32_16x16x32_bf16 v[28:31], v[118:121], v[168:171], v[28:31]
	v_mfma_f32_16x16x32_bf16 v[32:35], v[126:129], v[168:171], v[32:35]
	v_mfma_f32_16x16x32_bf16 v[40:43], v[118:121], v[172:175], v[40:43]
	v_mfma_f32_16x16x32_bf16 v[44:47], v[126:129], v[172:175], v[44:47]
	v_mfma_f32_16x16x32_bf16 v[48:51], v[118:121], v[176:179], v[48:51]
	v_mfma_f32_16x16x32_bf16 v[52:55], v[126:129], v[176:179], v[52:55]
	v_mfma_f32_16x16x32_bf16 v[56:59], v[118:121], v[180:183], v[56:59]
	v_mfma_f32_16x16x32_bf16 v[60:63], v[126:129], v[180:183], v[60:63]
	s_mov_b32 s0, s26
	v_lshl_add_u64 v[70:71], v[64:65], 0, s[0:1]
	global_load_dwordx4 v[118:121], v[70:71], off offset:192
	s_mov_b32 s0, s11
	v_lshl_add_u64 v[72:73], v[148:149], 0, s[0:1]
	global_load_dwordx4 v[122:125], v[72:73], off offset:192
	s_mov_b32 s0, s88
	v_lshl_add_u64 v[66:67], v[64:65], 0, s[0:1]
	global_load_dwordx4 v[126:129], v[66:67], off offset:192
	s_mov_b32 s0, s12
	v_lshl_add_u64 v[68:69], v[148:149], 0, s[0:1]
	global_load_dwordx4 v[130:133], v[68:69], off offset:192
	s_mov_b32 s0, s13
	v_lshl_add_u64 v[70:71], v[148:149], 0, s[0:1]
	global_load_dwordx4 v[134:137], v[70:71], off offset:192
	s_mov_b32 s0, s14
	v_lshl_add_u64 v[72:73], v[148:149], 0, s[0:1]
	global_load_dwordx4 v[150:153], v[72:73], off offset:192
	s_mov_b32 s0, s15
	v_lshl_add_u64 v[66:67], v[148:149], 0, s[0:1]
	global_load_dwordx4 v[168:171], v[66:67], off offset:192
	s_mov_b32 s0, s16
	v_lshl_add_u64 v[68:69], v[148:149], 0, s[0:1]
	global_load_dwordx4 v[172:175], v[68:69], off offset:192
	s_mov_b32 s0, s17
	v_lshl_add_u64 v[70:71], v[148:149], 0, s[0:1]
	global_load_dwordx4 v[176:179], v[70:71], off offset:192
	s_mov_b32 s0, s35
	v_lshl_add_u64 v[72:73], v[148:149], 0, s[0:1]
	global_load_dwordx4 v[180:183], v[72:73], off offset:192
	s_waitcnt vmcnt(10)
	v_mfma_f32_16x16x32_bf16 v[36:39], v[74:77], v[78:81], v[36:39]
	v_mfma_f32_16x16x32_bf16 v[24:27], v[82:85], v[78:81], v[24:27]
	v_mfma_f32_16x16x32_bf16 v[20:23], v[74:77], v[86:89], v[20:23]
	v_mfma_f32_16x16x32_bf16 v[16:19], v[82:85], v[86:89], v[16:19]
	v_mfma_f32_16x16x32_bf16 v[12:15], v[74:77], v[90:93], v[12:15]
	v_mfma_f32_16x16x32_bf16 v[8:11], v[82:85], v[90:93], v[8:11]
	v_mfma_f32_16x16x32_bf16 v[4:7], v[74:77], v[98:101], v[4:7]
	v_mfma_f32_16x16x32_bf16 v[0:3], v[82:85], v[98:101], v[0:3]
	v_mfma_f32_16x16x32_bf16 v[28:31], v[74:77], v[102:105], v[28:31]
	v_mfma_f32_16x16x32_bf16 v[32:35], v[82:85], v[102:105], v[32:35]
	v_mfma_f32_16x16x32_bf16 v[40:43], v[74:77], v[106:109], v[40:43]
	v_mfma_f32_16x16x32_bf16 v[44:47], v[82:85], v[106:109], v[44:47]
	v_mfma_f32_16x16x32_bf16 v[48:51], v[74:77], v[110:113], v[48:51]
	v_mfma_f32_16x16x32_bf16 v[52:55], v[82:85], v[110:113], v[52:55]
	v_mfma_f32_16x16x32_bf16 v[56:59], v[74:77], v[114:117], v[56:59]
	v_mfma_f32_16x16x32_bf16 v[60:63], v[82:85], v[114:117], v[60:63]
	s_waitcnt vmcnt(0)
	v_mfma_f32_16x16x32_bf16 v[36:39], v[118:121], v[122:125], v[36:39]
	v_mfma_f32_16x16x32_bf16 v[24:27], v[126:129], v[122:125], v[24:27]
	v_mfma_f32_16x16x32_bf16 v[20:23], v[118:121], v[130:133], v[20:23]
	v_mfma_f32_16x16x32_bf16 v[16:19], v[126:129], v[130:133], v[16:19]
	v_mfma_f32_16x16x32_bf16 v[12:15], v[118:121], v[134:137], v[12:15]
	v_mfma_f32_16x16x32_bf16 v[8:11], v[126:129], v[134:137], v[8:11]
	v_mfma_f32_16x16x32_bf16 v[4:7], v[118:121], v[150:153], v[4:7]
	v_mfma_f32_16x16x32_bf16 v[0:3], v[126:129], v[150:153], v[0:3]
	v_mfma_f32_16x16x32_bf16 v[28:31], v[118:121], v[168:171], v[28:31]
	v_mfma_f32_16x16x32_bf16 v[32:35], v[126:129], v[168:171], v[32:35]
	v_mfma_f32_16x16x32_bf16 v[40:43], v[118:121], v[172:175], v[40:43]
	v_mfma_f32_16x16x32_bf16 v[44:47], v[126:129], v[172:175], v[44:47]
	v_mfma_f32_16x16x32_bf16 v[48:51], v[118:121], v[176:179], v[48:51]
	v_mfma_f32_16x16x32_bf16 v[52:55], v[126:129], v[176:179], v[52:55]
	v_mfma_f32_16x16x32_bf16 v[56:59], v[118:121], v[180:183], v[56:59]
	v_mfma_f32_16x16x32_bf16 v[60:63], v[126:129], v[180:183], v[60:63]
	s_add_i32 s9, s9, s8
	v_add_u32_e32 v64, s9, v96
	v_ashrrev_i32_e32 v65, 31, v64
	v_lshlrev_b64 v[64:65], 11, v[64:65]
	ds_write_b128 v157, v[36:39]
	ds_write_b128 v157, v[24:27] offset:1024
	ds_write_b128 v157, v[20:23] offset:2048
	ds_write_b128 v157, v[16:19] offset:3072
	ds_write_b128 v157, v[12:15] offset:4096
	ds_write_b128 v157, v[8:11] offset:5120
	ds_write_b128 v157, v[4:7] offset:6144
	ds_write_b128 v157, v[0:3] offset:7168
	ds_write_b128 v157, v[28:31] offset:8192
	ds_write_b128 v157, v[32:35] offset:9216
	ds_write_b128 v157, v[40:43] offset:10240
	ds_write_b128 v157, v[44:47] offset:11264
	ds_write_b128 v157, v[48:51] offset:12288
	ds_write_b128 v157, v[52:55] offset:13312
	ds_write_b128 v157, v[56:59] offset:14336
	ds_write_b128 v157, v[60:63] offset:15360
	v_lshl_add_u64 v[130:131], v[146:147], 0, v[64:65]
	s_waitcnt lgkmcnt(0)
	s_waitcnt lgkmcnt(0)
	s_barrier
; #define LAS __attribute__((address_space(3)))
; template <int KSTEPS  >
; __device__ __forceinline__ void small_mma_ksplit(f32x4 (&acc)[2], const bf16_t* A, int lda, const bf16_t* Bt, int ldb, int n0, LAS unsigned char* lds, const SmallId& id) {
;     ...
;     f32x4 part[8][2];
; #pragma unroll
;     for (int rb = 0; rb < 8; ++rb) { part[rb][0] = (f32x4){0.f, 0.f, 0.f, 0.f}; part[rb][1] = part[rb][0]; }
;     const bf16_t* ap = A + (size_t)(MP + id.fr) * lda + k0 + 8 * id.fq;
;     const bf16_t* bp = Bt + (size_t)(n0 + id.fr) * ldb + k0 + 8 * id.fq;
; #pragma unroll 1
;     for (int ks = 0; ks < KSTEPS; ++ks) {
;         bf16x8 a[8], b[2];
; #pragma unroll
;         for (int rb = 0; rb < 8; ++rb) a[rb] = *(const bf16x8*)(ap + (size_t)(16 * rb) * lda + 32 * ks);
;         b[0] = *(const bf16x8*)(bp + 32 * ks); b[1] = *(const bf16x8*)(bp + (size_t)16 * ldb + 32 * ks);
; #pragma unroll
;         for (int rb = 0; rb < 8; ++rb) { part[rb][0] = __builtin_amdgcn_mfma_f32_16x16x32_bf16(b[0], a[rb], part[rb][0], 0, 0, 0); part[rb][1] = __builtin_amdgcn_mfma_f32_16x16x32_bf16(b[1], a[rb], part[rb][1], 0, 0, 0); }
;     }
;     LAS f32x4* red = (LAS f32x4*)lds;
; #pragma unroll
;     for (int rb = 0; rb < 8; ++rb) { red[((id.w * 8 + rb) * 2 + 0) * 64 + lane] = part[rb][0]; red[((id.w * 8 + rb) * 2 + 1) * 64 + lane] = part[rb][1]; }
;     asm volatile("s_waitcnt lgkmcnt(0)" ::: "memory"); __syncthreads();
;     acc[0] = (f32x4){0.f, 0.f, 0.f, 0.f}; acc[1] = acc[0];
; #pragma unroll
;     for (int w2 = 0; w2 < 8; ++w2) { acc[0] += red[((w2 * 8 + id.w) * 2 + 0) * 64 + lane]; acc[1] += red[((w2 * 8 + id.w) * 2 + 1) * 64 + lane]; }
;     asm volatile("s_waitcnt lgkmcnt(0)" ::: "memory"); __syncthreads();
	ds_read_b128 v[92:95], v158
	ds_read_b128 v[28:31], v158 offset:1024
	ds_read_b128 v[88:91], v158 offset:16384
	ds_read_b128 v[24:27], v158 offset:17408
	ds_read_b128 v[84:87], v158 offset:32768
	ds_read_b128 v[20:23], v158 offset:33792
	ds_read_b128 v[80:83], v158 offset:49152
	ds_read_b128 v[16:19], v158 offset:50176
	ds_read_b128 v[76:79], v159
	ds_read_b128 v[12:15], v160
	ds_read_b128 v[72:75], v161
	ds_read_b128 v[8:11], v162
	ds_read_b128 v[68:71], v163
	ds_read_b128 v[4:7], v164
	ds_read_b128 v[64:67], v165
	ds_read_b128 v[0:3], v166
	s_waitcnt lgkmcnt(0)
	v_mov_b32_e32 v32, 0
	s_mov_b64 s[0:1], 0
	v_mov_b32_e32 v33, v32
	v_mov_b32_e32 v34, v32
	v_mov_b32_e32 v35, v32
	v_mov_b32_e32 v36, v32
	v_mov_b32_e32 v37, v32
	v_mov_b32_e32 v38, v32
	v_mov_b32_e32 v39, v32
	v_mov_b32_e32 v40, v32
	v_mov_b32_e32 v41, v32
	v_mov_b32_e32 v42, v32
	v_mov_b32_e32 v43, v32
	v_mov_b32_e32 v44, v32
	v_mov_b32_e32 v45, v32
	v_mov_b32_e32 v46, v32
	v_mov_b32_e32 v47, v32
	v_mov_b32_e32 v48, v32
	v_mov_b32_e32 v49, v32
	v_mov_b32_e32 v50, v32
	v_mov_b32_e32 v51, v32
	v_mov_b32_e32 v52, v32
	v_mov_b32_e32 v53, v32
	v_mov_b32_e32 v54, v32
	v_mov_b32_e32 v55, v32
	v_mov_b32_e32 v56, v32
	v_mov_b32_e32 v57, v32
	v_mov_b32_e32 v58, v32
	v_mov_b32_e32 v59, v32
	v_mov_b32_e32 v102, v32
	v_mov_b32_e32 v103, v32
	v_mov_b32_e32 v104, v32
	v_mov_b32_e32 v105, v32
	v_mov_b32_e32 v60, v32
	v_mov_b32_e32 v61, v32
	v_mov_b32_e32 v62, v32
	v_mov_b32_e32 v63, v32
	v_mov_b32_e32 v98, v32
	v_mov_b32_e32 v99, v32
	v_mov_b32_e32 v100, v32
	v_mov_b32_e32 v101, v32
	v_mov_b32_e32 v106, v32
	v_mov_b32_e32 v107, v32
	v_mov_b32_e32 v108, v32
	v_mov_b32_e32 v109, v32
	v_mov_b32_e32 v110, v32
	v_mov_b32_e32 v111, v32
	v_mov_b32_e32 v112, v32
	v_mov_b32_e32 v113, v32
	v_mov_b32_e32 v114, v32
	v_mov_b32_e32 v115, v32
	v_mov_b32_e32 v116, v32
	v_mov_b32_e32 v117, v32
	v_mov_b32_e32 v118, v32
	v_mov_b32_e32 v119, v32
	v_mov_b32_e32 v120, v32
	v_mov_b32_e32 v121, v32
	v_mov_b32_e32 v122, v32
	v_mov_b32_e32 v123, v32
	v_mov_b32_e32 v124, v32
	v_mov_b32_e32 v125, v32
	v_mov_b32_e32 v126, v32
	v_mov_b32_e32 v127, v32
	v_mov_b32_e32 v128, v32
	v_mov_b32_e32 v129, v32
	s_waitcnt lgkmcnt(0)
	s_barrier
.LBB0_1005:
	s_waitcnt lgkmcnt(0)
	s_mov_b32 s1, 0
	s_mov_b32 s0, s26
	v_lshl_add_u64 v[132:133], v[130:131], 0, s[0:1]
	global_load_dwordx4 v[150:153], v[132:133], off
	s_mov_b32 s0, s11
	v_lshl_add_u64 v[134:135], v[148:149], 0, s[0:1]
	global_load_dwordx4 v[168:171], v[134:135], off
	s_mov_b32 s0, s88
	v_lshl_add_u64 v[136:137], v[130:131], 0, s[0:1]
	global_load_dwordx4 v[172:175], v[136:137], off
	s_mov_b32 s0, s12
	v_lshl_add_u64 v[146:147], v[148:149], 0, s[0:1]
	global_load_dwordx4 v[176:179], v[146:147], off
	s_mov_b32 s0, s13
	v_lshl_add_u64 v[132:133], v[148:149], 0, s[0:1]
	global_load_dwordx4 v[180:183], v[132:133], off
	s_mov_b32 s0, s14
	v_lshl_add_u64 v[134:135], v[148:149], 0, s[0:1]
	global_load_dwordx4 v[184:187], v[134:135], off
	s_mov_b32 s0, s15
	v_lshl_add_u64 v[136:137], v[148:149], 0, s[0:1]
	global_load_dwordx4 v[188:191], v[136:137], off
	s_mov_b32 s0, s16
	v_lshl_add_u64 v[146:147], v[148:149], 0, s[0:1]
	global_load_dwordx4 v[206:209], v[146:147], off
	s_mov_b32 s0, s17
	v_lshl_add_u64 v[132:133], v[148:149], 0, s[0:1]
	global_load_dwordx4 v[210:213], v[132:133], off
	s_mov_b32 s0, s35
	v_lshl_add_u64 v[134:135], v[148:149], 0, s[0:1]
	global_load_dwordx4 v[214:217], v[134:135], off
	s_waitcnt vmcnt(0)
	v_mfma_f32_16x16x32_bf16 v[102:105], v[150:153], v[168:171], v[102:105]
	v_mfma_f32_16x16x32_bf16 v[56:59], v[172:175], v[168:171], v[56:59]
	v_mfma_f32_16x16x32_bf16 v[52:55], v[150:153], v[176:179], v[52:55]
	v_mfma_f32_16x16x32_bf16 v[48:51], v[172:175], v[176:179], v[48:51]
	v_mfma_f32_16x16x32_bf16 v[44:47], v[150:153], v[180:183], v[44:47]
	v_mfma_f32_16x16x32_bf16 v[40:43], v[172:175], v[180:183], v[40:43]
	v_mfma_f32_16x16x32_bf16 v[36:39], v[150:153], v[184:187], v[36:39]
	v_mfma_f32_16x16x32_bf16 v[32:35], v[172:175], v[184:187], v[32:35]
	v_mfma_f32_16x16x32_bf16 v[60:63], v[150:153], v[188:191], v[60:63]
	v_mfma_f32_16x16x32_bf16 v[98:101], v[172:175], v[188:191], v[98:101]
	v_mfma_f32_16x16x32_bf16 v[106:109], v[150:153], v[206:209], v[106:109]
	v_mfma_f32_16x16x32_bf16 v[110:113], v[172:175], v[206:209], v[110:113]
	v_mfma_f32_16x16x32_bf16 v[114:117], v[150:153], v[210:213], v[114:117]
	v_mfma_f32_16x16x32_bf16 v[118:121], v[172:175], v[210:213], v[118:121]
	v_mfma_f32_16x16x32_bf16 v[122:125], v[150:153], v[214:217], v[122:125]
	v_mfma_f32_16x16x32_bf16 v[126:129], v[172:175], v[214:217], v[126:129]
	s_mov_b32 s0, s26
	v_lshl_add_u64 v[136:137], v[130:131], 0, s[0:1]
	global_load_dwordx4 v[150:153], v[136:137], off offset:64
	s_mov_b32 s0, s11
	v_lshl_add_u64 v[146:147], v[148:149], 0, s[0:1]
	global_load_dwordx4 v[168:171], v[146:147], off offset:64
	s_mov_b32 s0, s88
	v_lshl_add_u64 v[132:133], v[130:131], 0, s[0:1]
	global_load_dwordx4 v[172:175], v[132:133], off offset:64
	s_mov_b32 s0, s12
	v_lshl_add_u64 v[134:135], v[148:149], 0, s[0:1]
	global_load_dwordx4 v[176:179], v[134:135], off offset:64
	s_mov_b32 s0, s13
	v_lshl_add_u64 v[136:137], v[148:149], 0, s[0:1]
	global_load_dwordx4 v[180:183], v[136:137], off offset:64
	s_mov_b32 s0, s14
	v_lshl_add_u64 v[146:147], v[148:149], 0, s[0:1]
	global_load_dwordx4 v[184:187], v[146:147], off offset:64
	s_mov_b32 s0, s15
	v_lshl_add_u64 v[132:133], v[148:149], 0, s[0:1]
	global_load_dwordx4 v[188:191], v[132:133], off offset:64
	s_mov_b32 s0, s16
	v_lshl_add_u64 v[134:135], v[148:149], 0, s[0:1]
	global_load_dwordx4 v[206:209], v[134:135], off offset:64
	s_mov_b32 s0, s17
	v_lshl_add_u64 v[136:137], v[148:149], 0, s[0:1]
	global_load_dwordx4 v[210:213], v[136:137], off offset:64
	s_mov_b32 s0, s35
	v_lshl_add_u64 v[146:147], v[148:149], 0, s[0:1]
	global_load_dwordx4 v[214:217], v[146:147], off offset:64
	s_waitcnt vmcnt(0)
; #define LAS __attribute__((address_space(3)))
; template <int KSTEPS  >
; __device__ __forceinline__ void small_mma_ksplit(f32x4 (&acc)[2], const bf16_t* A, int lda, const bf16_t* Bt, int ldb, int n0, LAS unsigned char* lds, const SmallId& id) {
;     ...
;     for (int ks = 0; ks < KSTEPS; ++ks) {
;         bf16x8 a[8], b[2];
; #pragma unroll
;         for (int rb = 0; rb < 8; ++rb) a[rb] = *(const bf16x8*)(ap + (size_t)(16 * rb) * lda + 32 * ks);
;         b[0] = *(const bf16x8*)(bp + 32 * ks); b[1] = *(const bf16x8*)(bp + (size_t)16 * ldb + 32 * ks);
; #pragma unroll
;         for (int rb = 0; rb < 8; ++rb) { part[rb][0] = __builtin_amdgcn_mfma_f32_16x16x32_bf16(b[0], a[rb], part[rb][0], 0, 0, 0); part[rb][1] = __builtin_amdgcn_mfma_f32_16x16x32_bf16(b[1], a[rb], part[rb][1], 0, 0, 0); }
;     }
;     LAS f32x4* red = (LAS f32x4*)lds;
; #pragma unroll
;     for (int rb = 0; rb < 8; ++rb) { red[((id.w * 8 + rb) * 2 + 0) * 64 + lane] = part[rb][0]; red[((id.w * 8 + rb) * 2 + 1) * 64 + lane] = part[rb][1]; }
;     asm volatile("s_waitcnt lgkmcnt(0)" ::: "memory"); __syncthreads();
	v_mfma_f32_16x16x32_bf16 v[102:105], v[150:153], v[168:171], v[102:105]
	v_mfma_f32_16x16x32_bf16 v[56:59], v[172:175], v[168:171], v[56:59]
	v_mfma_f32_16x16x32_bf16 v[52:55], v[150:153], v[176:179], v[52:55]
	v_mfma_f32_16x16x32_bf16 v[48:51], v[172:175], v[176:179], v[48:51]
	v_mfma_f32_16x16x32_bf16 v[44:47], v[150:153], v[180:183], v[44:47]
	v_mfma_f32_16x16x32_bf16 v[40:43], v[172:175], v[180:183], v[40:43]
	v_mfma_f32_16x16x32_bf16 v[36:39], v[150:153], v[184:187], v[36:39]
	v_mfma_f32_16x16x32_bf16 v[32:35], v[172:175], v[184:187], v[32:35]
	v_mfma_f32_16x16x32_bf16 v[60:63], v[150:153], v[188:191], v[60:63]
	v_mfma_f32_16x16x32_bf16 v[98:101], v[172:175], v[188:191], v[98:101]
	v_mfma_f32_16x16x32_bf16 v[106:109], v[150:153], v[206:209], v[106:109]
	v_mfma_f32_16x16x32_bf16 v[110:113], v[172:175], v[206:209], v[110:113]
	v_mfma_f32_16x16x32_bf16 v[114:117], v[150:153], v[210:213], v[114:117]
	v_mfma_f32_16x16x32_bf16 v[118:121], v[172:175], v[210:213], v[118:121]
	v_mfma_f32_16x16x32_bf16 v[122:125], v[150:153], v[214:217], v[122:125]
	v_mfma_f32_16x16x32_bf16 v[126:129], v[172:175], v[214:217], v[126:129]
	s_mov_b32 s0, s26
	v_lshl_add_u64 v[132:133], v[130:131], 0, s[0:1]
	global_load_dwordx4 v[150:153], v[132:133], off offset:128
	s_mov_b32 s0, s11
	v_lshl_add_u64 v[134:135], v[148:149], 0, s[0:1]
	global_load_dwordx4 v[168:171], v[134:135], off offset:128
	s_mov_b32 s0, s88
	v_lshl_add_u64 v[136:137], v[130:131], 0, s[0:1]
	global_load_dwordx4 v[172:175], v[136:137], off offset:128
	s_mov_b32 s0, s12
	v_lshl_add_u64 v[146:147], v[148:149], 0, s[0:1]
	global_load_dwordx4 v[176:179], v[146:147], off offset:128
	s_mov_b32 s0, s13
	v_lshl_add_u64 v[132:133], v[148:149], 0, s[0:1]
	global_load_dwordx4 v[180:183], v[132:133], off offset:128
	s_mov_b32 s0, s14
	v_lshl_add_u64 v[134:135], v[148:149], 0, s[0:1]
	global_load_dwordx4 v[184:187], v[134:135], off offset:128
	s_mov_b32 s0, s15
	v_lshl_add_u64 v[136:137], v[148:149], 0, s[0:1]
	global_load_dwordx4 v[188:191], v[136:137], off offset:128
	s_mov_b32 s0, s16
	v_lshl_add_u64 v[146:147], v[148:149], 0, s[0:1]
	global_load_dwordx4 v[206:209], v[146:147], off offset:128
	s_mov_b32 s0, s17
	v_lshl_add_u64 v[132:133], v[148:149], 0, s[0:1]
	global_load_dwordx4 v[210:213], v[132:133], off offset:128
	s_mov_b32 s0, s35
	v_lshl_add_u64 v[134:135], v[148:149], 0, s[0:1]
	global_load_dwordx4 v[214:217], v[134:135], off offset:128
	s_waitcnt vmcnt(0)
	v_mfma_f32_16x16x32_bf16 v[102:105], v[150:153], v[168:171], v[102:105]
	v_mfma_f32_16x16x32_bf16 v[56:59], v[172:175], v[168:171], v[56:59]
	v_mfma_f32_16x16x32_bf16 v[52:55], v[150:153], v[176:179], v[52:55]
	v_mfma_f32_16x16x32_bf16 v[48:51], v[172:175], v[176:179], v[48:51]
	v_mfma_f32_16x16x32_bf16 v[44:47], v[150:153], v[180:183], v[44:47]
	v_mfma_f32_16x16x32_bf16 v[40:43], v[172:175], v[180:183], v[40:43]
	v_mfma_f32_16x16x32_bf16 v[36:39], v[150:153], v[184:187], v[36:39]
	v_mfma_f32_16x16x32_bf16 v[32:35], v[172:175], v[184:187], v[32:35]
	v_mfma_f32_16x16x32_bf16 v[60:63], v[150:153], v[188:191], v[60:63]
	v_mfma_f32_16x16x32_bf16 v[98:101], v[172:175], v[188:191], v[98:101]
	v_mfma_f32_16x16x32_bf16 v[106:109], v[150:153], v[206:209], v[106:109]
	v_mfma_f32_16x16x32_bf16 v[110:113], v[172:175], v[206:209], v[110:113]
	v_mfma_f32_16x16x32_bf16 v[114:117], v[150:153], v[210:213], v[114:117]
	v_mfma_f32_16x16x32_bf16 v[118:121], v[172:175], v[210:213], v[118:121]
	v_mfma_f32_16x16x32_bf16 v[122:125], v[150:153], v[214:217], v[122:125]
	v_mfma_f32_16x16x32_bf16 v[126:129], v[172:175], v[214:217], v[126:129]
	s_mov_b32 s0, s26
	v_lshl_add_u64 v[136:137], v[130:131], 0, s[0:1]
	global_load_dwordx4 v[150:153], v[136:137], off offset:192
	s_mov_b32 s0, s11
	v_lshl_add_u64 v[146:147], v[148:149], 0, s[0:1]
	global_load_dwordx4 v[168:171], v[146:147], off offset:192
	s_mov_b32 s0, s88
	v_lshl_add_u64 v[132:133], v[130:131], 0, s[0:1]
	global_load_dwordx4 v[172:175], v[132:133], off offset:192
	s_mov_b32 s0, s12
	v_lshl_add_u64 v[134:135], v[148:149], 0, s[0:1]
	global_load_dwordx4 v[176:179], v[134:135], off offset:192
	s_mov_b32 s0, s13
	v_lshl_add_u64 v[136:137], v[148:149], 0, s[0:1]
	global_load_dwordx4 v[180:183], v[136:137], off offset:192
	s_mov_b32 s0, s14
	v_lshl_add_u64 v[146:147], v[148:149], 0, s[0:1]
	global_load_dwordx4 v[184:187], v[146:147], off offset:192
	s_mov_b32 s0, s15
	v_lshl_add_u64 v[132:133], v[148:149], 0, s[0:1]
	global_load_dwordx4 v[188:191], v[132:133], off offset:192
	s_mov_b32 s0, s16
	v_lshl_add_u64 v[134:135], v[148:149], 0, s[0:1]
	global_load_dwordx4 v[206:209], v[134:135], off offset:192
	s_mov_b32 s0, s17
	v_lshl_add_u64 v[136:137], v[148:149], 0, s[0:1]
	global_load_dwordx4 v[210:213], v[136:137], off offset:192
	s_mov_b32 s0, s35
	v_lshl_add_u64 v[146:147], v[148:149], 0, s[0:1]
	global_load_dwordx4 v[214:217], v[146:147], off offset:192
	s_waitcnt vmcnt(0)
	v_mfma_f32_16x16x32_bf16 v[102:105], v[150:153], v[168:171], v[102:105]
	v_mfma_f32_16x16x32_bf16 v[56:59], v[172:175], v[168:171], v[56:59]
	v_mfma_f32_16x16x32_bf16 v[52:55], v[150:153], v[176:179], v[52:55]
	v_mfma_f32_16x16x32_bf16 v[48:51], v[172:175], v[176:179], v[48:51]
	v_mfma_f32_16x16x32_bf16 v[44:47], v[150:153], v[180:183], v[44:47]
	v_mfma_f32_16x16x32_bf16 v[40:43], v[172:175], v[180:183], v[40:43]
	v_mfma_f32_16x16x32_bf16 v[36:39], v[150:153], v[184:187], v[36:39]
	v_mfma_f32_16x16x32_bf16 v[32:35], v[172:175], v[184:187], v[32:35]
	v_mfma_f32_16x16x32_bf16 v[60:63], v[150:153], v[188:191], v[60:63]
	v_mfma_f32_16x16x32_bf16 v[98:101], v[172:175], v[188:191], v[98:101]
	v_mfma_f32_16x16x32_bf16 v[106:109], v[150:153], v[206:209], v[106:109]
	v_mfma_f32_16x16x32_bf16 v[110:113], v[172:175], v[206:209], v[110:113]
	v_mfma_f32_16x16x32_bf16 v[114:117], v[150:153], v[210:213], v[114:117]
	v_mfma_f32_16x16x32_bf16 v[118:121], v[172:175], v[210:213], v[118:121]
	v_mfma_f32_16x16x32_bf16 v[122:125], v[150:153], v[214:217], v[122:125]
	v_mfma_f32_16x16x32_bf16 v[126:129], v[172:175], v[214:217], v[126:129]
	ds_write_b128 v157, v[102:105]
	ds_write_b128 v157, v[56:59] offset:1024
	ds_write_b128 v157, v[52:55] offset:2048
	ds_write_b128 v157, v[48:51] offset:3072
	ds_write_b128 v157, v[44:47] offset:4096
	ds_write_b128 v157, v[40:43] offset:5120
	ds_write_b128 v157, v[36:39] offset:6144
	ds_write_b128 v157, v[32:35] offset:7168
	ds_write_b128 v157, v[60:63] offset:8192
	ds_write_b128 v157, v[98:101] offset:9216
	ds_write_b128 v157, v[106:109] offset:10240
	ds_write_b128 v157, v[110:113] offset:11264
	ds_write_b128 v157, v[114:117] offset:12288
	ds_write_b128 v157, v[118:121] offset:13312
	ds_write_b128 v157, v[122:125] offset:14336
	ds_write_b128 v157, v[126:129] offset:15360
	s_waitcnt lgkmcnt(0)
	s_waitcnt lgkmcnt(0)
	s_barrier
; template <int KSTEPS  >
; __device__ __forceinline__ void small_mma_ksplit(f32x4 (&acc)[2], const bf16_t* A, int lda, const bf16_t* Bt, int ldb, int n0, LAS unsigned char* lds, const SmallId& id) {
;     ...
;     for (int w2 = 0; w2 < 8; ++w2) { acc[0] += red[((w2 * 8 + id.w) * 2 + 0) * 64 + lane]; acc[1] += red[((w2 * 8 + id.w) * 2 + 1) * 64 + lane]; }
;     asm volatile("s_waitcnt lgkmcnt(0)" ::: "memory"); __syncthreads();
; __device__ __forceinline__ void small_up(const Params& p, int l, LAS unsigned char* lds, int G, int bx) {
;     ...
;         const float rs = __builtin_amdgcn_rsqf(ssq[id.row] * (1.0f / 1024.0f) + EPS);
;         const int fr = id.fr;
; #pragma unroll
;         for (int nb = 0; nb < 2; ++nb) {
;             const int colg = c0 + 16 * nb + 4 * id.fq, colv = FF + colg;
;             const f32x4 cg_ = acc[nb] * rs, cv_ = acc[2 + nb] * rs;
;             f32x4 hg = (f32x4){0.f, 0.f, 0.f, 0.f}, hv = hg;
;             if (fr >= 14) { const float* sp = sconv + (size_t)(id.w * 2 + (fr - 14)) * FF2; hg = *(const f32x4*)(sp + colg); hv = *(const f32x4*)(sp + colv); }
	ds_read_b128 v[106:109], v158
	ds_read_b128 v[52:55], v158 offset:1024
	ds_read_b128 v[110:113], v158 offset:16384
	ds_read_b128 v[56:59], v158 offset:17408
	ds_read_b128 v[114:117], v158 offset:32768
	ds_read_b128 v[60:63], v158 offset:33792
	ds_read_b128 v[118:121], v158 offset:49152
	ds_read_b128 v[32:35], v158 offset:50176
	ds_read_b128 v[122:125], v159
	ds_read_b128 v[36:39], v160
	ds_read_b128 v[126:129], v161
	ds_read_b128 v[40:43], v162
	ds_read_b128 v[130:133], v163
	ds_read_b128 v[44:47], v164
	ds_read_b128 v[134:137], v165
	ds_read_b128 v[48:51], v166
	s_waitcnt lgkmcnt(0)
	s_waitcnt lgkmcnt(0)
	s_barrier
	global_load_dword v168, v[138:139], off
	v_lshl_or_b32 v150, s7, 5, v167
	v_add_u32_e32 v154, 0xb00, v150
	v_ashrrev_i32_e32 v155, 31, v154
	s_and_saveexec_b64 s[0:1], s[48:49]
	s_xor_b64 s[0:1], exec, s[0:1]
	s_or_saveexec_b64 s[0:1], s[0:1]
	v_ashrrev_i32_e32 v151, 31, v150
	v_mov_b32_e32 v98, 0
	v_lshl_add_u64 v[152:153], v[150:151], 2, v[140:141]
	v_mov_b32_e32 v99, 0
	v_mov_b32_e32 v100, 0
	v_mov_b32_e32 v101, 0
	v_mov_b32_e32 v102, 0
	v_mov_b32_e32 v103, 0
	v_mov_b32_e32 v104, 0
	v_mov_b32_e32 v105, 0
	s_xor_b64 exec, exec, s[0:1]
	s_cbranch_execz .LBB0_1008
	v_add_co_u32_e32 v98, vcc, 0x2000, v152
	s_nop 1
	v_addc_co_u32_e32 v99, vcc, 0, v153, vcc
	global_load_dwordx4 v[102:105], v[152:153], off
	s_nop 0
	global_load_dwordx4 v[98:101], v[98:99], off offset:3072

; template <int KSTEPS  >
; __device__ __forceinline__ void small_mma_ksplit(f32x4 (&acc)[2], const bf16_t* A, int lda, const bf16_t* Bt, int ldb, int n0, LAS unsigned char* lds, const SmallId& id) {
;     ...
;     const bf16_t* ap = A + (size_t)(MP + id.fr) * lda + k0 + 8 * id.fq;
;     const bf16_t* bp = Bt + (size_t)(n0 + id.fr) * ldb + k0 + 8 * id.fq;
; #pragma unroll 1
;     for (int ks = 0; ks < KSTEPS; ++ks) {
;         bf16x8 a[8], b[2];
; #pragma unroll
;         for (int rb = 0; rb < 8; ++rb) a[rb] = *(const bf16x8*)(ap + (size_t)(16 * rb) * lda + 32 * ks);
;         b[0] = *(const bf16x8*)(bp + 32 * ks); b[1] = *(const bf16x8*)(bp + (size_t)16 * ldb + 32 * ks);
; #pragma unroll
;         for (int rb = 0; rb < 8; ++rb) { part[rb][0] = __builtin_amdgcn_mfma_f32_16x16x32_bf16(b[0], a[rb], part[rb][0], 0, 0, 0); part[rb][1] = __builtin_amdgcn_mfma_f32_16x16x32_bf16(b[1], a[rb], part[rb][1], 0, 0, 0); }
;     }
.LBB0_1223:
	s_waitcnt lgkmcnt(0)
	s_mov_b32 s1, 0
	s_mov_b32 s0, s62
	v_lshl_add_u64 v[68:69], v[72:73], 0, s[0:1]
	global_load_dwordx4 v[92:95], v[68:69], off
	s_mov_b32 s0, s52
	v_lshl_add_u64 v[86:87], v[70:71], 0, s[0:1]
	global_load_dwordx4 v[98:101], v[86:87], off
	s_mov_b32 s0, s63
	v_lshl_add_u64 v[88:89], v[72:73], 0, s[0:1]
	global_load_dwordx4 v[102:105], v[88:89], off
	s_mov_b32 s0, s53
	v_lshl_add_u64 v[90:91], v[70:71], 0, s[0:1]
	global_load_dwordx4 v[106:109], v[90:91], off
	s_mov_b32 s0, s56
	v_lshl_add_u64 v[68:69], v[70:71], 0, s[0:1]
	global_load_dwordx4 v[110:113], v[68:69], off
	s_mov_b32 s0, s57
	v_lshl_add_u64 v[86:87], v[70:71], 0, s[0:1]
	global_load_dwordx4 v[114:117], v[86:87], off
	s_mov_b32 s0, s58
	v_lshl_add_u64 v[88:89], v[70:71], 0, s[0:1]
	global_load_dwordx4 v[118:121], v[88:89], off
	s_mov_b32 s0, s59
	v_lshl_add_u64 v[90:91], v[70:71], 0, s[0:1]
	global_load_dwordx4 v[122:125], v[90:91], off
	s_mov_b32 s0, s60
	v_lshl_add_u64 v[68:69], v[70:71], 0, s[0:1]
	global_load_dwordx4 v[126:129], v[68:69], off
	s_mov_b32 s0, s61
	v_lshl_add_u64 v[86:87], v[70:71], 0, s[0:1]
	global_load_dwordx4 v[130:133], v[86:87], off
	s_mov_b32 s0, s62
	v_lshl_add_u64 v[88:89], v[72:73], 0, s[0:1]
	global_load_dwordx4 v[134:137], v[88:89], off offset:64
	s_mov_b32 s0, s52
	v_lshl_add_u64 v[90:91], v[70:71], 0, s[0:1]
	global_load_dwordx4 v[138:141], v[90:91], off offset:64
	s_mov_b32 s0, s63
	v_lshl_add_u64 v[68:69], v[72:73], 0, s[0:1]
	global_load_dwordx4 v[142:145], v[68:69], off offset:64
	s_mov_b32 s0, s53
	v_lshl_add_u64 v[86:87], v[70:71], 0, s[0:1]
	global_load_dwordx4 v[146:149], v[86:87], off offset:64
	s_mov_b32 s0, s56
	v_lshl_add_u64 v[88:89], v[70:71], 0, s[0:1]
	global_load_dwordx4 v[150:153], v[88:89], off offset:64
	s_mov_b32 s0, s57
	v_lshl_add_u64 v[90:91], v[70:71], 0, s[0:1]
	global_load_dwordx4 v[154:157], v[90:91], off offset:64
	s_mov_b32 s0, s58
	v_lshl_add_u64 v[68:69], v[70:71], 0, s[0:1]
	global_load_dwordx4 v[158:161], v[68:69], off offset:64
	s_mov_b32 s0, s59
	v_lshl_add_u64 v[86:87], v[70:71], 0, s[0:1]
	global_load_dwordx4 v[162:165], v[86:87], off offset:64
	s_mov_b32 s0, s60
	v_lshl_add_u64 v[88:89], v[70:71], 0, s[0:1]
	global_load_dwordx4 v[166:169], v[88:89], off offset:64
	s_mov_b32 s0, s61
	v_lshl_add_u64 v[90:91], v[70:71], 0, s[0:1]
	global_load_dwordx4 v[170:173], v[90:91], off offset:64
	s_mov_b32 s0, s62
	v_lshl_add_u64 v[68:69], v[72:73], 0, s[0:1]
	global_load_dwordx4 v[174:177], v[68:69], off offset:128
	s_mov_b32 s0, s52
	v_lshl_add_u64 v[86:87], v[70:71], 0, s[0:1]
	global_load_dwordx4 v[178:181], v[86:87], off offset:128
	s_mov_b32 s0, s63
	v_lshl_add_u64 v[88:89], v[72:73], 0, s[0:1]
	global_load_dwordx4 v[182:185], v[88:89], off offset:128
	s_mov_b32 s0, s53
	v_lshl_add_u64 v[90:91], v[70:71], 0, s[0:1]
	global_load_dwordx4 v[186:189], v[90:91], off offset:128
	s_mov_b32 s0, s56
	v_lshl_add_u64 v[68:69], v[70:71], 0, s[0:1]
	global_load_dwordx4 v[190:193], v[68:69], off offset:128
	s_mov_b32 s0, s57
	v_lshl_add_u64 v[86:87], v[70:71], 0, s[0:1]
	global_load_dwordx4 v[206:209], v[86:87], off offset:128
	s_mov_b32 s0, s58
	v_lshl_add_u64 v[88:89], v[70:71], 0, s[0:1]
	global_load_dwordx4 v[210:213], v[88:89], off offset:128
	s_mov_b32 s0, s59
	v_lshl_add_u64 v[90:91], v[70:71], 0, s[0:1]
	global_load_dwordx4 v[214:217], v[90:91], off offset:128
	s_mov_b32 s0, s60
	v_lshl_add_u64 v[68:69], v[70:71], 0, s[0:1]
	global_load_dwordx4 v[218:221], v[68:69], off offset:128
	s_mov_b32 s0, s61
	v_lshl_add_u64 v[86:87], v[70:71], 0, s[0:1]
	global_load_dwordx4 v[234:237], v[86:87], off offset:128
	s_waitcnt vmcnt(20)
	v_mfma_f32_16x16x32_bf16 v[36:39], v[92:95], v[98:101], v[36:39]
	v_mfma_f32_16x16x32_bf16 v[24:27], v[102:105], v[98:101], v[24:27]
	v_mfma_f32_16x16x32_bf16 v[20:23], v[92:95], v[106:109], v[20:23]
	v_mfma_f32_16x16x32_bf16 v[16:19], v[102:105], v[106:109], v[16:19]
	v_mfma_f32_16x16x32_bf16 v[12:15], v[92:95], v[110:113], v[12:15]
	v_mfma_f32_16x16x32_bf16 v[8:11], v[102:105], v[110:113], v[8:11]
	v_mfma_f32_16x16x32_bf16 v[4:7], v[92:95], v[114:117], v[4:7]
	v_mfma_f32_16x16x32_bf16 v[0:3], v[102:105], v[114:117], v[0:3]
	v_mfma_f32_16x16x32_bf16 v[28:31], v[92:95], v[118:121], v[28:31]
	v_mfma_f32_16x16x32_bf16 v[32:35], v[102:105], v[118:121], v[32:35]
	v_mfma_f32_16x16x32_bf16 v[40:43], v[92:95], v[122:125], v[40:43]
	v_mfma_f32_16x16x32_bf16 v[44:47], v[102:105], v[122:125], v[44:47]
	v_mfma_f32_16x16x32_bf16 v[48:51], v[92:95], v[126:129], v[48:51]
	v_mfma_f32_16x16x32_bf16 v[52:55], v[102:105], v[126:129], v[52:55]
	v_mfma_f32_16x16x32_bf16 v[56:59], v[92:95], v[130:133], v[56:59]
	v_mfma_f32_16x16x32_bf16 v[60:63], v[102:105], v[130:133], v[60:63]
	s_mov_b32 s0, s62
	v_lshl_add_u64 v[88:89], v[72:73], 0, s[0:1]
	global_load_dwordx4 v[92:95], v[88:89], off offset:192
	s_mov_b32 s0, s52
	v_lshl_add_u64 v[90:91], v[70:71], 0, s[0:1]
	global_load_dwordx4 v[98:101], v[90:91], off offset:192
	s_mov_b32 s0, s63
	v_lshl_add_u64 v[68:69], v[72:73], 0, s[0:1]
	global_load_dwordx4 v[102:105], v[68:69], off offset:192
	s_mov_b32 s0, s53
	v_lshl_add_u64 v[86:87], v[70:71], 0, s[0:1]
	global_load_dwordx4 v[106:109], v[86:87], off offset:192
	s_mov_b32 s0, s56
	v_lshl_add_u64 v[88:89], v[70:71], 0, s[0:1]
	global_load_dwordx4 v[110:113], v[88:89], off offset:192
	s_mov_b32 s0, s57
	v_lshl_add_u64 v[90:91], v[70:71], 0, s[0:1]
	global_load_dwordx4 v[114:117], v[90:91], off offset:192
	s_mov_b32 s0, s58
	v_lshl_add_u64 v[68:69], v[70:71], 0, s[0:1]
	global_load_dwordx4 v[118:121], v[68:69], off offset:192
	s_mov_b32 s0, s59
	v_lshl_add_u64 v[86:87], v[70:71], 0, s[0:1]
	global_load_dwordx4 v[122:125], v[86:87], off offset:192
	s_mov_b32 s0, s60
	v_lshl_add_u64 v[88:89], v[70:71], 0, s[0:1]
	global_load_dwordx4 v[126:129], v[88:89], off offset:192
	s_mov_b32 s0, s61
	v_lshl_add_u64 v[90:91], v[70:71], 0, s[0:1]
	global_load_dwordx4 v[130:133], v[90:91], off offset:192
	s_waitcnt vmcnt(20)
; template <int KSTEPS  >
; __device__ __forceinline__ void small_mma_ksplit(f32x4 (&acc)[2], const bf16_t* A, int lda, const bf16_t* Bt, int ldb, int n0, LAS unsigned char* lds, const SmallId& id) {
;     ...
;     for (int ks = 0; ks < KSTEPS; ++ks) {
;         bf16x8 a[8], b[2];
; #pragma unroll
;         for (int rb = 0; rb < 8; ++rb) a[rb] = *(const bf16x8*)(ap + (size_t)(16 * rb) * lda + 32 * ks);
;         b[0] = *(const bf16x8*)(bp + 32 * ks); b[1] = *(const bf16x8*)(bp + (size_t)16 * ldb + 32 * ks);
; #pragma unroll
;         for (int rb = 0; rb < 8; ++rb) { part[rb][0] = __builtin_amdgcn_mfma_f32_16x16x32_bf16(b[0], a[rb], part[rb][0], 0, 0, 0); part[rb][1] = __builtin_amdgcn_mfma_f32_16x16x32_bf16(b[1], a[rb], part[rb][1], 0, 0, 0); }
	v_mfma_f32_16x16x32_bf16 v[36:39], v[134:137], v[138:141], v[36:39]
	v_mfma_f32_16x16x32_bf16 v[24:27], v[142:145], v[138:141], v[24:27]
	v_mfma_f32_16x16x32_bf16 v[20:23], v[134:137], v[146:149], v[20:23]
	v_mfma_f32_16x16x32_bf16 v[16:19], v[142:145], v[146:149], v[16:19]
	v_mfma_f32_16x16x32_bf16 v[12:15], v[134:137], v[150:153], v[12:15]
	v_mfma_f32_16x16x32_bf16 v[8:11], v[142:145], v[150:153], v[8:11]
	v_mfma_f32_16x16x32_bf16 v[4:7], v[134:137], v[154:157], v[4:7]
	v_mfma_f32_16x16x32_bf16 v[0:3], v[142:145], v[154:157], v[0:3]
	v_mfma_f32_16x16x32_bf16 v[28:31], v[134:137], v[158:161], v[28:31]
	v_mfma_f32_16x16x32_bf16 v[32:35], v[142:145], v[158:161], v[32:35]
	v_mfma_f32_16x16x32_bf16 v[40:43], v[134:137], v[162:165], v[40:43]
	v_mfma_f32_16x16x32_bf16 v[44:47], v[142:145], v[162:165], v[44:47]
	v_mfma_f32_16x16x32_bf16 v[48:51], v[134:137], v[166:169], v[48:51]
	v_mfma_f32_16x16x32_bf16 v[52:55], v[142:145], v[166:169], v[52:55]
	v_mfma_f32_16x16x32_bf16 v[56:59], v[134:137], v[170:173], v[56:59]
	v_mfma_f32_16x16x32_bf16 v[60:63], v[142:145], v[170:173], v[60:63]
	s_mov_b32 s0, s62
	v_lshl_add_u64 v[68:69], v[72:73], 0, s[0:1]
	global_load_dwordx4 v[134:137], v[68:69], off offset:256
	s_mov_b32 s0, s52
	v_lshl_add_u64 v[86:87], v[70:71], 0, s[0:1]
	global_load_dwordx4 v[138:141], v[86:87], off offset:256
	s_mov_b32 s0, s63
	v_lshl_add_u64 v[88:89], v[72:73], 0, s[0:1]
	global_load_dwordx4 v[142:145], v[88:89], off offset:256
	s_mov_b32 s0, s53
	v_lshl_add_u64 v[90:91], v[70:71], 0, s[0:1]
	global_load_dwordx4 v[146:149], v[90:91], off offset:256
	s_mov_b32 s0, s56
	v_lshl_add_u64 v[68:69], v[70:71], 0, s[0:1]
	global_load_dwordx4 v[150:153], v[68:69], off offset:256
	s_mov_b32 s0, s57
	v_lshl_add_u64 v[86:87], v[70:71], 0, s[0:1]
	global_load_dwordx4 v[154:157], v[86:87], off offset:256
	s_mov_b32 s0, s58
	v_lshl_add_u64 v[88:89], v[70:71], 0, s[0:1]
	global_load_dwordx4 v[158:161], v[88:89], off offset:256
	s_mov_b32 s0, s59
	v_lshl_add_u64 v[90:91], v[70:71], 0, s[0:1]
	global_load_dwordx4 v[162:165], v[90:91], off offset:256
	s_mov_b32 s0, s60
	v_lshl_add_u64 v[68:69], v[70:71], 0, s[0:1]
	global_load_dwordx4 v[166:169], v[68:69], off offset:256
	s_mov_b32 s0, s61
	v_lshl_add_u64 v[86:87], v[70:71], 0, s[0:1]
	global_load_dwordx4 v[170:173], v[86:87], off offset:256
	s_waitcnt vmcnt(20)
	v_mfma_f32_16x16x32_bf16 v[36:39], v[174:177], v[178:181], v[36:39]
	v_mfma_f32_16x16x32_bf16 v[24:27], v[182:185], v[178:181], v[24:27]
	v_mfma_f32_16x16x32_bf16 v[20:23], v[174:177], v[186:189], v[20:23]
	v_mfma_f32_16x16x32_bf16 v[16:19], v[182:185], v[186:189], v[16:19]
	v_mfma_f32_16x16x32_bf16 v[12:15], v[174:177], v[190:193], v[12:15]
	v_mfma_f32_16x16x32_bf16 v[8:11], v[182:185], v[190:193], v[8:11]
	v_mfma_f32_16x16x32_bf16 v[4:7], v[174:177], v[206:209], v[4:7]
	v_mfma_f32_16x16x32_bf16 v[0:3], v[182:185], v[206:209], v[0:3]
	v_mfma_f32_16x16x32_bf16 v[28:31], v[174:177], v[210:213], v[28:31]
	v_mfma_f32_16x16x32_bf16 v[32:35], v[182:185], v[210:213], v[32:35]
	v_mfma_f32_16x16x32_bf16 v[40:43], v[174:177], v[214:217], v[40:43]
	v_mfma_f32_16x16x32_bf16 v[44:47], v[182:185], v[214:217], v[44:47]
	v_mfma_f32_16x16x32_bf16 v[48:51], v[174:177], v[218:221], v[48:51]
	v_mfma_f32_16x16x32_bf16 v[52:55], v[182:185], v[218:221], v[52:55]
	v_mfma_f32_16x16x32_bf16 v[56:59], v[174:177], v[234:237], v[56:59]
	v_mfma_f32_16x16x32_bf16 v[60:63], v[182:185], v[234:237], v[60:63]
	s_mov_b32 s0, s62
	v_lshl_add_u64 v[88:89], v[72:73], 0, s[0:1]
	global_load_dwordx4 v[174:177], v[88:89], off offset:320
	s_mov_b32 s0, s52
	v_lshl_add_u64 v[90:91], v[70:71], 0, s[0:1]
	global_load_dwordx4 v[178:181], v[90:91], off offset:320
	s_mov_b32 s0, s63
	v_lshl_add_u64 v[68:69], v[72:73], 0, s[0:1]
	global_load_dwordx4 v[182:185], v[68:69], off offset:320
	s_mov_b32 s0, s53
	v_lshl_add_u64 v[86:87], v[70:71], 0, s[0:1]
	global_load_dwordx4 v[186:189], v[86:87], off offset:320
	s_mov_b32 s0, s56
	v_lshl_add_u64 v[88:89], v[70:71], 0, s[0:1]
	global_load_dwordx4 v[190:193], v[88:89], off offset:320
	s_mov_b32 s0, s57
	v_lshl_add_u64 v[90:91], v[70:71], 0, s[0:1]
	global_load_dwordx4 v[206:209], v[90:91], off offset:320
	s_mov_b32 s0, s58
	v_lshl_add_u64 v[68:69], v[70:71], 0, s[0:1]
	global_load_dwordx4 v[210:213], v[68:69], off offset:320
	s_mov_b32 s0, s59
	v_lshl_add_u64 v[86:87], v[70:71], 0, s[0:1]
	global_load_dwordx4 v[214:217], v[86:87], off offset:320
	s_mov_b32 s0, s60
	v_lshl_add_u64 v[88:89], v[70:71], 0, s[0:1]
	global_load_dwordx4 v[218:221], v[88:89], off offset:320
	s_mov_b32 s0, s61
	v_lshl_add_u64 v[90:91], v[70:71], 0, s[0:1]
	global_load_dwordx4 v[234:237], v[90:91], off offset:320
	s_waitcnt vmcnt(20)
; template <int KSTEPS  >
; __device__ __forceinline__ void small_mma_ksplit(f32x4 (&acc)[2], const bf16_t* A, int lda, const bf16_t* Bt, int ldb, int n0, LAS unsigned char* lds, const SmallId& id) {
;     ...
;     for (int ks = 0; ks < KSTEPS; ++ks) {
;         bf16x8 a[8], b[2];
; #pragma unroll
;         for (int rb = 0; rb < 8; ++rb) a[rb] = *(const bf16x8*)(ap + (size_t)(16 * rb) * lda + 32 * ks);
;         b[0] = *(const bf16x8*)(bp + 32 * ks); b[1] = *(const bf16x8*)(bp + (size_t)16 * ldb + 32 * ks);
; #pragma unroll
;         for (int rb = 0; rb < 8; ++rb) { part[rb][0] = __builtin_amdgcn_mfma_f32_16x16x32_bf16(b[0], a[rb], part[rb][0], 0, 0, 0); part[rb][1] = __builtin_amdgcn_mfma_f32_16x16x32_bf16(b[1], a[rb], part[rb][1], 0, 0, 0); }
	v_mfma_f32_16x16x32_bf16 v[36:39], v[92:95], v[98:101], v[36:39]
	v_mfma_f32_16x16x32_bf16 v[24:27], v[102:105], v[98:101], v[24:27]
	v_mfma_f32_16x16x32_bf16 v[20:23], v[92:95], v[106:109], v[20:23]
	v_mfma_f32_16x16x32_bf16 v[16:19], v[102:105], v[106:109], v[16:19]
	v_mfma_f32_16x16x32_bf16 v[12:15], v[92:95], v[110:113], v[12:15]
	v_mfma_f32_16x16x32_bf16 v[8:11], v[102:105], v[110:113], v[8:11]
	v_mfma_f32_16x16x32_bf16 v[4:7], v[92:95], v[114:117], v[4:7]
	v_mfma_f32_16x16x32_bf16 v[0:3], v[102:105], v[114:117], v[0:3]
	v_mfma_f32_16x16x32_bf16 v[28:31], v[92:95], v[118:121], v[28:31]
	v_mfma_f32_16x16x32_bf16 v[32:35], v[102:105], v[118:121], v[32:35]
	v_mfma_f32_16x16x32_bf16 v[40:43], v[92:95], v[122:125], v[40:43]
	v_mfma_f32_16x16x32_bf16 v[44:47], v[102:105], v[122:125], v[44:47]
	v_mfma_f32_16x16x32_bf16 v[48:51], v[92:95], v[126:129], v[48:51]
	v_mfma_f32_16x16x32_bf16 v[52:55], v[102:105], v[126:129], v[52:55]
	v_mfma_f32_16x16x32_bf16 v[56:59], v[92:95], v[130:133], v[56:59]
	v_mfma_f32_16x16x32_bf16 v[60:63], v[102:105], v[130:133], v[60:63]
	s_mov_b32 s0, s62
	v_lshl_add_u64 v[68:69], v[72:73], 0, s[0:1]
	global_load_dwordx4 v[92:95], v[68:69], off offset:384
	s_mov_b32 s0, s52
	v_lshl_add_u64 v[86:87], v[70:71], 0, s[0:1]
	global_load_dwordx4 v[98:101], v[86:87], off offset:384
	s_mov_b32 s0, s63
	v_lshl_add_u64 v[88:89], v[72:73], 0, s[0:1]
	global_load_dwordx4 v[102:105], v[88:89], off offset:384
	s_mov_b32 s0, s53
	v_lshl_add_u64 v[90:91], v[70:71], 0, s[0:1]
	global_load_dwordx4 v[106:109], v[90:91], off offset:384
	s_mov_b32 s0, s56
	v_lshl_add_u64 v[68:69], v[70:71], 0, s[0:1]
	global_load_dwordx4 v[110:113], v[68:69], off offset:384
	s_mov_b32 s0, s57
	v_lshl_add_u64 v[86:87], v[70:71], 0, s[0:1]
	global_load_dwordx4 v[114:117], v[86:87], off offset:384
	s_mov_b32 s0, s58
	v_lshl_add_u64 v[88:89], v[70:71], 0, s[0:1]
	global_load_dwordx4 v[118:121], v[88:89], off offset:384
	s_mov_b32 s0, s59
	v_lshl_add_u64 v[90:91], v[70:71], 0, s[0:1]
	global_load_dwordx4 v[122:125], v[90:91], off offset:384
	s_mov_b32 s0, s60
	v_lshl_add_u64 v[68:69], v[70:71], 0, s[0:1]
	global_load_dwordx4 v[126:129], v[68:69], off offset:384
	s_mov_b32 s0, s61
	v_lshl_add_u64 v[86:87], v[70:71], 0, s[0:1]
	global_load_dwordx4 v[130:133], v[86:87], off offset:384
	s_waitcnt vmcnt(20)
	v_mfma_f32_16x16x32_bf16 v[36:39], v[134:137], v[138:141], v[36:39]
	v_mfma_f32_16x16x32_bf16 v[24:27], v[142:145], v[138:141], v[24:27]
	v_mfma_f32_16x16x32_bf16 v[20:23], v[134:137], v[146:149], v[20:23]
	v_mfma_f32_16x16x32_bf16 v[16:19], v[142:145], v[146:149], v[16:19]
	v_mfma_f32_16x16x32_bf16 v[12:15], v[134:137], v[150:153], v[12:15]
	v_mfma_f32_16x16x32_bf16 v[8:11], v[142:145], v[150:153], v[8:11]
	v_mfma_f32_16x16x32_bf16 v[4:7], v[134:137], v[154:157], v[4:7]
	v_mfma_f32_16x16x32_bf16 v[0:3], v[142:145], v[154:157], v[0:3]
	v_mfma_f32_16x16x32_bf16 v[28:31], v[134:137], v[158:161], v[28:31]
	v_mfma_f32_16x16x32_bf16 v[32:35], v[142:145], v[158:161], v[32:35]
	v_mfma_f32_16x16x32_bf16 v[40:43], v[134:137], v[162:165], v[40:43]
	v_mfma_f32_16x16x32_bf16 v[44:47], v[142:145], v[162:165], v[44:47]
	v_mfma_f32_16x16x32_bf16 v[48:51], v[134:137], v[166:169], v[48:51]
	v_mfma_f32_16x16x32_bf16 v[52:55], v[142:145], v[166:169], v[52:55]
	v_mfma_f32_16x16x32_bf16 v[56:59], v[134:137], v[170:173], v[56:59]
	v_mfma_f32_16x16x32_bf16 v[60:63], v[142:145], v[170:173], v[60:63]
	s_mov_b32 s0, s62
	v_lshl_add_u64 v[88:89], v[72:73], 0, s[0:1]
	global_load_dwordx4 v[134:137], v[88:89], off offset:448
	s_mov_b32 s0, s52
	v_lshl_add_u64 v[90:91], v[70:71], 0, s[0:1]
	global_load_dwordx4 v[138:141], v[90:91], off offset:448
	s_mov_b32 s0, s63
	v_lshl_add_u64 v[68:69], v[72:73], 0, s[0:1]
	global_load_dwordx4 v[142:145], v[68:69], off offset:448
	s_mov_b32 s0, s53
	v_lshl_add_u64 v[86:87], v[70:71], 0, s[0:1]
	global_load_dwordx4 v[146:149], v[86:87], off offset:448
	s_mov_b32 s0, s56
	v_lshl_add_u64 v[88:89], v[70:71], 0, s[0:1]
	global_load_dwordx4 v[150:153], v[88:89], off offset:448
	s_mov_b32 s0, s57
	v_lshl_add_u64 v[90:91], v[70:71], 0, s[0:1]
	global_load_dwordx4 v[154:157], v[90:91], off offset:448
	s_mov_b32 s0, s58
	v_lshl_add_u64 v[68:69], v[70:71], 0, s[0:1]
	global_load_dwordx4 v[158:161], v[68:69], off offset:448
	s_mov_b32 s0, s59
	v_lshl_add_u64 v[86:87], v[70:71], 0, s[0:1]
	global_load_dwordx4 v[162:165], v[86:87], off offset:448
	s_mov_b32 s0, s60
	v_lshl_add_u64 v[88:89], v[70:71], 0, s[0:1]
	global_load_dwordx4 v[166:169], v[88:89], off offset:448
	s_mov_b32 s0, s61
	v_lshl_add_u64 v[90:91], v[70:71], 0, s[0:1]
	global_load_dwordx4 v[170:173], v[90:91], off offset:448
	s_waitcnt vmcnt(20)
; template <int KSTEPS  >
; __device__ __forceinline__ void small_mma_ksplit(f32x4 (&acc)[2], const bf16_t* A, int lda, const bf16_t* Bt, int ldb, int n0, LAS unsigned char* lds, const SmallId& id) {
;     ...
;     for (int ks = 0; ks < KSTEPS; ++ks) {
;         bf16x8 a[8], b[2];
; #pragma unroll
;         for (int rb = 0; rb < 8; ++rb) a[rb] = *(const bf16x8*)(ap + (size_t)(16 * rb) * lda + 32 * ks);
;         b[0] = *(const bf16x8*)(bp + 32 * ks); b[1] = *(const bf16x8*)(bp + (size_t)16 * ldb + 32 * ks);
; #pragma unroll
;         for (int rb = 0; rb < 8; ++rb) { part[rb][0] = __builtin_amdgcn_mfma_f32_16x16x32_bf16(b[0], a[rb], part[rb][0], 0, 0, 0); part[rb][1] = __builtin_amdgcn_mfma_f32_16x16x32_bf16(b[1], a[rb], part[rb][1], 0, 0, 0); }
	v_mfma_f32_16x16x32_bf16 v[36:39], v[174:177], v[178:181], v[36:39]
	v_mfma_f32_16x16x32_bf16 v[24:27], v[182:185], v[178:181], v[24:27]
	v_mfma_f32_16x16x32_bf16 v[20:23], v[174:177], v[186:189], v[20:23]
	v_mfma_f32_16x16x32_bf16 v[16:19], v[182:185], v[186:189], v[16:19]
	v_mfma_f32_16x16x32_bf16 v[12:15], v[174:177], v[190:193], v[12:15]
	v_mfma_f32_16x16x32_bf16 v[8:11], v[182:185], v[190:193], v[8:11]
	v_mfma_f32_16x16x32_bf16 v[4:7], v[174:177], v[206:209], v[4:7]
	v_mfma_f32_16x16x32_bf16 v[0:3], v[182:185], v[206:209], v[0:3]
	v_mfma_f32_16x16x32_bf16 v[28:31], v[174:177], v[210:213], v[28:31]
	v_mfma_f32_16x16x32_bf16 v[32:35], v[182:185], v[210:213], v[32:35]
	v_mfma_f32_16x16x32_bf16 v[40:43], v[174:177], v[214:217], v[40:43]
	v_mfma_f32_16x16x32_bf16 v[44:47], v[182:185], v[214:217], v[44:47]
	v_mfma_f32_16x16x32_bf16 v[48:51], v[174:177], v[218:221], v[48:51]
	v_mfma_f32_16x16x32_bf16 v[52:55], v[182:185], v[218:221], v[52:55]
	v_mfma_f32_16x16x32_bf16 v[56:59], v[174:177], v[234:237], v[56:59]
	v_mfma_f32_16x16x32_bf16 v[60:63], v[182:185], v[234:237], v[60:63]
	s_mov_b32 s0, s62
	v_lshl_add_u64 v[68:69], v[72:73], 0, s[0:1]
	global_load_dwordx4 v[174:177], v[68:69], off offset:512
	s_mov_b32 s0, s52
	v_lshl_add_u64 v[86:87], v[70:71], 0, s[0:1]
	global_load_dwordx4 v[178:181], v[86:87], off offset:512
	s_mov_b32 s0, s63
	v_lshl_add_u64 v[88:89], v[72:73], 0, s[0:1]
	global_load_dwordx4 v[182:185], v[88:89], off offset:512
	s_mov_b32 s0, s53
	v_lshl_add_u64 v[90:91], v[70:71], 0, s[0:1]
	global_load_dwordx4 v[186:189], v[90:91], off offset:512
	s_mov_b32 s0, s56
	v_lshl_add_u64 v[68:69], v[70:71], 0, s[0:1]
	global_load_dwordx4 v[190:193], v[68:69], off offset:512
	s_mov_b32 s0, s57
	v_lshl_add_u64 v[86:87], v[70:71], 0, s[0:1]
	global_load_dwordx4 v[206:209], v[86:87], off offset:512
	s_mov_b32 s0, s58
	v_lshl_add_u64 v[88:89], v[70:71], 0, s[0:1]
	global_load_dwordx4 v[210:213], v[88:89], off offset:512
	s_mov_b32 s0, s59
	v_lshl_add_u64 v[90:91], v[70:71], 0, s[0:1]
	global_load_dwordx4 v[214:217], v[90:91], off offset:512
	s_mov_b32 s0, s60
	v_lshl_add_u64 v[68:69], v[70:71], 0, s[0:1]
	global_load_dwordx4 v[218:221], v[68:69], off offset:512
	s_mov_b32 s0, s61
	v_lshl_add_u64 v[86:87], v[70:71], 0, s[0:1]
	global_load_dwordx4 v[234:237], v[86:87], off offset:512
	s_waitcnt vmcnt(20)
	v_mfma_f32_16x16x32_bf16 v[36:39], v[92:95], v[98:101], v[36:39]
	v_mfma_f32_16x16x32_bf16 v[24:27], v[102:105], v[98:101], v[24:27]
	v_mfma_f32_16x16x32_bf16 v[20:23], v[92:95], v[106:109], v[20:23]
	v_mfma_f32_16x16x32_bf16 v[16:19], v[102:105], v[106:109], v[16:19]
	v_mfma_f32_16x16x32_bf16 v[12:15], v[92:95], v[110:113], v[12:15]
	v_mfma_f32_16x16x32_bf16 v[8:11], v[102:105], v[110:113], v[8:11]
	v_mfma_f32_16x16x32_bf16 v[4:7], v[92:95], v[114:117], v[4:7]
	v_mfma_f32_16x16x32_bf16 v[0:3], v[102:105], v[114:117], v[0:3]
	v_mfma_f32_16x16x32_bf16 v[28:31], v[92:95], v[118:121], v[28:31]
	v_mfma_f32_16x16x32_bf16 v[32:35], v[102:105], v[118:121], v[32:35]
	v_mfma_f32_16x16x32_bf16 v[40:43], v[92:95], v[122:125], v[40:43]
	v_mfma_f32_16x16x32_bf16 v[44:47], v[102:105], v[122:125], v[44:47]
	v_mfma_f32_16x16x32_bf16 v[48:51], v[92:95], v[126:129], v[48:51]
	v_mfma_f32_16x16x32_bf16 v[52:55], v[102:105], v[126:129], v[52:55]
	v_mfma_f32_16x16x32_bf16 v[56:59], v[92:95], v[130:133], v[56:59]
	v_mfma_f32_16x16x32_bf16 v[60:63], v[102:105], v[130:133], v[60:63]
	s_mov_b32 s0, s62
	v_lshl_add_u64 v[88:89], v[72:73], 0, s[0:1]
	global_load_dwordx4 v[92:95], v[88:89], off offset:576
	s_mov_b32 s0, s52
	v_lshl_add_u64 v[90:91], v[70:71], 0, s[0:1]
	global_load_dwordx4 v[98:101], v[90:91], off offset:576
	s_mov_b32 s0, s63
	v_lshl_add_u64 v[68:69], v[72:73], 0, s[0:1]
	global_load_dwordx4 v[102:105], v[68:69], off offset:576
	s_mov_b32 s0, s53
	v_lshl_add_u64 v[86:87], v[70:71], 0, s[0:1]
	global_load_dwordx4 v[106:109], v[86:87], off offset:576
	s_mov_b32 s0, s56
	v_lshl_add_u64 v[88:89], v[70:71], 0, s[0:1]
	global_load_dwordx4 v[110:113], v[88:89], off offset:576
	s_mov_b32 s0, s57
	v_lshl_add_u64 v[90:91], v[70:71], 0, s[0:1]
	global_load_dwordx4 v[114:117], v[90:91], off offset:576
	s_mov_b32 s0, s58
	v_lshl_add_u64 v[68:69], v[70:71], 0, s[0:1]
	global_load_dwordx4 v[118:121], v[68:69], off offset:576
	s_mov_b32 s0, s59
	v_lshl_add_u64 v[86:87], v[70:71], 0, s[0:1]
	global_load_dwordx4 v[122:125], v[86:87], off offset:576
	s_mov_b32 s0, s60
	v_lshl_add_u64 v[88:89], v[70:71], 0, s[0:1]
	global_load_dwordx4 v[126:129], v[88:89], off offset:576
	s_mov_b32 s0, s61
	v_lshl_add_u64 v[90:91], v[70:71], 0, s[0:1]
	global_load_dwordx4 v[130:133], v[90:91], off offset:576
	s_waitcnt vmcnt(20)
; #define LAS __attribute__((address_space(3)))
; template <int KSTEPS  >
; __device__ __forceinline__ void small_mma_ksplit(f32x4 (&acc)[2], const bf16_t* A, int lda, const bf16_t* Bt, int ldb, int n0, LAS unsigned char* lds, const SmallId& id) {
;     ...
;     for (int ks = 0; ks < KSTEPS; ++ks) {
;         bf16x8 a[8], b[2];
; #pragma unroll
;         for (int rb = 0; rb < 8; ++rb) a[rb] = *(const bf16x8*)(ap + (size_t)(16 * rb) * lda + 32 * ks);
;         b[0] = *(const bf16x8*)(bp + 32 * ks); b[1] = *(const bf16x8*)(bp + (size_t)16 * ldb + 32 * ks);
; #pragma unroll
;         for (int rb = 0; rb < 8; ++rb) { part[rb][0] = __builtin_amdgcn_mfma_f32_16x16x32_bf16(b[0], a[rb], part[rb][0], 0, 0, 0); part[rb][1] = __builtin_amdgcn_mfma_f32_16x16x32_bf16(b[1], a[rb], part[rb][1], 0, 0, 0); }
;     }
;     LAS f32x4* red = (LAS f32x4*)lds;
; #pragma unroll
;     for (int rb = 0; rb < 8; ++rb) { red[((id.w * 8 + rb) * 2 + 0) * 64 + lane] = part[rb][0]; red[((id.w * 8 + rb) * 2 + 1) * 64 + lane] = part[rb][1]; }
;     asm volatile("s_waitcnt lgkmcnt(0)" ::: "memory"); __syncthreads();
	v_mfma_f32_16x16x32_bf16 v[36:39], v[134:137], v[138:141], v[36:39]
	v_mfma_f32_16x16x32_bf16 v[24:27], v[142:145], v[138:141], v[24:27]
	v_mfma_f32_16x16x32_bf16 v[20:23], v[134:137], v[146:149], v[20:23]
	v_mfma_f32_16x16x32_bf16 v[16:19], v[142:145], v[146:149], v[16:19]
	v_mfma_f32_16x16x32_bf16 v[12:15], v[134:137], v[150:153], v[12:15]
	v_mfma_f32_16x16x32_bf16 v[8:11], v[142:145], v[150:153], v[8:11]
	v_mfma_f32_16x16x32_bf16 v[4:7], v[134:137], v[154:157], v[4:7]
	v_mfma_f32_16x16x32_bf16 v[0:3], v[142:145], v[154:157], v[0:3]
	v_mfma_f32_16x16x32_bf16 v[28:31], v[134:137], v[158:161], v[28:31]
	v_mfma_f32_16x16x32_bf16 v[32:35], v[142:145], v[158:161], v[32:35]
	v_mfma_f32_16x16x32_bf16 v[40:43], v[134:137], v[162:165], v[40:43]
	v_mfma_f32_16x16x32_bf16 v[44:47], v[142:145], v[162:165], v[44:47]
	v_mfma_f32_16x16x32_bf16 v[48:51], v[134:137], v[166:169], v[48:51]
	v_mfma_f32_16x16x32_bf16 v[52:55], v[142:145], v[166:169], v[52:55]
	v_mfma_f32_16x16x32_bf16 v[56:59], v[134:137], v[170:173], v[56:59]
	v_mfma_f32_16x16x32_bf16 v[60:63], v[142:145], v[170:173], v[60:63]
	s_mov_b32 s0, s62
	v_lshl_add_u64 v[68:69], v[72:73], 0, s[0:1]
	global_load_dwordx4 v[134:137], v[68:69], off offset:640
	s_mov_b32 s0, s52
	v_lshl_add_u64 v[86:87], v[70:71], 0, s[0:1]
	global_load_dwordx4 v[138:141], v[86:87], off offset:640
	s_mov_b32 s0, s63
	v_lshl_add_u64 v[88:89], v[72:73], 0, s[0:1]
	global_load_dwordx4 v[142:145], v[88:89], off offset:640
	s_mov_b32 s0, s53
	v_lshl_add_u64 v[90:91], v[70:71], 0, s[0:1]
	global_load_dwordx4 v[146:149], v[90:91], off offset:640
	s_mov_b32 s0, s56
	v_lshl_add_u64 v[68:69], v[70:71], 0, s[0:1]
	global_load_dwordx4 v[150:153], v[68:69], off offset:640
	s_mov_b32 s0, s57
	v_lshl_add_u64 v[86:87], v[70:71], 0, s[0:1]
	global_load_dwordx4 v[154:157], v[86:87], off offset:640
	s_mov_b32 s0, s58
	v_lshl_add_u64 v[88:89], v[70:71], 0, s[0:1]
	global_load_dwordx4 v[158:161], v[88:89], off offset:640
	s_mov_b32 s0, s59
	v_lshl_add_u64 v[90:91], v[70:71], 0, s[0:1]
	global_load_dwordx4 v[162:165], v[90:91], off offset:640
	s_mov_b32 s0, s60
	v_lshl_add_u64 v[68:69], v[70:71], 0, s[0:1]
	global_load_dwordx4 v[166:169], v[68:69], off offset:640
	s_mov_b32 s0, s61
	v_lshl_add_u64 v[86:87], v[70:71], 0, s[0:1]
	global_load_dwordx4 v[170:173], v[86:87], off offset:640
	s_waitcnt vmcnt(20)
	v_mfma_f32_16x16x32_bf16 v[36:39], v[174:177], v[178:181], v[36:39]
	v_mfma_f32_16x16x32_bf16 v[24:27], v[182:185], v[178:181], v[24:27]
	v_mfma_f32_16x16x32_bf16 v[20:23], v[174:177], v[186:189], v[20:23]
	v_mfma_f32_16x16x32_bf16 v[16:19], v[182:185], v[186:189], v[16:19]
	v_mfma_f32_16x16x32_bf16 v[12:15], v[174:177], v[190:193], v[12:15]
	v_mfma_f32_16x16x32_bf16 v[8:11], v[182:185], v[190:193], v[8:11]
	v_mfma_f32_16x16x32_bf16 v[4:7], v[174:177], v[206:209], v[4:7]
	v_mfma_f32_16x16x32_bf16 v[0:3], v[182:185], v[206:209], v[0:3]
	v_mfma_f32_16x16x32_bf16 v[28:31], v[174:177], v[210:213], v[28:31]
	v_mfma_f32_16x16x32_bf16 v[32:35], v[182:185], v[210:213], v[32:35]
	v_mfma_f32_16x16x32_bf16 v[40:43], v[174:177], v[214:217], v[40:43]
	v_mfma_f32_16x16x32_bf16 v[44:47], v[182:185], v[214:217], v[44:47]
	v_mfma_f32_16x16x32_bf16 v[48:51], v[174:177], v[218:221], v[48:51]
	v_mfma_f32_16x16x32_bf16 v[52:55], v[182:185], v[218:221], v[52:55]
	v_mfma_f32_16x16x32_bf16 v[56:59], v[174:177], v[234:237], v[56:59]
	v_mfma_f32_16x16x32_bf16 v[60:63], v[182:185], v[234:237], v[60:63]
	s_waitcnt vmcnt(10)
	v_mfma_f32_16x16x32_bf16 v[36:39], v[92:95], v[98:101], v[36:39]
	v_mfma_f32_16x16x32_bf16 v[24:27], v[102:105], v[98:101], v[24:27]
	v_mfma_f32_16x16x32_bf16 v[20:23], v[92:95], v[106:109], v[20:23]
	v_mfma_f32_16x16x32_bf16 v[16:19], v[102:105], v[106:109], v[16:19]
	v_mfma_f32_16x16x32_bf16 v[12:15], v[92:95], v[110:113], v[12:15]
	v_mfma_f32_16x16x32_bf16 v[8:11], v[102:105], v[110:113], v[8:11]
	v_mfma_f32_16x16x32_bf16 v[4:7], v[92:95], v[114:117], v[4:7]
	v_mfma_f32_16x16x32_bf16 v[0:3], v[102:105], v[114:117], v[0:3]
	v_mfma_f32_16x16x32_bf16 v[28:31], v[92:95], v[118:121], v[28:31]
	v_mfma_f32_16x16x32_bf16 v[32:35], v[102:105], v[118:121], v[32:35]
	v_mfma_f32_16x16x32_bf16 v[40:43], v[92:95], v[122:125], v[40:43]
	v_mfma_f32_16x16x32_bf16 v[44:47], v[102:105], v[122:125], v[44:47]
	v_mfma_f32_16x16x32_bf16 v[48:51], v[92:95], v[126:129], v[48:51]
	v_mfma_f32_16x16x32_bf16 v[52:55], v[102:105], v[126:129], v[52:55]
	v_mfma_f32_16x16x32_bf16 v[56:59], v[92:95], v[130:133], v[56:59]
	v_mfma_f32_16x16x32_bf16 v[60:63], v[102:105], v[130:133], v[60:63]
	s_waitcnt vmcnt(0)
	v_mfma_f32_16x16x32_bf16 v[36:39], v[134:137], v[138:141], v[36:39]
	v_mfma_f32_16x16x32_bf16 v[24:27], v[142:145], v[138:141], v[24:27]
	v_mfma_f32_16x16x32_bf16 v[20:23], v[134:137], v[146:149], v[20:23]
	v_mfma_f32_16x16x32_bf16 v[16:19], v[142:145], v[146:149], v[16:19]
	v_mfma_f32_16x16x32_bf16 v[12:15], v[134:137], v[150:153], v[12:15]
	v_mfma_f32_16x16x32_bf16 v[8:11], v[142:145], v[150:153], v[8:11]
	v_mfma_f32_16x16x32_bf16 v[4:7], v[134:137], v[154:157], v[4:7]
	v_mfma_f32_16x16x32_bf16 v[0:3], v[142:145], v[154:157], v[0:3]
	v_mfma_f32_16x16x32_bf16 v[28:31], v[134:137], v[158:161], v[28:31]
	v_mfma_f32_16x16x32_bf16 v[32:35], v[142:145], v[158:161], v[32:35]
	v_mfma_f32_16x16x32_bf16 v[40:43], v[134:137], v[162:165], v[40:43]
	v_mfma_f32_16x16x32_bf16 v[44:47], v[142:145], v[162:165], v[44:47]
	v_mfma_f32_16x16x32_bf16 v[48:51], v[134:137], v[166:169], v[48:51]
	v_mfma_f32_16x16x32_bf16 v[52:55], v[142:145], v[166:169], v[52:55]
	v_mfma_f32_16x16x32_bf16 v[56:59], v[134:137], v[170:173], v[56:59]
	v_mfma_f32_16x16x32_bf16 v[60:63], v[142:145], v[170:173], v[60:63]
	ds_write_b128 v74, v[36:39]
	ds_write_b128 v74, v[24:27] offset:1024
	ds_write_b128 v74, v[20:23] offset:2048
	ds_write_b128 v74, v[16:19] offset:3072
	ds_write_b128 v74, v[12:15] offset:4096
	ds_write_b128 v74, v[8:11] offset:5120
	ds_write_b128 v74, v[4:7] offset:6144
	ds_write_b128 v74, v[0:3] offset:7168
	ds_write_b128 v74, v[28:31] offset:8192
	ds_write_b128 v74, v[32:35] offset:9216
	ds_write_b128 v74, v[40:43] offset:10240
	ds_write_b128 v74, v[44:47] offset:11264
	ds_write_b128 v74, v[48:51] offset:12288
	ds_write_b128 v74, v[52:55] offset:13312
	ds_write_b128 v74, v[56:59] offset:14336
	ds_write_b128 v74, v[60:63] offset:15360
	s_waitcnt lgkmcnt(0)
	s_waitcnt lgkmcnt(0)
	s_barrier
; __device__ __forceinline__ unsigned cvt_pk_bf16(float lo, float hi) { unsigned r; asm volatile("v_cvt_pk_bf16_f32 %0, %1, %2" : "=v"(r) : "v"(lo), "v"(hi)); return r; }
; template <int KSTEPS  >
; __device__ __forceinline__ void small_mma_ksplit(f32x4 (&acc)[2], const bf16_t* A, int lda, const bf16_t* Bt, int ldb, int n0, LAS unsigned char* lds, const SmallId& id) {
;     ...
;     acc[0] = (f32x4){0.f, 0.f, 0.f, 0.f}; acc[1] = acc[0];
; #pragma unroll
;     for (int w2 = 0; w2 < 8; ++w2) { acc[0] += red[((w2 * 8 + id.w) * 2 + 0) * 64 + lane]; acc[1] += red[((w2 * 8 + id.w) * 2 + 1) * 64 + lane]; }
;     asm volatile("s_waitcnt lgkmcnt(0)" ::: "memory"); __syncthreads();
; template <bool RES_F32, bool OUT_F32, int KSTEPS>
; __device__ __forceinline__ void small_res(const Params& p, LAS unsigned char* lds, const bf16_t* A, int lda, const bf16_t* Bt, int K, float* ssq_next, int G, int bx) {
;     ...
;         float s = 0.f;
; #pragma unroll
;         for (int nb = 0; nb < 2; ++nb) { const int col = n0 + 16 * nb + 4 * id.fq;
;             f32x4 r;
;             if (RES_F32) r = *(const f32x4*)(p.xs + (size_t)(id.row - MP) * DM + col);
;             else { const u32x2 w = *(const u32x2*)(XB + (size_t)id.row * DM + col); r = (f32x4){bf_lo(w.x), bf_hi(w.x), bf_lo(w.y), bf_hi(w.y)}; }
;             const f32x4 x = r + acc[nb];
;             if (OUT_F32) *(f32x4*)(p.out + (size_t)id.row * DM + col) = x;
;             else { u32x2 w; w.x = cvt_pk_bf16(x[0], x[1]); w.y = cvt_pk_bf16(x[2], x[3]); *(u32x2*)(XB + (size_t)id.row * DM + col) = w; }
;             s += (x[0] * x[0] + x[1] * x[1]) + (x[2] * x[2] + x[3] * x[3]); }
;         if (!OUT_F32) { s += __shfl_xor(s, 16); s += __shfl_xor(s, 32); if (id.fq == 0) atomicAdd(ssq_next + id.row, s); }
;     }
	ds_read_b128 v[0:3], v75
	v_lshl_or_b32 v12, s2, 5, v84
	v_ashrrev_i32_e32 v13, 31, v12
	v_lshl_add_u64 v[14:15], v[12:13], 1, v[64:65]
	s_add_i32 s2, s2, s92
	s_waitcnt lgkmcnt(0)
	v_pk_add_f32 v[4:5], v[2:3], 0 op_sel_hi:[1,0]
	v_pk_add_f32 v[6:7], v[0:1], 0 op_sel_hi:[1,0]
	ds_read_b128 v[0:3], v75 offset:1024
	v_add_u32_e32 v85, s37, v85
	s_cmp_lt_i32 s2, 32
	s_waitcnt lgkmcnt(0)
	v_pk_add_f32 v[8:9], v[2:3], 0 op_sel_hi:[1,0]
	v_pk_add_f32 v[10:11], v[0:1], 0 op_sel_hi:[1,0]
	ds_read_b128 v[0:3], v75 offset:16384
	s_waitcnt lgkmcnt(0)
	v_pk_add_f32 v[4:5], v[4:5], v[2:3]
	v_pk_add_f32 v[6:7], v[6:7], v[0:1]
	ds_read_b128 v[0:3], v75 offset:17408
	s_waitcnt lgkmcnt(0)
	v_pk_add_f32 v[8:9], v[8:9], v[2:3]
	v_pk_add_f32 v[10:11], v[10:11], v[0:1]
	ds_read_b128 v[0:3], v75 offset:32768
	s_waitcnt lgkmcnt(0)
	v_pk_add_f32 v[4:5], v[4:5], v[2:3]
	v_pk_add_f32 v[6:7], v[6:7], v[0:1]
	ds_read_b128 v[0:3], v75 offset:33792
	s_waitcnt lgkmcnt(0)
	v_pk_add_f32 v[8:9], v[8:9], v[2:3]
	v_pk_add_f32 v[10:11], v[10:11], v[0:1]
	ds_read_b128 v[0:3], v75 offset:49152
	s_waitcnt lgkmcnt(0)
	v_pk_add_f32 v[4:5], v[4:5], v[2:3]
	v_pk_add_f32 v[6:7], v[6:7], v[0:1]
	ds_read_b128 v[0:3], v75 offset:50176
	s_waitcnt lgkmcnt(0)
	v_pk_add_f32 v[8:9], v[8:9], v[2:3]
	v_pk_add_f32 v[10:11], v[10:11], v[0:1]
	ds_read_b128 v[0:3], v76
	s_waitcnt lgkmcnt(0)
	v_pk_add_f32 v[4:5], v[4:5], v[2:3]
	v_pk_add_f32 v[6:7], v[6:7], v[0:1]
	ds_read_b128 v[0:3], v77
	s_waitcnt lgkmcnt(0)
	v_pk_add_f32 v[8:9], v[8:9], v[2:3]
	v_pk_add_f32 v[10:11], v[10:11], v[0:1]
	ds_read_b128 v[0:3], v78
	s_waitcnt lgkmcnt(0)
	v_pk_add_f32 v[4:5], v[4:5], v[2:3]
	v_pk_add_f32 v[6:7], v[6:7], v[0:1]
	ds_read_b128 v[0:3], v79
	s_waitcnt lgkmcnt(0)
	v_pk_add_f32 v[8:9], v[8:9], v[2:3]
	v_pk_add_f32 v[10:11], v[10:11], v[0:1]
	ds_read_b128 v[0:3], v80
	s_waitcnt lgkmcnt(0)
	v_pk_add_f32 v[4:5], v[4:5], v[2:3]
	v_pk_add_f32 v[6:7], v[6:7], v[0:1]
	ds_read_b128 v[0:3], v81
	s_waitcnt lgkmcnt(0)
	v_pk_add_f32 v[8:9], v[8:9], v[2:3]
	v_pk_add_f32 v[10:11], v[10:11], v[0:1]
	ds_read_b128 v[0:3], v82
	s_waitcnt lgkmcnt(0)
	v_pk_add_f32 v[4:5], v[4:5], v[2:3]
	v_pk_add_f32 v[6:7], v[6:7], v[0:1]
	ds_read_b128 v[0:3], v83
	s_waitcnt lgkmcnt(0)
	s_waitcnt lgkmcnt(0)
	s_barrier
	v_pk_add_f32 v[10:11], v[10:11], v[0:1]
	global_load_dwordx2 v[0:1], v[14:15], off
	v_pk_add_f32 v[8:9], v[8:9], v[2:3]
	s_waitcnt vmcnt(0) lgkmcnt(0)
	v_lshlrev_b32_e32 v2, 16, v0
	v_and_b32_e32 v3, 0xffff0000, v0
	v_lshlrev_b32_e32 v16, 16, v1
	v_and_b32_e32 v17, 0xffff0000, v1
	v_pk_add_f32 v[0:1], v[6:7], v[2:3]
	v_pk_add_f32 v[2:3], v[4:5], v[16:17]
	v_lshl_add_u64 v[4:5], v[12:13], 2, v[66:67]
	global_store_dwordx4 v[4:5], v[0:3], off
	global_load_dwordx2 v[0:1], v[14:15], off offset:32
	s_waitcnt vmcnt(0) lgkmcnt(0)
	v_lshlrev_b32_e32 v6, 16, v0
	v_and_b32_e32 v7, 0xffff0000, v0
	v_lshlrev_b32_e32 v0, 16, v1
	v_and_b32_e32 v1, 0xffff0000, v1
	v_pk_add_f32 v[2:3], v[8:9], v[0:1]
	v_pk_add_f32 v[0:1], v[10:11], v[6:7]
	global_store_dwordx4 v[4:5], v[0:3], off offset:64
	s_cbranch_scc1 .LBB0_1222

; template <int KSTEPS  >
; __device__ __forceinline__ void small_mma_ksplit(f32x4 (&acc)[2], const bf16_t* A, int lda, const bf16_t* Bt, int ldb, int n0, LAS unsigned char* lds, const SmallId& id) {
;     ...
;     const bf16_t* ap = A + (size_t)(MP + id.fr) * lda + k0 + 8 * id.fq;
;     const bf16_t* bp = Bt + (size_t)(n0 + id.fr) * ldb + k0 + 8 * id.fq;
; #pragma unroll 1
;     for (int ks = 0; ks < KSTEPS; ++ks) {
;         bf16x8 a[8], b[2];
; #pragma unroll
;         for (int rb = 0; rb < 8; ++rb) a[rb] = *(const bf16x8*)(ap + (size_t)(16 * rb) * lda + 32 * ks);
;         b[0] = *(const bf16x8*)(bp + 32 * ks); b[1] = *(const bf16x8*)(bp + (size_t)16 * ldb + 32 * ks);
; #pragma unroll
;         for (int rb = 0; rb < 8; ++rb) { part[rb][0] = __builtin_amdgcn_mfma_f32_16x16x32_bf16(b[0], a[rb], part[rb][0], 0, 0, 0); part[rb][1] = __builtin_amdgcn_mfma_f32_16x16x32_bf16(b[1], a[rb], part[rb][1], 0, 0, 0); }
;     }
.LBB0_1255:
	s_waitcnt lgkmcnt(0)
	s_mov_b32 s9, 0
	s_mov_b32 s8, s62
	v_lshl_add_u64 v[68:69], v[72:73], 0, s[8:9]
	global_load_dwordx4 v[92:95], v[68:69], off
	s_mov_b32 s8, s52
	v_lshl_add_u64 v[86:87], v[70:71], 0, s[8:9]
	global_load_dwordx4 v[98:101], v[86:87], off
	s_mov_b32 s8, s63
	v_lshl_add_u64 v[88:89], v[72:73], 0, s[8:9]
	global_load_dwordx4 v[102:105], v[88:89], off
	s_mov_b32 s8, s53
	v_lshl_add_u64 v[90:91], v[70:71], 0, s[8:9]
	global_load_dwordx4 v[106:109], v[90:91], off
	s_mov_b32 s8, s56
	v_lshl_add_u64 v[68:69], v[70:71], 0, s[8:9]
	global_load_dwordx4 v[110:113], v[68:69], off
	s_mov_b32 s8, s57
	v_lshl_add_u64 v[86:87], v[70:71], 0, s[8:9]
	global_load_dwordx4 v[114:117], v[86:87], off
	s_mov_b32 s8, s58
	v_lshl_add_u64 v[88:89], v[70:71], 0, s[8:9]
	global_load_dwordx4 v[118:121], v[88:89], off
	s_mov_b32 s8, s59
	v_lshl_add_u64 v[90:91], v[70:71], 0, s[8:9]
	global_load_dwordx4 v[122:125], v[90:91], off
	s_mov_b32 s8, s60
	v_lshl_add_u64 v[68:69], v[70:71], 0, s[8:9]
	global_load_dwordx4 v[126:129], v[68:69], off
	s_mov_b32 s8, s61
	v_lshl_add_u64 v[86:87], v[70:71], 0, s[8:9]
	global_load_dwordx4 v[130:133], v[86:87], off
	s_mov_b32 s8, s62
	v_lshl_add_u64 v[88:89], v[72:73], 0, s[8:9]
	global_load_dwordx4 v[134:137], v[88:89], off offset:64
	s_mov_b32 s8, s52
	v_lshl_add_u64 v[90:91], v[70:71], 0, s[8:9]
	global_load_dwordx4 v[138:141], v[90:91], off offset:64
	s_mov_b32 s8, s63
	v_lshl_add_u64 v[68:69], v[72:73], 0, s[8:9]
	global_load_dwordx4 v[142:145], v[68:69], off offset:64
	s_mov_b32 s8, s53
	v_lshl_add_u64 v[86:87], v[70:71], 0, s[8:9]
	global_load_dwordx4 v[146:149], v[86:87], off offset:64
	s_mov_b32 s8, s56
	v_lshl_add_u64 v[88:89], v[70:71], 0, s[8:9]
	global_load_dwordx4 v[150:153], v[88:89], off offset:64
	s_mov_b32 s8, s57
	v_lshl_add_u64 v[90:91], v[70:71], 0, s[8:9]
	global_load_dwordx4 v[154:157], v[90:91], off offset:64
	s_mov_b32 s8, s58
	v_lshl_add_u64 v[68:69], v[70:71], 0, s[8:9]
	global_load_dwordx4 v[158:161], v[68:69], off offset:64
	s_mov_b32 s8, s59
	v_lshl_add_u64 v[86:87], v[70:71], 0, s[8:9]
	global_load_dwordx4 v[162:165], v[86:87], off offset:64
	s_mov_b32 s8, s60
	v_lshl_add_u64 v[88:89], v[70:71], 0, s[8:9]
	global_load_dwordx4 v[166:169], v[88:89], off offset:64
	s_mov_b32 s8, s61
	v_lshl_add_u64 v[90:91], v[70:71], 0, s[8:9]
	global_load_dwordx4 v[170:173], v[90:91], off offset:64
	s_mov_b32 s8, s62
	v_lshl_add_u64 v[68:69], v[72:73], 0, s[8:9]
	global_load_dwordx4 v[174:177], v[68:69], off offset:128
	s_mov_b32 s8, s52
	v_lshl_add_u64 v[86:87], v[70:71], 0, s[8:9]
	global_load_dwordx4 v[178:181], v[86:87], off offset:128
	s_mov_b32 s8, s63
	v_lshl_add_u64 v[88:89], v[72:73], 0, s[8:9]
	global_load_dwordx4 v[182:185], v[88:89], off offset:128
	s_mov_b32 s8, s53
	v_lshl_add_u64 v[90:91], v[70:71], 0, s[8:9]
	global_load_dwordx4 v[186:189], v[90:91], off offset:128
	s_mov_b32 s8, s56
	v_lshl_add_u64 v[68:69], v[70:71], 0, s[8:9]
	global_load_dwordx4 v[190:193], v[68:69], off offset:128
	s_mov_b32 s8, s57
	v_lshl_add_u64 v[86:87], v[70:71], 0, s[8:9]
	global_load_dwordx4 v[206:209], v[86:87], off offset:128
	s_mov_b32 s8, s58
	v_lshl_add_u64 v[88:89], v[70:71], 0, s[8:9]
	global_load_dwordx4 v[210:213], v[88:89], off offset:128
	s_mov_b32 s8, s59
	v_lshl_add_u64 v[90:91], v[70:71], 0, s[8:9]
	global_load_dwordx4 v[214:217], v[90:91], off offset:128
	s_mov_b32 s8, s60
	v_lshl_add_u64 v[68:69], v[70:71], 0, s[8:9]
	global_load_dwordx4 v[218:221], v[68:69], off offset:128
	s_mov_b32 s8, s61
	v_lshl_add_u64 v[86:87], v[70:71], 0, s[8:9]
	global_load_dwordx4 v[234:237], v[86:87], off offset:128
	s_waitcnt vmcnt(20)
	v_mfma_f32_16x16x32_bf16 v[36:39], v[92:95], v[98:101], v[36:39]
	v_mfma_f32_16x16x32_bf16 v[24:27], v[102:105], v[98:101], v[24:27]
	v_mfma_f32_16x16x32_bf16 v[20:23], v[92:95], v[106:109], v[20:23]
	v_mfma_f32_16x16x32_bf16 v[16:19], v[102:105], v[106:109], v[16:19]
	v_mfma_f32_16x16x32_bf16 v[12:15], v[92:95], v[110:113], v[12:15]
	v_mfma_f32_16x16x32_bf16 v[8:11], v[102:105], v[110:113], v[8:11]
	v_mfma_f32_16x16x32_bf16 v[4:7], v[92:95], v[114:117], v[4:7]
	v_mfma_f32_16x16x32_bf16 v[0:3], v[102:105], v[114:117], v[0:3]
	v_mfma_f32_16x16x32_bf16 v[28:31], v[92:95], v[118:121], v[28:31]
	v_mfma_f32_16x16x32_bf16 v[32:35], v[102:105], v[118:121], v[32:35]
	v_mfma_f32_16x16x32_bf16 v[40:43], v[92:95], v[122:125], v[40:43]
	v_mfma_f32_16x16x32_bf16 v[44:47], v[102:105], v[122:125], v[44:47]
	v_mfma_f32_16x16x32_bf16 v[48:51], v[92:95], v[126:129], v[48:51]
	v_mfma_f32_16x16x32_bf16 v[52:55], v[102:105], v[126:129], v[52:55]
	v_mfma_f32_16x16x32_bf16 v[56:59], v[92:95], v[130:133], v[56:59]
	v_mfma_f32_16x16x32_bf16 v[60:63], v[102:105], v[130:133], v[60:63]
	s_mov_b32 s8, s62
	v_lshl_add_u64 v[88:89], v[72:73], 0, s[8:9]
	global_load_dwordx4 v[92:95], v[88:89], off offset:192
	s_mov_b32 s8, s52
	v_lshl_add_u64 v[90:91], v[70:71], 0, s[8:9]
	global_load_dwordx4 v[98:101], v[90:91], off offset:192
	s_mov_b32 s8, s63
	v_lshl_add_u64 v[68:69], v[72:73], 0, s[8:9]
	global_load_dwordx4 v[102:105], v[68:69], off offset:192
	s_mov_b32 s8, s53
	v_lshl_add_u64 v[86:87], v[70:71], 0, s[8:9]
	global_load_dwordx4 v[106:109], v[86:87], off offset:192
	s_mov_b32 s8, s56
	v_lshl_add_u64 v[88:89], v[70:71], 0, s[8:9]
	global_load_dwordx4 v[110:113], v[88:89], off offset:192
	s_mov_b32 s8, s57
	v_lshl_add_u64 v[90:91], v[70:71], 0, s[8:9]
	global_load_dwordx4 v[114:117], v[90:91], off offset:192
	s_mov_b32 s8, s58
	v_lshl_add_u64 v[68:69], v[70:71], 0, s[8:9]
	global_load_dwordx4 v[118:121], v[68:69], off offset:192
	s_mov_b32 s8, s59
	v_lshl_add_u64 v[86:87], v[70:71], 0, s[8:9]
	global_load_dwordx4 v[122:125], v[86:87], off offset:192
	s_mov_b32 s8, s60
	v_lshl_add_u64 v[88:89], v[70:71], 0, s[8:9]
	global_load_dwordx4 v[126:129], v[88:89], off offset:192
	s_mov_b32 s8, s61
	v_lshl_add_u64 v[90:91], v[70:71], 0, s[8:9]
	global_load_dwordx4 v[130:133], v[90:91], off offset:192
	s_waitcnt vmcnt(20)
; template <int KSTEPS  >
; __device__ __forceinline__ void small_mma_ksplit(f32x4 (&acc)[2], const bf16_t* A, int lda, const bf16_t* Bt, int ldb, int n0, LAS unsigned char* lds, const SmallId& id) {
;     ...
;     for (int ks = 0; ks < KSTEPS; ++ks) {
;         bf16x8 a[8], b[2];
; #pragma unroll
;         for (int rb = 0; rb < 8; ++rb) a[rb] = *(const bf16x8*)(ap + (size_t)(16 * rb) * lda + 32 * ks);
;         b[0] = *(const bf16x8*)(bp + 32 * ks); b[1] = *(const bf16x8*)(bp + (size_t)16 * ldb + 32 * ks);
; #pragma unroll
;         for (int rb = 0; rb < 8; ++rb) { part[rb][0] = __builtin_amdgcn_mfma_f32_16x16x32_bf16(b[0], a[rb], part[rb][0], 0, 0, 0); part[rb][1] = __builtin_amdgcn_mfma_f32_16x16x32_bf16(b[1], a[rb], part[rb][1], 0, 0, 0); }
	v_mfma_f32_16x16x32_bf16 v[36:39], v[134:137], v[138:141], v[36:39]
	v_mfma_f32_16x16x32_bf16 v[24:27], v[142:145], v[138:141], v[24:27]
	v_mfma_f32_16x16x32_bf16 v[20:23], v[134:137], v[146:149], v[20:23]
	v_mfma_f32_16x16x32_bf16 v[16:19], v[142:145], v[146:149], v[16:19]
	v_mfma_f32_16x16x32_bf16 v[12:15], v[134:137], v[150:153], v[12:15]
	v_mfma_f32_16x16x32_bf16 v[8:11], v[142:145], v[150:153], v[8:11]
	v_mfma_f32_16x16x32_bf16 v[4:7], v[134:137], v[154:157], v[4:7]
	v_mfma_f32_16x16x32_bf16 v[0:3], v[142:145], v[154:157], v[0:3]
	v_mfma_f32_16x16x32_bf16 v[28:31], v[134:137], v[158:161], v[28:31]
	v_mfma_f32_16x16x32_bf16 v[32:35], v[142:145], v[158:161], v[32:35]
	v_mfma_f32_16x16x32_bf16 v[40:43], v[134:137], v[162:165], v[40:43]
	v_mfma_f32_16x16x32_bf16 v[44:47], v[142:145], v[162:165], v[44:47]
	v_mfma_f32_16x16x32_bf16 v[48:51], v[134:137], v[166:169], v[48:51]
	v_mfma_f32_16x16x32_bf16 v[52:55], v[142:145], v[166:169], v[52:55]
	v_mfma_f32_16x16x32_bf16 v[56:59], v[134:137], v[170:173], v[56:59]
	v_mfma_f32_16x16x32_bf16 v[60:63], v[142:145], v[170:173], v[60:63]
	s_mov_b32 s8, s62
	v_lshl_add_u64 v[68:69], v[72:73], 0, s[8:9]
	global_load_dwordx4 v[134:137], v[68:69], off offset:256
	s_mov_b32 s8, s52
	v_lshl_add_u64 v[86:87], v[70:71], 0, s[8:9]
	global_load_dwordx4 v[138:141], v[86:87], off offset:256
	s_mov_b32 s8, s63
	v_lshl_add_u64 v[88:89], v[72:73], 0, s[8:9]
	global_load_dwordx4 v[142:145], v[88:89], off offset:256
	s_mov_b32 s8, s53
	v_lshl_add_u64 v[90:91], v[70:71], 0, s[8:9]
	global_load_dwordx4 v[146:149], v[90:91], off offset:256
	s_mov_b32 s8, s56
	v_lshl_add_u64 v[68:69], v[70:71], 0, s[8:9]
	global_load_dwordx4 v[150:153], v[68:69], off offset:256
	s_mov_b32 s8, s57
	v_lshl_add_u64 v[86:87], v[70:71], 0, s[8:9]
	global_load_dwordx4 v[154:157], v[86:87], off offset:256
	s_mov_b32 s8, s58
	v_lshl_add_u64 v[88:89], v[70:71], 0, s[8:9]
	global_load_dwordx4 v[158:161], v[88:89], off offset:256
	s_mov_b32 s8, s59
	v_lshl_add_u64 v[90:91], v[70:71], 0, s[8:9]
	global_load_dwordx4 v[162:165], v[90:91], off offset:256
	s_mov_b32 s8, s60
	v_lshl_add_u64 v[68:69], v[70:71], 0, s[8:9]
	global_load_dwordx4 v[166:169], v[68:69], off offset:256
	s_mov_b32 s8, s61
	v_lshl_add_u64 v[86:87], v[70:71], 0, s[8:9]
	global_load_dwordx4 v[170:173], v[86:87], off offset:256
	s_waitcnt vmcnt(20)
	v_mfma_f32_16x16x32_bf16 v[36:39], v[174:177], v[178:181], v[36:39]
	v_mfma_f32_16x16x32_bf16 v[24:27], v[182:185], v[178:181], v[24:27]
	v_mfma_f32_16x16x32_bf16 v[20:23], v[174:177], v[186:189], v[20:23]
	v_mfma_f32_16x16x32_bf16 v[16:19], v[182:185], v[186:189], v[16:19]
	v_mfma_f32_16x16x32_bf16 v[12:15], v[174:177], v[190:193], v[12:15]
	v_mfma_f32_16x16x32_bf16 v[8:11], v[182:185], v[190:193], v[8:11]
	v_mfma_f32_16x16x32_bf16 v[4:7], v[174:177], v[206:209], v[4:7]
	v_mfma_f32_16x16x32_bf16 v[0:3], v[182:185], v[206:209], v[0:3]
	v_mfma_f32_16x16x32_bf16 v[28:31], v[174:177], v[210:213], v[28:31]
	v_mfma_f32_16x16x32_bf16 v[32:35], v[182:185], v[210:213], v[32:35]
	v_mfma_f32_16x16x32_bf16 v[40:43], v[174:177], v[214:217], v[40:43]
	v_mfma_f32_16x16x32_bf16 v[44:47], v[182:185], v[214:217], v[44:47]
	v_mfma_f32_16x16x32_bf16 v[48:51], v[174:177], v[218:221], v[48:51]
	v_mfma_f32_16x16x32_bf16 v[52:55], v[182:185], v[218:221], v[52:55]
	v_mfma_f32_16x16x32_bf16 v[56:59], v[174:177], v[234:237], v[56:59]
	v_mfma_f32_16x16x32_bf16 v[60:63], v[182:185], v[234:237], v[60:63]
	s_mov_b32 s8, s62
	v_lshl_add_u64 v[88:89], v[72:73], 0, s[8:9]
	global_load_dwordx4 v[174:177], v[88:89], off offset:320
	s_mov_b32 s8, s52
	v_lshl_add_u64 v[90:91], v[70:71], 0, s[8:9]
	global_load_dwordx4 v[178:181], v[90:91], off offset:320
	s_mov_b32 s8, s63
	v_lshl_add_u64 v[68:69], v[72:73], 0, s[8:9]
	global_load_dwordx4 v[182:185], v[68:69], off offset:320
	s_mov_b32 s8, s53
	v_lshl_add_u64 v[86:87], v[70:71], 0, s[8:9]
	global_load_dwordx4 v[186:189], v[86:87], off offset:320
	s_mov_b32 s8, s56
	v_lshl_add_u64 v[88:89], v[70:71], 0, s[8:9]
	global_load_dwordx4 v[190:193], v[88:89], off offset:320
	s_mov_b32 s8, s57
	v_lshl_add_u64 v[90:91], v[70:71], 0, s[8:9]
	global_load_dwordx4 v[206:209], v[90:91], off offset:320
	s_mov_b32 s8, s58
	v_lshl_add_u64 v[68:69], v[70:71], 0, s[8:9]
	global_load_dwordx4 v[210:213], v[68:69], off offset:320
	s_mov_b32 s8, s59
	v_lshl_add_u64 v[86:87], v[70:71], 0, s[8:9]
	global_load_dwordx4 v[214:217], v[86:87], off offset:320
	s_mov_b32 s8, s60
	v_lshl_add_u64 v[88:89], v[70:71], 0, s[8:9]
	global_load_dwordx4 v[218:221], v[88:89], off offset:320
	s_mov_b32 s8, s61
	v_lshl_add_u64 v[90:91], v[70:71], 0, s[8:9]
	global_load_dwordx4 v[234:237], v[90:91], off offset:320
	s_waitcnt vmcnt(20)
; template <int KSTEPS  >
; __device__ __forceinline__ void small_mma_ksplit(f32x4 (&acc)[2], const bf16_t* A, int lda, const bf16_t* Bt, int ldb, int n0, LAS unsigned char* lds, const SmallId& id) {
;     ...
;     for (int ks = 0; ks < KSTEPS; ++ks) {
;         bf16x8 a[8], b[2];
; #pragma unroll
;         for (int rb = 0; rb < 8; ++rb) a[rb] = *(const bf16x8*)(ap + (size_t)(16 * rb) * lda + 32 * ks);
;         b[0] = *(const bf16x8*)(bp + 32 * ks); b[1] = *(const bf16x8*)(bp + (size_t)16 * ldb + 32 * ks);
; #pragma unroll
;         for (int rb = 0; rb < 8; ++rb) { part[rb][0] = __builtin_amdgcn_mfma_f32_16x16x32_bf16(b[0], a[rb], part[rb][0], 0, 0, 0); part[rb][1] = __builtin_amdgcn_mfma_f32_16x16x32_bf16(b[1], a[rb], part[rb][1], 0, 0, 0); }
	v_mfma_f32_16x16x32_bf16 v[36:39], v[92:95], v[98:101], v[36:39]
	v_mfma_f32_16x16x32_bf16 v[24:27], v[102:105], v[98:101], v[24:27]
	v_mfma_f32_16x16x32_bf16 v[20:23], v[92:95], v[106:109], v[20:23]
	v_mfma_f32_16x16x32_bf16 v[16:19], v[102:105], v[106:109], v[16:19]
	v_mfma_f32_16x16x32_bf16 v[12:15], v[92:95], v[110:113], v[12:15]
	v_mfma_f32_16x16x32_bf16 v[8:11], v[102:105], v[110:113], v[8:11]
	v_mfma_f32_16x16x32_bf16 v[4:7], v[92:95], v[114:117], v[4:7]
	v_mfma_f32_16x16x32_bf16 v[0:3], v[102:105], v[114:117], v[0:3]
	v_mfma_f32_16x16x32_bf16 v[28:31], v[92:95], v[118:121], v[28:31]
	v_mfma_f32_16x16x32_bf16 v[32:35], v[102:105], v[118:121], v[32:35]
	v_mfma_f32_16x16x32_bf16 v[40:43], v[92:95], v[122:125], v[40:43]
	v_mfma_f32_16x16x32_bf16 v[44:47], v[102:105], v[122:125], v[44:47]
	v_mfma_f32_16x16x32_bf16 v[48:51], v[92:95], v[126:129], v[48:51]
	v_mfma_f32_16x16x32_bf16 v[52:55], v[102:105], v[126:129], v[52:55]
	v_mfma_f32_16x16x32_bf16 v[56:59], v[92:95], v[130:133], v[56:59]
	v_mfma_f32_16x16x32_bf16 v[60:63], v[102:105], v[130:133], v[60:63]
	s_mov_b32 s8, s62
	v_lshl_add_u64 v[68:69], v[72:73], 0, s[8:9]
	global_load_dwordx4 v[92:95], v[68:69], off offset:384
	s_mov_b32 s8, s52
	v_lshl_add_u64 v[86:87], v[70:71], 0, s[8:9]
	global_load_dwordx4 v[98:101], v[86:87], off offset:384
	s_mov_b32 s8, s63
	v_lshl_add_u64 v[88:89], v[72:73], 0, s[8:9]
	global_load_dwordx4 v[102:105], v[88:89], off offset:384
	s_mov_b32 s8, s53
	v_lshl_add_u64 v[90:91], v[70:71], 0, s[8:9]
	global_load_dwordx4 v[106:109], v[90:91], off offset:384
	s_mov_b32 s8, s56
	v_lshl_add_u64 v[68:69], v[70:71], 0, s[8:9]
	global_load_dwordx4 v[110:113], v[68:69], off offset:384
	s_mov_b32 s8, s57
	v_lshl_add_u64 v[86:87], v[70:71], 0, s[8:9]
	global_load_dwordx4 v[114:117], v[86:87], off offset:384
	s_mov_b32 s8, s58
	v_lshl_add_u64 v[88:89], v[70:71], 0, s[8:9]
	global_load_dwordx4 v[118:121], v[88:89], off offset:384
	s_mov_b32 s8, s59
	v_lshl_add_u64 v[90:91], v[70:71], 0, s[8:9]
	global_load_dwordx4 v[122:125], v[90:91], off offset:384
	s_mov_b32 s8, s60
	v_lshl_add_u64 v[68:69], v[70:71], 0, s[8:9]
	global_load_dwordx4 v[126:129], v[68:69], off offset:384
	s_mov_b32 s8, s61
	v_lshl_add_u64 v[86:87], v[70:71], 0, s[8:9]
	global_load_dwordx4 v[130:133], v[86:87], off offset:384
	s_waitcnt vmcnt(20)
	v_mfma_f32_16x16x32_bf16 v[36:39], v[134:137], v[138:141], v[36:39]
	v_mfma_f32_16x16x32_bf16 v[24:27], v[142:145], v[138:141], v[24:27]
	v_mfma_f32_16x16x32_bf16 v[20:23], v[134:137], v[146:149], v[20:23]
	v_mfma_f32_16x16x32_bf16 v[16:19], v[142:145], v[146:149], v[16:19]
	v_mfma_f32_16x16x32_bf16 v[12:15], v[134:137], v[150:153], v[12:15]
	v_mfma_f32_16x16x32_bf16 v[8:11], v[142:145], v[150:153], v[8:11]
	v_mfma_f32_16x16x32_bf16 v[4:7], v[134:137], v[154:157], v[4:7]
	v_mfma_f32_16x16x32_bf16 v[0:3], v[142:145], v[154:157], v[0:3]
	v_mfma_f32_16x16x32_bf16 v[28:31], v[134:137], v[158:161], v[28:31]
	v_mfma_f32_16x16x32_bf16 v[32:35], v[142:145], v[158:161], v[32:35]
	v_mfma_f32_16x16x32_bf16 v[40:43], v[134:137], v[162:165], v[40:43]
	v_mfma_f32_16x16x32_bf16 v[44:47], v[142:145], v[162:165], v[44:47]
	v_mfma_f32_16x16x32_bf16 v[48:51], v[134:137], v[166:169], v[48:51]
	v_mfma_f32_16x16x32_bf16 v[52:55], v[142:145], v[166:169], v[52:55]
	v_mfma_f32_16x16x32_bf16 v[56:59], v[134:137], v[170:173], v[56:59]
	v_mfma_f32_16x16x32_bf16 v[60:63], v[142:145], v[170:173], v[60:63]
	s_mov_b32 s8, s62
	v_lshl_add_u64 v[88:89], v[72:73], 0, s[8:9]
	global_load_dwordx4 v[134:137], v[88:89], off offset:448
	s_mov_b32 s8, s52
	v_lshl_add_u64 v[90:91], v[70:71], 0, s[8:9]
	global_load_dwordx4 v[138:141], v[90:91], off offset:448
	s_mov_b32 s8, s63
	v_lshl_add_u64 v[68:69], v[72:73], 0, s[8:9]
	global_load_dwordx4 v[142:145], v[68:69], off offset:448
	s_mov_b32 s8, s53
	v_lshl_add_u64 v[86:87], v[70:71], 0, s[8:9]
	global_load_dwordx4 v[146:149], v[86:87], off offset:448
	s_mov_b32 s8, s56
	v_lshl_add_u64 v[88:89], v[70:71], 0, s[8:9]
	global_load_dwordx4 v[150:153], v[88:89], off offset:448
	s_mov_b32 s8, s57
	v_lshl_add_u64 v[90:91], v[70:71], 0, s[8:9]
	global_load_dwordx4 v[154:157], v[90:91], off offset:448
	s_mov_b32 s8, s58
	v_lshl_add_u64 v[68:69], v[70:71], 0, s[8:9]
	global_load_dwordx4 v[158:161], v[68:69], off offset:448
	s_mov_b32 s8, s59
	v_lshl_add_u64 v[86:87], v[70:71], 0, s[8:9]
	global_load_dwordx4 v[162:165], v[86:87], off offset:448
	s_mov_b32 s8, s60
	v_lshl_add_u64 v[88:89], v[70:71], 0, s[8:9]
	global_load_dwordx4 v[166:169], v[88:89], off offset:448
	s_mov_b32 s8, s61
	v_lshl_add_u64 v[90:91], v[70:71], 0, s[8:9]
	global_load_dwordx4 v[170:173], v[90:91], off offset:448
	s_waitcnt vmcnt(20)
; template <int KSTEPS  >
; __device__ __forceinline__ void small_mma_ksplit(f32x4 (&acc)[2], const bf16_t* A, int lda, const bf16_t* Bt, int ldb, int n0, LAS unsigned char* lds, const SmallId& id) {
;     ...
;     for (int ks = 0; ks < KSTEPS; ++ks) {
;         bf16x8 a[8], b[2];
; #pragma unroll
;         for (int rb = 0; rb < 8; ++rb) a[rb] = *(const bf16x8*)(ap + (size_t)(16 * rb) * lda + 32 * ks);
;         b[0] = *(const bf16x8*)(bp + 32 * ks); b[1] = *(const bf16x8*)(bp + (size_t)16 * ldb + 32 * ks);
; #pragma unroll
;         for (int rb = 0; rb < 8; ++rb) { part[rb][0] = __builtin_amdgcn_mfma_f32_16x16x32_bf16(b[0], a[rb], part[rb][0], 0, 0, 0); part[rb][1] = __builtin_amdgcn_mfma_f32_16x16x32_bf16(b[1], a[rb], part[rb][1], 0, 0, 0); }
	v_mfma_f32_16x16x32_bf16 v[36:39], v[174:177], v[178:181], v[36:39]
	v_mfma_f32_16x16x32_bf16 v[24:27], v[182:185], v[178:181], v[24:27]
	v_mfma_f32_16x16x32_bf16 v[20:23], v[174:177], v[186:189], v[20:23]
	v_mfma_f32_16x16x32_bf16 v[16:19], v[182:185], v[186:189], v[16:19]
	v_mfma_f32_16x16x32_bf16 v[12:15], v[174:177], v[190:193], v[12:15]
	v_mfma_f32_16x16x32_bf16 v[8:11], v[182:185], v[190:193], v[8:11]
	v_mfma_f32_16x16x32_bf16 v[4:7], v[174:177], v[206:209], v[4:7]
	v_mfma_f32_16x16x32_bf16 v[0:3], v[182:185], v[206:209], v[0:3]
	v_mfma_f32_16x16x32_bf16 v[28:31], v[174:177], v[210:213], v[28:31]
	v_mfma_f32_16x16x32_bf16 v[32:35], v[182:185], v[210:213], v[32:35]
	v_mfma_f32_16x16x32_bf16 v[40:43], v[174:177], v[214:217], v[40:43]
	v_mfma_f32_16x16x32_bf16 v[44:47], v[182:185], v[214:217], v[44:47]
	v_mfma_f32_16x16x32_bf16 v[48:51], v[174:177], v[218:221], v[48:51]
	v_mfma_f32_16x16x32_bf16 v[52:55], v[182:185], v[218:221], v[52:55]
	v_mfma_f32_16x16x32_bf16 v[56:59], v[174:177], v[234:237], v[56:59]
	v_mfma_f32_16x16x32_bf16 v[60:63], v[182:185], v[234:237], v[60:63]
	s_mov_b32 s8, s62
	v_lshl_add_u64 v[68:69], v[72:73], 0, s[8:9]
	global_load_dwordx4 v[174:177], v[68:69], off offset:512
	s_mov_b32 s8, s52
	v_lshl_add_u64 v[86:87], v[70:71], 0, s[8:9]
	global_load_dwordx4 v[178:181], v[86:87], off offset:512
	s_mov_b32 s8, s63
	v_lshl_add_u64 v[88:89], v[72:73], 0, s[8:9]
	global_load_dwordx4 v[182:185], v[88:89], off offset:512
	s_mov_b32 s8, s53
	v_lshl_add_u64 v[90:91], v[70:71], 0, s[8:9]
	global_load_dwordx4 v[186:189], v[90:91], off offset:512
	s_mov_b32 s8, s56
	v_lshl_add_u64 v[68:69], v[70:71], 0, s[8:9]
	global_load_dwordx4 v[190:193], v[68:69], off offset:512
	s_mov_b32 s8, s57
	v_lshl_add_u64 v[86:87], v[70:71], 0, s[8:9]
	global_load_dwordx4 v[206:209], v[86:87], off offset:512
	s_mov_b32 s8, s58
	v_lshl_add_u64 v[88:89], v[70:71], 0, s[8:9]
	global_load_dwordx4 v[210:213], v[88:89], off offset:512
	s_mov_b32 s8, s59
	v_lshl_add_u64 v[90:91], v[70:71], 0, s[8:9]
	global_load_dwordx4 v[214:217], v[90:91], off offset:512
	s_mov_b32 s8, s60
	v_lshl_add_u64 v[68:69], v[70:71], 0, s[8:9]
	global_load_dwordx4 v[218:221], v[68:69], off offset:512
	s_mov_b32 s8, s61
	v_lshl_add_u64 v[86:87], v[70:71], 0, s[8:9]
	global_load_dwordx4 v[234:237], v[86:87], off offset:512
	s_waitcnt vmcnt(20)
	v_mfma_f32_16x16x32_bf16 v[36:39], v[92:95], v[98:101], v[36:39]
	v_mfma_f32_16x16x32_bf16 v[24:27], v[102:105], v[98:101], v[24:27]
	v_mfma_f32_16x16x32_bf16 v[20:23], v[92:95], v[106:109], v[20:23]
	v_mfma_f32_16x16x32_bf16 v[16:19], v[102:105], v[106:109], v[16:19]
	v_mfma_f32_16x16x32_bf16 v[12:15], v[92:95], v[110:113], v[12:15]
	v_mfma_f32_16x16x32_bf16 v[8:11], v[102:105], v[110:113], v[8:11]
	v_mfma_f32_16x16x32_bf16 v[4:7], v[92:95], v[114:117], v[4:7]
	v_mfma_f32_16x16x32_bf16 v[0:3], v[102:105], v[114:117], v[0:3]
	v_mfma_f32_16x16x32_bf16 v[28:31], v[92:95], v[118:121], v[28:31]
	v_mfma_f32_16x16x32_bf16 v[32:35], v[102:105], v[118:121], v[32:35]
	v_mfma_f32_16x16x32_bf16 v[40:43], v[92:95], v[122:125], v[40:43]
	v_mfma_f32_16x16x32_bf16 v[44:47], v[102:105], v[122:125], v[44:47]
	v_mfma_f32_16x16x32_bf16 v[48:51], v[92:95], v[126:129], v[48:51]
	v_mfma_f32_16x16x32_bf16 v[52:55], v[102:105], v[126:129], v[52:55]
	v_mfma_f32_16x16x32_bf16 v[56:59], v[92:95], v[130:133], v[56:59]
	v_mfma_f32_16x16x32_bf16 v[60:63], v[102:105], v[130:133], v[60:63]
	s_mov_b32 s8, s62
	v_lshl_add_u64 v[88:89], v[72:73], 0, s[8:9]
	global_load_dwordx4 v[92:95], v[88:89], off offset:576
	s_mov_b32 s8, s52
	v_lshl_add_u64 v[90:91], v[70:71], 0, s[8:9]
	global_load_dwordx4 v[98:101], v[90:91], off offset:576
	s_mov_b32 s8, s63
	v_lshl_add_u64 v[68:69], v[72:73], 0, s[8:9]
	global_load_dwordx4 v[102:105], v[68:69], off offset:576
	s_mov_b32 s8, s53
	v_lshl_add_u64 v[86:87], v[70:71], 0, s[8:9]
	global_load_dwordx4 v[106:109], v[86:87], off offset:576
	s_mov_b32 s8, s56
	v_lshl_add_u64 v[88:89], v[70:71], 0, s[8:9]
	global_load_dwordx4 v[110:113], v[88:89], off offset:576
	s_mov_b32 s8, s57
	v_lshl_add_u64 v[90:91], v[70:71], 0, s[8:9]
	global_load_dwordx4 v[114:117], v[90:91], off offset:576
	s_mov_b32 s8, s58
	v_lshl_add_u64 v[68:69], v[70:71], 0, s[8:9]
	global_load_dwordx4 v[118:121], v[68:69], off offset:576
	s_mov_b32 s8, s59
	v_lshl_add_u64 v[86:87], v[70:71], 0, s[8:9]
	global_load_dwordx4 v[122:125], v[86:87], off offset:576
	s_mov_b32 s8, s60
	v_lshl_add_u64 v[88:89], v[70:71], 0, s[8:9]
	global_load_dwordx4 v[126:129], v[88:89], off offset:576
	s_mov_b32 s8, s61
	v_lshl_add_u64 v[90:91], v[70:71], 0, s[8:9]
	global_load_dwordx4 v[130:133], v[90:91], off offset:576
	s_waitcnt vmcnt(20)
; #define LAS __attribute__((address_space(3)))
; template <int KSTEPS  >
; __device__ __forceinline__ void small_mma_ksplit(f32x4 (&acc)[2], const bf16_t* A, int lda, const bf16_t* Bt, int ldb, int n0, LAS unsigned char* lds, const SmallId& id) {
;     ...
;     for (int ks = 0; ks < KSTEPS; ++ks) {
;         bf16x8 a[8], b[2];
; #pragma unroll
;         for (int rb = 0; rb < 8; ++rb) a[rb] = *(const bf16x8*)(ap + (size_t)(16 * rb) * lda + 32 * ks);
;         b[0] = *(const bf16x8*)(bp + 32 * ks); b[1] = *(const bf16x8*)(bp + (size_t)16 * ldb + 32 * ks);
; #pragma unroll
;         for (int rb = 0; rb < 8; ++rb) { part[rb][0] = __builtin_amdgcn_mfma_f32_16x16x32_bf16(b[0], a[rb], part[rb][0], 0, 0, 0); part[rb][1] = __builtin_amdgcn_mfma_f32_16x16x32_bf16(b[1], a[rb], part[rb][1], 0, 0, 0); }
;     }
;     LAS f32x4* red = (LAS f32x4*)lds;
; #pragma unroll
;     for (int rb = 0; rb < 8; ++rb) { red[((id.w * 8 + rb) * 2 + 0) * 64 + lane] = part[rb][0]; red[((id.w * 8 + rb) * 2 + 1) * 64 + lane] = part[rb][1]; }
;     asm volatile("s_waitcnt lgkmcnt(0)" ::: "memory"); __syncthreads();
	v_mfma_f32_16x16x32_bf16 v[36:39], v[134:137], v[138:141], v[36:39]
	v_mfma_f32_16x16x32_bf16 v[24:27], v[142:145], v[138:141], v[24:27]
	v_mfma_f32_16x16x32_bf16 v[20:23], v[134:137], v[146:149], v[20:23]
	v_mfma_f32_16x16x32_bf16 v[16:19], v[142:145], v[146:149], v[16:19]
	v_mfma_f32_16x16x32_bf16 v[12:15], v[134:137], v[150:153], v[12:15]
	v_mfma_f32_16x16x32_bf16 v[8:11], v[142:145], v[150:153], v[8:11]
	v_mfma_f32_16x16x32_bf16 v[4:7], v[134:137], v[154:157], v[4:7]
	v_mfma_f32_16x16x32_bf16 v[0:3], v[142:145], v[154:157], v[0:3]
	v_mfma_f32_16x16x32_bf16 v[28:31], v[134:137], v[158:161], v[28:31]
	v_mfma_f32_16x16x32_bf16 v[32:35], v[142:145], v[158:161], v[32:35]
	v_mfma_f32_16x16x32_bf16 v[40:43], v[134:137], v[162:165], v[40:43]
	v_mfma_f32_16x16x32_bf16 v[44:47], v[142:145], v[162:165], v[44:47]
	v_mfma_f32_16x16x32_bf16 v[48:51], v[134:137], v[166:169], v[48:51]
	v_mfma_f32_16x16x32_bf16 v[52:55], v[142:145], v[166:169], v[52:55]
	v_mfma_f32_16x16x32_bf16 v[56:59], v[134:137], v[170:173], v[56:59]
	v_mfma_f32_16x16x32_bf16 v[60:63], v[142:145], v[170:173], v[60:63]
	s_mov_b32 s8, s62
	v_lshl_add_u64 v[68:69], v[72:73], 0, s[8:9]
	global_load_dwordx4 v[134:137], v[68:69], off offset:640
	s_mov_b32 s8, s52
	v_lshl_add_u64 v[86:87], v[70:71], 0, s[8:9]
	global_load_dwordx4 v[138:141], v[86:87], off offset:640
	s_mov_b32 s8, s63
	v_lshl_add_u64 v[88:89], v[72:73], 0, s[8:9]
	global_load_dwordx4 v[142:145], v[88:89], off offset:640
	s_mov_b32 s8, s53
	v_lshl_add_u64 v[90:91], v[70:71], 0, s[8:9]
	global_load_dwordx4 v[146:149], v[90:91], off offset:640
	s_mov_b32 s8, s56
	v_lshl_add_u64 v[68:69], v[70:71], 0, s[8:9]
	global_load_dwordx4 v[150:153], v[68:69], off offset:640
	s_mov_b32 s8, s57
	v_lshl_add_u64 v[86:87], v[70:71], 0, s[8:9]
	global_load_dwordx4 v[154:157], v[86:87], off offset:640
	s_mov_b32 s8, s58
	v_lshl_add_u64 v[88:89], v[70:71], 0, s[8:9]
	global_load_dwordx4 v[158:161], v[88:89], off offset:640
	s_mov_b32 s8, s59
	v_lshl_add_u64 v[90:91], v[70:71], 0, s[8:9]
	global_load_dwordx4 v[162:165], v[90:91], off offset:640
	s_mov_b32 s8, s60
	v_lshl_add_u64 v[68:69], v[70:71], 0, s[8:9]
	global_load_dwordx4 v[166:169], v[68:69], off offset:640
	s_mov_b32 s8, s61
	v_lshl_add_u64 v[86:87], v[70:71], 0, s[8:9]
	global_load_dwordx4 v[170:173], v[86:87], off offset:640
	s_waitcnt vmcnt(20)
	v_mfma_f32_16x16x32_bf16 v[36:39], v[174:177], v[178:181], v[36:39]
	v_mfma_f32_16x16x32_bf16 v[24:27], v[182:185], v[178:181], v[24:27]
	v_mfma_f32_16x16x32_bf16 v[20:23], v[174:177], v[186:189], v[20:23]
	v_mfma_f32_16x16x32_bf16 v[16:19], v[182:185], v[186:189], v[16:19]
	v_mfma_f32_16x16x32_bf16 v[12:15], v[174:177], v[190:193], v[12:15]
	v_mfma_f32_16x16x32_bf16 v[8:11], v[182:185], v[190:193], v[8:11]
	v_mfma_f32_16x16x32_bf16 v[4:7], v[174:177], v[206:209], v[4:7]
	v_mfma_f32_16x16x32_bf16 v[0:3], v[182:185], v[206:209], v[0:3]
	v_mfma_f32_16x16x32_bf16 v[28:31], v[174:177], v[210:213], v[28:31]
	v_mfma_f32_16x16x32_bf16 v[32:35], v[182:185], v[210:213], v[32:35]
	v_mfma_f32_16x16x32_bf16 v[40:43], v[174:177], v[214:217], v[40:43]
	v_mfma_f32_16x16x32_bf16 v[44:47], v[182:185], v[214:217], v[44:47]
	v_mfma_f32_16x16x32_bf16 v[48:51], v[174:177], v[218:221], v[48:51]
	v_mfma_f32_16x16x32_bf16 v[52:55], v[182:185], v[218:221], v[52:55]
	v_mfma_f32_16x16x32_bf16 v[56:59], v[174:177], v[234:237], v[56:59]
	v_mfma_f32_16x16x32_bf16 v[60:63], v[182:185], v[234:237], v[60:63]
	s_waitcnt vmcnt(10)
	v_mfma_f32_16x16x32_bf16 v[36:39], v[92:95], v[98:101], v[36:39]
	v_mfma_f32_16x16x32_bf16 v[24:27], v[102:105], v[98:101], v[24:27]
	v_mfma_f32_16x16x32_bf16 v[20:23], v[92:95], v[106:109], v[20:23]
	v_mfma_f32_16x16x32_bf16 v[16:19], v[102:105], v[106:109], v[16:19]
	v_mfma_f32_16x16x32_bf16 v[12:15], v[92:95], v[110:113], v[12:15]
	v_mfma_f32_16x16x32_bf16 v[8:11], v[102:105], v[110:113], v[8:11]
	v_mfma_f32_16x16x32_bf16 v[4:7], v[92:95], v[114:117], v[4:7]
	v_mfma_f32_16x16x32_bf16 v[0:3], v[102:105], v[114:117], v[0:3]
	v_mfma_f32_16x16x32_bf16 v[28:31], v[92:95], v[118:121], v[28:31]
	v_mfma_f32_16x16x32_bf16 v[32:35], v[102:105], v[118:121], v[32:35]
	v_mfma_f32_16x16x32_bf16 v[40:43], v[92:95], v[122:125], v[40:43]
	v_mfma_f32_16x16x32_bf16 v[44:47], v[102:105], v[122:125], v[44:47]
	v_mfma_f32_16x16x32_bf16 v[48:51], v[92:95], v[126:129], v[48:51]
	v_mfma_f32_16x16x32_bf16 v[52:55], v[102:105], v[126:129], v[52:55]
	v_mfma_f32_16x16x32_bf16 v[56:59], v[92:95], v[130:133], v[56:59]
	v_mfma_f32_16x16x32_bf16 v[60:63], v[102:105], v[130:133], v[60:63]
	s_waitcnt vmcnt(0)
	v_mfma_f32_16x16x32_bf16 v[36:39], v[134:137], v[138:141], v[36:39]
	v_mfma_f32_16x16x32_bf16 v[24:27], v[142:145], v[138:141], v[24:27]
	v_mfma_f32_16x16x32_bf16 v[20:23], v[134:137], v[146:149], v[20:23]
	v_mfma_f32_16x16x32_bf16 v[16:19], v[142:145], v[146:149], v[16:19]
	v_mfma_f32_16x16x32_bf16 v[12:15], v[134:137], v[150:153], v[12:15]
	v_mfma_f32_16x16x32_bf16 v[8:11], v[142:145], v[150:153], v[8:11]
	v_mfma_f32_16x16x32_bf16 v[4:7], v[134:137], v[154:157], v[4:7]
	v_mfma_f32_16x16x32_bf16 v[0:3], v[142:145], v[154:157], v[0:3]
	v_mfma_f32_16x16x32_bf16 v[28:31], v[134:137], v[158:161], v[28:31]
	v_mfma_f32_16x16x32_bf16 v[32:35], v[142:145], v[158:161], v[32:35]
	v_mfma_f32_16x16x32_bf16 v[40:43], v[134:137], v[162:165], v[40:43]
	v_mfma_f32_16x16x32_bf16 v[44:47], v[142:145], v[162:165], v[44:47]
	v_mfma_f32_16x16x32_bf16 v[48:51], v[134:137], v[166:169], v[48:51]
	v_mfma_f32_16x16x32_bf16 v[52:55], v[142:145], v[166:169], v[52:55]
	v_mfma_f32_16x16x32_bf16 v[56:59], v[134:137], v[170:173], v[56:59]
	v_mfma_f32_16x16x32_bf16 v[60:63], v[142:145], v[170:173], v[60:63]
	ds_write_b128 v74, v[36:39]
	ds_write_b128 v74, v[24:27] offset:1024
	ds_write_b128 v74, v[20:23] offset:2048
	ds_write_b128 v74, v[16:19] offset:3072
	ds_write_b128 v74, v[12:15] offset:4096
	ds_write_b128 v74, v[8:11] offset:5120
	ds_write_b128 v74, v[4:7] offset:6144
	ds_write_b128 v74, v[0:3] offset:7168
	ds_write_b128 v74, v[28:31] offset:8192
	ds_write_b128 v74, v[32:35] offset:9216
	ds_write_b128 v74, v[40:43] offset:10240
	ds_write_b128 v74, v[44:47] offset:11264
	ds_write_b128 v74, v[48:51] offset:12288
	ds_write_b128 v74, v[52:55] offset:13312
	ds_write_b128 v74, v[56:59] offset:14336
	ds_write_b128 v74, v[60:63] offset:15360
	s_waitcnt lgkmcnt(0)
	s_waitcnt lgkmcnt(0)
	s_barrier
; __device__ __forceinline__ unsigned cvt_pk_bf16(float lo, float hi) { unsigned r; asm volatile("v_cvt_pk_bf16_f32 %0, %1, %2" : "=v"(r) : "v"(lo), "v"(hi)); return r; }
; template <int KSTEPS  >
; __device__ __forceinline__ void small_mma_ksplit(f32x4 (&acc)[2], const bf16_t* A, int lda, const bf16_t* Bt, int ldb, int n0, LAS unsigned char* lds, const SmallId& id) {
;     ...
;     acc[0] = (f32x4){0.f, 0.f, 0.f, 0.f}; acc[1] = acc[0];
; #pragma unroll
;     for (int w2 = 0; w2 < 8; ++w2) { acc[0] += red[((w2 * 8 + id.w) * 2 + 0) * 64 + lane]; acc[1] += red[((w2 * 8 + id.w) * 2 + 1) * 64 + lane]; }
;     asm volatile("s_waitcnt lgkmcnt(0)" ::: "memory"); __syncthreads();
; template <bool RES_F32, bool OUT_F32, int KSTEPS>
; __device__ __forceinline__ void small_res(const Params& p, LAS unsigned char* lds, const bf16_t* A, int lda, const bf16_t* Bt, int K, float* ssq_next, int G, int bx) {
;     ...
;         float s = 0.f;
; #pragma unroll
;         for (int nb = 0; nb < 2; ++nb) { const int col = n0 + 16 * nb + 4 * id.fq;
;             f32x4 r;
;             if (RES_F32) r = *(const f32x4*)(p.xs + (size_t)(id.row - MP) * DM + col);
;             else { const u32x2 w = *(const u32x2*)(XB + (size_t)id.row * DM + col); r = (f32x4){bf_lo(w.x), bf_hi(w.x), bf_lo(w.y), bf_hi(w.y)}; }
;             const f32x4 x = r + acc[nb];
;             if (OUT_F32) *(f32x4*)(p.out + (size_t)id.row * DM + col) = x;
;             else { u32x2 w; w.x = cvt_pk_bf16(x[0], x[1]); w.y = cvt_pk_bf16(x[2], x[3]); *(u32x2*)(XB + (size_t)id.row * DM + col) = w; }
;             s += (x[0] * x[0] + x[1] * x[1]) + (x[2] * x[2] + x[3] * x[3]); }
;         if (!OUT_F32) { s += __shfl_xor(s, 16); s += __shfl_xor(s, 32); if (id.fq == 0) atomicAdd(ssq_next + id.row, s); }
;     }
	ds_read_b128 v[0:3], v75
	s_waitcnt lgkmcnt(0)
	v_pk_add_f32 v[4:5], v[2:3], 0 op_sel_hi:[1,0]
	v_pk_add_f32 v[6:7], v[0:1], 0 op_sel_hi:[1,0]
	ds_read_b128 v[0:3], v75 offset:1024
	s_waitcnt lgkmcnt(0)
	v_pk_add_f32 v[8:9], v[2:3], 0 op_sel_hi:[1,0]
	v_pk_add_f32 v[10:11], v[0:1], 0 op_sel_hi:[1,0]
	ds_read_b128 v[0:3], v75 offset:16384
	s_waitcnt lgkmcnt(0)
	v_pk_add_f32 v[4:5], v[4:5], v[2:3]
	v_pk_add_f32 v[6:7], v[6:7], v[0:1]
	ds_read_b128 v[0:3], v75 offset:17408
	s_waitcnt lgkmcnt(0)
	v_pk_add_f32 v[8:9], v[8:9], v[2:3]
	v_pk_add_f32 v[10:11], v[10:11], v[0:1]
	ds_read_b128 v[0:3], v75 offset:32768
	s_waitcnt lgkmcnt(0)
	v_pk_add_f32 v[4:5], v[4:5], v[2:3]
	v_pk_add_f32 v[6:7], v[6:7], v[0:1]
	ds_read_b128 v[0:3], v75 offset:33792
	s_waitcnt lgkmcnt(0)
	v_pk_add_f32 v[8:9], v[8:9], v[2:3]
	v_pk_add_f32 v[10:11], v[10:11], v[0:1]
	ds_read_b128 v[0:3], v75 offset:49152
	s_waitcnt lgkmcnt(0)
	v_pk_add_f32 v[4:5], v[4:5], v[2:3]
	v_pk_add_f32 v[6:7], v[6:7], v[0:1]
	ds_read_b128 v[0:3], v75 offset:50176
	s_waitcnt lgkmcnt(0)
	v_pk_add_f32 v[8:9], v[8:9], v[2:3]
	v_pk_add_f32 v[10:11], v[10:11], v[0:1]
	ds_read_b128 v[0:3], v76
	s_waitcnt lgkmcnt(0)
	v_pk_add_f32 v[4:5], v[4:5], v[2:3]
	v_pk_add_f32 v[6:7], v[6:7], v[0:1]
	ds_read_b128 v[0:3], v77
	s_waitcnt lgkmcnt(0)
	v_pk_add_f32 v[8:9], v[8:9], v[2:3]
	v_pk_add_f32 v[10:11], v[10:11], v[0:1]
	ds_read_b128 v[0:3], v78
	s_waitcnt lgkmcnt(0)
	v_pk_add_f32 v[4:5], v[4:5], v[2:3]
	v_pk_add_f32 v[6:7], v[6:7], v[0:1]
	ds_read_b128 v[0:3], v79
	s_waitcnt lgkmcnt(0)
	v_pk_add_f32 v[8:9], v[8:9], v[2:3]
	v_pk_add_f32 v[10:11], v[10:11], v[0:1]
	ds_read_b128 v[0:3], v80
	s_waitcnt lgkmcnt(0)
	v_pk_add_f32 v[4:5], v[4:5], v[2:3]
	v_pk_add_f32 v[6:7], v[6:7], v[0:1]
	ds_read_b128 v[0:3], v81
	s_waitcnt lgkmcnt(0)
	v_pk_add_f32 v[8:9], v[8:9], v[2:3]
	v_pk_add_f32 v[10:11], v[10:11], v[0:1]
	ds_read_b128 v[0:3], v82
	s_waitcnt lgkmcnt(0)
	v_pk_add_f32 v[4:5], v[4:5], v[2:3]
	v_pk_add_f32 v[6:7], v[6:7], v[0:1]
	ds_read_b128 v[0:3], v83
	s_waitcnt lgkmcnt(0)
	s_waitcnt lgkmcnt(0)
	s_barrier
	v_pk_add_f32 v[2:3], v[8:9], v[2:3]
	v_lshl_or_b32 v8, s7, 5, v84
	v_ashrrev_i32_e32 v9, 31, v8
	v_lshl_add_u64 v[8:9], v[8:9], 1, v[64:65]
	v_pk_add_f32 v[0:1], v[10:11], v[0:1]
	global_load_dwordx2 v[10:11], v[8:9], off
	s_waitcnt vmcnt(0) lgkmcnt(0)
	v_lshlrev_b32_e32 v12, 16, v10
	v_and_b32_e32 v13, 0xffff0000, v10
	v_lshlrev_b32_e32 v10, 16, v11
	v_and_b32_e32 v11, 0xffff0000, v11
	v_pk_add_f32 v[4:5], v[4:5], v[10:11]
	v_pk_add_f32 v[6:7], v[6:7], v[12:13]
	s_nop 0
	v_cvt_pk_bf16_f32 v10, v6, v7
	v_cvt_pk_bf16_f32 v11, v4, v5
	v_mul_f32_e32 v7, v7, v7
	v_mul_f32_e32 v5, v5, v5
	v_fmac_f32_e32 v7, v6, v6
	v_fmac_f32_e32 v5, v4, v4
	global_store_dwordx2 v[8:9], v[10:11], off
	v_add_f32_e32 v10, v7, v5
	global_load_dwordx2 v[4:5], v[8:9], off offset:32
	s_waitcnt vmcnt(0) lgkmcnt(0)
	v_lshlrev_b32_e32 v6, 16, v4
	v_and_b32_e32 v7, 0xffff0000, v4
	v_lshlrev_b32_e32 v4, 16, v5
	v_and_b32_e32 v5, 0xffff0000, v5
	v_pk_add_f32 v[0:1], v[0:1], v[6:7]
	v_pk_add_f32 v[2:3], v[2:3], v[4:5]
	v_cvt_pk_bf16_f32 v4, v0, v1
	v_mul_f32_e32 v1, v1, v1
	v_fmac_f32_e32 v1, v0, v0
	v_mul_f32_e32 v0, v3, v3
	v_cvt_pk_bf16_f32 v5, v2, v3
	v_fmac_f32_e32 v0, v2, v2
	v_and_b32_e32 v2, 64, v225
	v_add_f32_e32 v0, v1, v0
	v_xor_b32_e32 v1, 16, v225
	v_add_u32_e32 v2, 64, v2
	v_cmp_lt_i32_e64 s[0:1], v1, v2
	v_add_f32_e32 v0, v10, v0
	global_store_dwordx2 v[8:9], v[4:5], off offset:32
	v_cndmask_b32_e64 v1, v225, v1, s[0:1]
	v_lshlrev_b32_e32 v1, 2, v1
	ds_bpermute_b32 v1, v1, v0
	s_waitcnt lgkmcnt(0)
	v_add_f32_e32 v0, v0, v1
	v_xor_b32_e32 v1, 32, v225
	v_cmp_lt_i32_e64 s[0:1], v1, v2
	s_nop 1
	v_cndmask_b32_e64 v1, v225, v1, s[0:1]
	v_lshlrev_b32_e32 v1, 2, v1
	ds_bpermute_b32 v1, v1, v0
	s_and_saveexec_b64 s[0:1], vcc
	s_cbranch_execz .LBB0_1253
	s_waitcnt lgkmcnt(0)
	v_add_f32_e32 v0, v0, v1
	global_atomic_add_f32 v[66:67], v0, off
	s_branch .LBB0_1253
